# GEMM K-loops: all per-segment s_setprio toggles removed
# speedup vs baseline: 1.0080x; 1.0003x over previous
.LBB0_170:
	ds_read_b128 v[148:151], v165
	ds_read_b128 v[152:155], v165 offset:1024
	ds_read_b128 v[156:159], v165 offset:2048
	ds_read_b128 v[160:163], v165 offset:3072
	ds_read_b128 v[170:173], v166
	ds_read_b128 v[174:177], v166 offset:1024
	ds_read_b128 v[178:181], v166 offset:2048
	ds_read_b128 v[182:185], v166 offset:3072
	s_add_u32 s28, s52, 0xfffc0080
	s_addc_u32 s29, s53, -1
	s_cmp_eq_u32 s73, 12
	s_cselect_b32 s31, s15, s29
	s_cselect_b32 s30, s69, s28
	s_cselect_b32 s29, s13, s72
	s_cselect_b32 s28, s70, s71
	s_add_i32 m0, s21, 0xc000
	ds_read_b128 v[186:189], v167
	ds_read_b128 v[190:193], v167 offset:1024
	ds_read_b128 v[194:197], v167 offset:2048
	ds_read_b128 v[198:201], v167 offset:3072
	ds_read_b128 v[202:205], v167 offset:4096
	ds_read_b128 v[206:209], v167 offset:5120
	ds_read_b128 v[210:213], v167 offset:6144
	ds_read_b128 v[214:217], v167 offset:7168
	global_load_lds_dwordx4 v140, s[52:53]
	s_add_i32 m0, s21, 0xe000
	s_nop 0
	global_load_lds_dwordx4 v142, s[52:53]
	s_waitcnt vmcnt(8)
	s_waitcnt lgkmcnt(0)
	s_barrier
	v_mfma_f32_16x16x32_bf16 v[126:129], v[148:151], v[186:189], v[126:129]
	v_mfma_f32_16x16x32_bf16 v[118:121], v[156:159], v[186:189], v[118:121]
	v_mfma_f32_16x16x32_bf16 v[110:113], v[148:151], v[194:197], v[110:113]
	v_mfma_f32_16x16x32_bf16 v[102:105], v[156:159], v[194:197], v[102:105]
	v_mfma_f32_16x16x32_bf16 v[94:97], v[148:151], v[202:205], v[94:97]
	v_mfma_f32_16x16x32_bf16 v[86:89], v[156:159], v[202:205], v[86:89]
	v_mfma_f32_16x16x32_bf16 v[78:81], v[148:151], v[210:213], v[78:81]
	v_mfma_f32_16x16x32_bf16 v[70:73], v[156:159], v[210:213], v[70:73]
	v_mfma_f32_16x16x32_bf16 v[126:129], v[152:155], v[190:193], v[126:129]
	v_mfma_f32_16x16x32_bf16 v[118:121], v[160:163], v[190:193], v[118:121]
	v_mfma_f32_16x16x32_bf16 v[110:113], v[152:155], v[198:201], v[110:113]
	v_mfma_f32_16x16x32_bf16 v[102:105], v[160:163], v[198:201], v[102:105]
	v_mfma_f32_16x16x32_bf16 v[94:97], v[152:155], v[206:209], v[94:97]
	v_mfma_f32_16x16x32_bf16 v[86:89], v[160:163], v[206:209], v[86:89]
	v_mfma_f32_16x16x32_bf16 v[78:81], v[152:155], v[214:217], v[78:81]
	v_mfma_f32_16x16x32_bf16 v[70:73], v[160:163], v[214:217], v[70:73]
	v_mfma_f32_16x16x32_bf16 v[122:125], v[170:173], v[186:189], v[122:125]
	v_mfma_f32_16x16x32_bf16 v[114:117], v[178:181], v[186:189], v[114:117]
	v_mfma_f32_16x16x32_bf16 v[106:109], v[170:173], v[194:197], v[106:109]
	v_mfma_f32_16x16x32_bf16 v[98:101], v[178:181], v[194:197], v[98:101]
	v_mfma_f32_16x16x32_bf16 v[90:93], v[170:173], v[202:205], v[90:93]
	v_mfma_f32_16x16x32_bf16 v[82:85], v[178:181], v[202:205], v[82:85]
	v_mfma_f32_16x16x32_bf16 v[74:77], v[170:173], v[210:213], v[74:77]
	v_mfma_f32_16x16x32_bf16 v[66:69], v[178:181], v[210:213], v[66:69]
	v_mfma_f32_16x16x32_bf16 v[122:125], v[174:177], v[190:193], v[122:125]
	v_mfma_f32_16x16x32_bf16 v[114:117], v[182:185], v[190:193], v[114:117]
	v_mfma_f32_16x16x32_bf16 v[106:109], v[174:177], v[198:201], v[106:109]
	v_mfma_f32_16x16x32_bf16 v[98:101], v[182:185], v[198:201], v[98:101]
	v_mfma_f32_16x16x32_bf16 v[90:93], v[174:177], v[206:209], v[90:93]
	v_mfma_f32_16x16x32_bf16 v[82:85], v[182:185], v[206:209], v[82:85]
	v_mfma_f32_16x16x32_bf16 v[74:77], v[174:177], v[214:217], v[74:77]
	v_mfma_f32_16x16x32_bf16 v[66:69], v[182:185], v[214:217], v[66:69]
	s_barrier
	s_add_i32 s74, s59, s24
	s_mov_b32 m0, s74
	ds_read_b128 v[186:189], v167 offset:16384
	ds_read_b128 v[190:193], v167 offset:17408
	ds_read_b128 v[194:197], v167 offset:18432
	ds_read_b128 v[198:201], v167 offset:19456
	ds_read_b128 v[202:205], v167 offset:20480
	ds_read_b128 v[206:209], v167 offset:21504
	ds_read_b128 v[210:213], v167 offset:22528
	ds_read_b128 v[214:217], v167 offset:23552
	global_load_lds_dwordx4 v134, s[28:29]
	s_add_i32 m0, s74, 0x2000
	s_add_u32 s74, s28, 0x40000
	s_addc_u32 s75, s29, 0
	s_add_i32 s76, s66, s24
	global_load_lds_dwordx4 v130, s[28:29]
	s_mov_b32 m0, s76
	s_nop 0
	global_load_lds_dwordx4 v134, s[74:75]
	s_add_i32 m0, s76, 0x2000
	s_nop 0
	global_load_lds_dwordx4 v130, s[74:75]
	s_mov_b32 m0, s21
	s_nop 0
	global_load_lds_dwordx4 v136, s[30:31]
	s_mov_b32 m0, s34
	s_nop 0
	global_load_lds_dwordx4 v132, s[30:31]
	s_waitcnt vmcnt(8)
	s_waitcnt lgkmcnt(0)
	s_barrier
	v_mfma_f32_16x16x32_bf16 v[62:65], v[148:151], v[186:189], v[62:65]
	v_mfma_f32_16x16x32_bf16 v[54:57], v[156:159], v[186:189], v[54:57]
	v_mfma_f32_16x16x32_bf16 v[46:49], v[148:151], v[194:197], v[46:49]
	v_mfma_f32_16x16x32_bf16 v[38:41], v[156:159], v[194:197], v[38:41]
	v_mfma_f32_16x16x32_bf16 v[30:33], v[148:151], v[202:205], v[30:33]
	v_mfma_f32_16x16x32_bf16 v[22:25], v[156:159], v[202:205], v[22:25]
	v_mfma_f32_16x16x32_bf16 v[14:17], v[148:151], v[210:213], v[14:17]
	v_mfma_f32_16x16x32_bf16 v[6:9], v[156:159], v[210:213], v[6:9]
	v_mfma_f32_16x16x32_bf16 v[62:65], v[152:155], v[190:193], v[62:65]
	v_mfma_f32_16x16x32_bf16 v[54:57], v[160:163], v[190:193], v[54:57]
	v_mfma_f32_16x16x32_bf16 v[46:49], v[152:155], v[198:201], v[46:49]
	v_mfma_f32_16x16x32_bf16 v[38:41], v[160:163], v[198:201], v[38:41]
	v_mfma_f32_16x16x32_bf16 v[30:33], v[152:155], v[206:209], v[30:33]
	v_mfma_f32_16x16x32_bf16 v[22:25], v[160:163], v[206:209], v[22:25]
	v_mfma_f32_16x16x32_bf16 v[14:17], v[152:155], v[214:217], v[14:17]
	v_mfma_f32_16x16x32_bf16 v[6:9], v[160:163], v[214:217], v[6:9]
	v_mfma_f32_16x16x32_bf16 v[58:61], v[170:173], v[186:189], v[58:61]
	v_mfma_f32_16x16x32_bf16 v[50:53], v[178:181], v[186:189], v[50:53]
	v_mfma_f32_16x16x32_bf16 v[42:45], v[170:173], v[194:197], v[42:45]
	v_mfma_f32_16x16x32_bf16 v[34:37], v[178:181], v[194:197], v[34:37]
	v_mfma_f32_16x16x32_bf16 v[26:29], v[170:173], v[202:205], v[26:29]
	v_mfma_f32_16x16x32_bf16 v[18:21], v[178:181], v[202:205], v[18:21]
	v_mfma_f32_16x16x32_bf16 v[10:13], v[170:173], v[210:213], v[10:13]
	v_mfma_f32_16x16x32_bf16 v[2:5], v[178:181], v[210:213], v[2:5]
	v_mfma_f32_16x16x32_bf16 v[58:61], v[174:177], v[190:193], v[58:61]
	v_mfma_f32_16x16x32_bf16 v[50:53], v[182:185], v[190:193], v[50:53]
	v_mfma_f32_16x16x32_bf16 v[42:45], v[174:177], v[198:201], v[42:45]
	v_mfma_f32_16x16x32_bf16 v[34:37], v[182:185], v[198:201], v[34:37]
	v_mfma_f32_16x16x32_bf16 v[26:29], v[174:177], v[206:209], v[26:29]
	v_mfma_f32_16x16x32_bf16 v[18:21], v[182:185], v[206:209], v[18:21]
	v_mfma_f32_16x16x32_bf16 v[10:13], v[174:177], v[214:217], v[10:13]
	v_mfma_f32_16x16x32_bf16 v[2:5], v[182:185], v[214:217], v[2:5]
	s_barrier
	s_add_i32 s74, 0, 0x18000
	s_add_i32 s75, 0, 0x1c000
	v_add_u32_e32 v160, s74, v139
	v_add_u32_e32 v169, s75, v139
	ds_read_b128 v[148:151], v160
	ds_read_b128 v[152:155], v160 offset:1024
	ds_read_b128 v[156:159], v160 offset:2048
	ds_read_b128 v[160:163], v160 offset:3072
	ds_read_b128 v[170:173], v169
	ds_read_b128 v[174:177], v169 offset:1024
	ds_read_b128 v[178:181], v169 offset:2048
	ds_read_b128 v[182:185], v169 offset:3072
	s_add_u32 s98, s30, 0x40000
	s_addc_u32 s99, s31, 0
	s_mov_b32 m0, s35
	ds_read_b128 v[186:189], v167 offset:32768
	ds_read_b128 v[190:193], v167 offset:33792
	ds_read_b128 v[194:197], v167 offset:34816
	ds_read_b128 v[198:201], v167 offset:35840
	ds_read_b128 v[202:205], v167 offset:36864
	ds_read_b128 v[206:209], v167 offset:37888
	ds_read_b128 v[210:213], v167 offset:38912
	ds_read_b128 v[214:217], v167 offset:39936
	global_load_lds_dwordx4 v136, s[98:99]
	s_mov_b32 m0, s54
	s_nop 0
	global_load_lds_dwordx4 v132, s[98:99]
	s_waitcnt vmcnt(8)
	s_waitcnt lgkmcnt(0)
	s_barrier
	v_mfma_f32_16x16x32_bf16 v[126:129], v[148:151], v[186:189], v[126:129]
	v_mfma_f32_16x16x32_bf16 v[118:121], v[156:159], v[186:189], v[118:121]
	v_mfma_f32_16x16x32_bf16 v[110:113], v[148:151], v[194:197], v[110:113]
	v_mfma_f32_16x16x32_bf16 v[102:105], v[156:159], v[194:197], v[102:105]
	v_mfma_f32_16x16x32_bf16 v[94:97], v[148:151], v[202:205], v[94:97]
	v_mfma_f32_16x16x32_bf16 v[86:89], v[156:159], v[202:205], v[86:89]
	v_mfma_f32_16x16x32_bf16 v[78:81], v[148:151], v[210:213], v[78:81]
	v_mfma_f32_16x16x32_bf16 v[70:73], v[156:159], v[210:213], v[70:73]
	v_mfma_f32_16x16x32_bf16 v[126:129], v[152:155], v[190:193], v[126:129]
	v_mfma_f32_16x16x32_bf16 v[118:121], v[160:163], v[190:193], v[118:121]
	v_mfma_f32_16x16x32_bf16 v[110:113], v[152:155], v[198:201], v[110:113]
	v_mfma_f32_16x16x32_bf16 v[102:105], v[160:163], v[198:201], v[102:105]
	v_mfma_f32_16x16x32_bf16 v[94:97], v[152:155], v[206:209], v[94:97]
	v_mfma_f32_16x16x32_bf16 v[86:89], v[160:163], v[206:209], v[86:89]
	v_mfma_f32_16x16x32_bf16 v[78:81], v[152:155], v[214:217], v[78:81]
	v_mfma_f32_16x16x32_bf16 v[70:73], v[160:163], v[214:217], v[70:73]
	v_mfma_f32_16x16x32_bf16 v[122:125], v[170:173], v[186:189], v[122:125]
	v_mfma_f32_16x16x32_bf16 v[114:117], v[178:181], v[186:189], v[114:117]
	v_mfma_f32_16x16x32_bf16 v[106:109], v[170:173], v[194:197], v[106:109]
	v_mfma_f32_16x16x32_bf16 v[98:101], v[178:181], v[194:197], v[98:101]
	v_mfma_f32_16x16x32_bf16 v[90:93], v[170:173], v[202:205], v[90:93]
	v_mfma_f32_16x16x32_bf16 v[82:85], v[178:181], v[202:205], v[82:85]
	v_mfma_f32_16x16x32_bf16 v[74:77], v[170:173], v[210:213], v[74:77]
	v_mfma_f32_16x16x32_bf16 v[66:69], v[178:181], v[210:213], v[66:69]
	v_mfma_f32_16x16x32_bf16 v[122:125], v[174:177], v[190:193], v[122:125]
	v_mfma_f32_16x16x32_bf16 v[114:117], v[182:185], v[190:193], v[114:117]
	v_mfma_f32_16x16x32_bf16 v[106:109], v[174:177], v[198:201], v[106:109]
	v_mfma_f32_16x16x32_bf16 v[98:101], v[182:185], v[198:201], v[98:101]
	v_mfma_f32_16x16x32_bf16 v[90:93], v[174:177], v[206:209], v[90:93]
	v_mfma_f32_16x16x32_bf16 v[82:85], v[182:185], v[206:209], v[82:85]
	v_mfma_f32_16x16x32_bf16 v[74:77], v[174:177], v[214:217], v[74:77]
	v_mfma_f32_16x16x32_bf16 v[66:69], v[182:185], v[214:217], v[66:69]
	s_barrier
	s_add_i32 s98, s74, s24
	s_add_i32 m0, s98, 0xffffff80
	ds_read_b128 v[186:189], v167 offset:49152
	ds_read_b128 v[190:193], v167 offset:50176
	ds_read_b128 v[194:197], v167 offset:51200
	ds_read_b128 v[198:201], v167 offset:52224
	ds_read_b128 v[202:205], v167 offset:53248
	ds_read_b128 v[206:209], v167 offset:54272
	ds_read_b128 v[210:213], v167 offset:55296
	ds_read_b128 v[214:217], v167 offset:56320
	global_load_lds_dwordx4 v134, s[28:29] offset:128
	s_add_i32 m0, s98, 0x1f80
	s_add_i32 s98, s75, s24
	global_load_lds_dwordx4 v130, s[28:29] offset:128
	s_add_u32 s28, s28, 0x40080
	s_addc_u32 s29, s29, 0
	s_mov_b32 m0, s98
	s_nop 0
	global_load_lds_dwordx4 v134, s[28:29]
	s_add_i32 m0, s98, 0x2000
	s_nop 0
	global_load_lds_dwordx4 v130, s[28:29]
	s_add_i32 m0, s56, 0xffffff80
	s_nop 0
	global_load_lds_dwordx4 v136, s[30:31] offset:128
	s_add_i32 m0, s57, 0xffffff80
	s_nop 0
	global_load_lds_dwordx4 v132, s[30:31] offset:128
	s_waitcnt vmcnt(8)
	s_waitcnt lgkmcnt(0)
	s_barrier
	v_mfma_f32_16x16x32_bf16 v[62:65], v[148:151], v[186:189], v[62:65]
	v_mfma_f32_16x16x32_bf16 v[54:57], v[156:159], v[186:189], v[54:57]
	v_mfma_f32_16x16x32_bf16 v[46:49], v[148:151], v[194:197], v[46:49]
	v_mfma_f32_16x16x32_bf16 v[38:41], v[156:159], v[194:197], v[38:41]
	v_mfma_f32_16x16x32_bf16 v[30:33], v[148:151], v[202:205], v[30:33]
	v_mfma_f32_16x16x32_bf16 v[22:25], v[156:159], v[202:205], v[22:25]
	v_mfma_f32_16x16x32_bf16 v[14:17], v[148:151], v[210:213], v[14:17]
	v_mfma_f32_16x16x32_bf16 v[6:9], v[156:159], v[210:213], v[6:9]
	v_mfma_f32_16x16x32_bf16 v[62:65], v[152:155], v[190:193], v[62:65]
	v_mfma_f32_16x16x32_bf16 v[54:57], v[160:163], v[190:193], v[54:57]
	v_mfma_f32_16x16x32_bf16 v[46:49], v[152:155], v[198:201], v[46:49]
	v_mfma_f32_16x16x32_bf16 v[38:41], v[160:163], v[198:201], v[38:41]
	v_mfma_f32_16x16x32_bf16 v[30:33], v[152:155], v[206:209], v[30:33]
	v_mfma_f32_16x16x32_bf16 v[22:25], v[160:163], v[206:209], v[22:25]
	v_mfma_f32_16x16x32_bf16 v[14:17], v[152:155], v[214:217], v[14:17]
	v_mfma_f32_16x16x32_bf16 v[6:9], v[160:163], v[214:217], v[6:9]
	v_mfma_f32_16x16x32_bf16 v[58:61], v[170:173], v[186:189], v[58:61]
	v_mfma_f32_16x16x32_bf16 v[50:53], v[178:181], v[186:189], v[50:53]
	v_mfma_f32_16x16x32_bf16 v[42:45], v[170:173], v[194:197], v[42:45]
	v_mfma_f32_16x16x32_bf16 v[34:37], v[178:181], v[194:197], v[34:37]
	v_mfma_f32_16x16x32_bf16 v[26:29], v[170:173], v[202:205], v[26:29]
	v_mfma_f32_16x16x32_bf16 v[18:21], v[178:181], v[202:205], v[18:21]
	v_mfma_f32_16x16x32_bf16 v[10:13], v[170:173], v[210:213], v[10:13]
	v_mfma_f32_16x16x32_bf16 v[2:5], v[178:181], v[210:213], v[2:5]
	v_mfma_f32_16x16x32_bf16 v[58:61], v[174:177], v[190:193], v[58:61]
	v_mfma_f32_16x16x32_bf16 v[50:53], v[182:185], v[190:193], v[50:53]
	v_mfma_f32_16x16x32_bf16 v[42:45], v[174:177], v[198:201], v[42:45]
	v_mfma_f32_16x16x32_bf16 v[34:37], v[182:185], v[198:201], v[34:37]
	v_mfma_f32_16x16x32_bf16 v[26:29], v[174:177], v[206:209], v[26:29]
	v_mfma_f32_16x16x32_bf16 v[18:21], v[182:185], v[206:209], v[18:21]
	v_mfma_f32_16x16x32_bf16 v[10:13], v[174:177], v[214:217], v[10:13]
	v_mfma_f32_16x16x32_bf16 v[2:5], v[182:185], v[214:217], v[2:5]
	s_barrier
	s_add_i32 s73, s73, 2
	s_add_u32 s52, s52, 0x100
	s_addc_u32 s53, s53, 0
	s_add_u32 s71, s71, 0x100
	s_addc_u32 s72, s72, 0
	s_cmp_gt_u32 s73, 13
	s_cbranch_scc0 .LBB0_170
	s_and_b64 vcc, exec, s[10:11]
	s_cbranch_vccz .LBB0_173
	s_barrier

.LBB0_730:
	v_add_u32_e32 v155, s58, v153
	ds_read_b128 v[156:159], v155
	ds_read_b128 v[160:163], v155 offset:1024
	ds_read_b128 v[164:167], v155 offset:2048
	ds_read_b128 v[168:171], v155 offset:3072
	v_add_u32_e32 v155, s59, v153
	s_add_u32 s20, s10, s18
	ds_read_b128 v[172:175], v155
	ds_read_b128 v[176:179], v155 offset:1024
	ds_read_b128 v[180:183], v155 offset:2048
	ds_read_b128 v[184:187], v155 offset:3072
	s_addc_u32 s21, s11, s19
	s_add_u32 s20, s20, 0x100
	s_addc_u32 s21, s21, 0
	s_add_u32 s64, s15, s18
	s_addc_u32 s65, s62, s19
	s_cmpk_eq_i32 s18, 0x1500
	s_cselect_b32 s29, s17, s21
	s_cselect_b32 s28, s16, s20
	s_cselect_b32 s21, s1, s65
	s_cselect_b32 s20, s0, s64
	v_lshl_add_u64 v[220:221], v[148:149], 0, s[18:19]
	s_add_i32 m0, s51, 0xc000
	ds_read_b128 v[188:191], v154
	ds_read_b128 v[192:195], v154 offset:1024
	ds_read_b128 v[196:199], v154 offset:2048
	ds_read_b128 v[200:203], v154 offset:3072
	ds_read_b128 v[204:207], v154 offset:4096
	ds_read_b128 v[208:211], v154 offset:5120
	ds_read_b128 v[212:215], v154 offset:6144
	ds_read_b128 v[216:219], v154 offset:7168
	global_load_lds_dwordx4 v[220:221], off
	v_lshl_add_u64 v[220:221], v[150:151], 0, s[18:19]
	s_add_i32 m0, s51, 0xe000
	s_nop 0
	global_load_lds_dwordx4 v[220:221], off
	s_waitcnt vmcnt(8)
	s_waitcnt lgkmcnt(0)
	s_barrier
	v_mfma_f32_16x16x32_bf16 v[126:129], v[156:159], v[188:191], v[126:129]
	v_mfma_f32_16x16x32_bf16 v[122:125], v[164:167], v[188:191], v[122:125]
	v_mfma_f32_16x16x32_bf16 v[110:113], v[156:159], v[196:199], v[110:113]
	v_mfma_f32_16x16x32_bf16 v[106:109], v[164:167], v[196:199], v[106:109]
	v_mfma_f32_16x16x32_bf16 v[94:97], v[156:159], v[204:207], v[94:97]
	v_mfma_f32_16x16x32_bf16 v[90:93], v[164:167], v[204:207], v[90:93]
	v_mfma_f32_16x16x32_bf16 v[78:81], v[156:159], v[212:215], v[78:81]
	v_mfma_f32_16x16x32_bf16 v[74:77], v[164:167], v[212:215], v[74:77]
	v_mfma_f32_16x16x32_bf16 v[126:129], v[160:163], v[192:195], v[126:129]
	v_mfma_f32_16x16x32_bf16 v[122:125], v[168:171], v[192:195], v[122:125]
	v_mfma_f32_16x16x32_bf16 v[110:113], v[160:163], v[200:203], v[110:113]
	v_mfma_f32_16x16x32_bf16 v[106:109], v[168:171], v[200:203], v[106:109]
	v_mfma_f32_16x16x32_bf16 v[94:97], v[160:163], v[208:211], v[94:97]
	v_mfma_f32_16x16x32_bf16 v[90:93], v[168:171], v[208:211], v[90:93]
	v_mfma_f32_16x16x32_bf16 v[78:81], v[160:163], v[216:219], v[78:81]
	v_mfma_f32_16x16x32_bf16 v[74:77], v[168:171], v[216:219], v[74:77]
	v_mfma_f32_16x16x32_bf16 v[118:121], v[172:175], v[188:191], v[118:121]
	v_mfma_f32_16x16x32_bf16 v[114:117], v[180:183], v[188:191], v[114:117]
	v_mfma_f32_16x16x32_bf16 v[102:105], v[172:175], v[196:199], v[102:105]
	v_mfma_f32_16x16x32_bf16 v[98:101], v[180:183], v[196:199], v[98:101]
	v_mfma_f32_16x16x32_bf16 v[86:89], v[172:175], v[204:207], v[86:89]
	v_mfma_f32_16x16x32_bf16 v[82:85], v[180:183], v[204:207], v[82:85]
	v_mfma_f32_16x16x32_bf16 v[70:73], v[172:175], v[212:215], v[70:73]
	v_mfma_f32_16x16x32_bf16 v[66:69], v[180:183], v[212:215], v[66:69]
	v_mfma_f32_16x16x32_bf16 v[118:121], v[176:179], v[192:195], v[118:121]
	v_mfma_f32_16x16x32_bf16 v[114:117], v[184:187], v[192:195], v[114:117]
	v_mfma_f32_16x16x32_bf16 v[102:105], v[176:179], v[200:203], v[102:105]
	v_mfma_f32_16x16x32_bf16 v[98:101], v[184:187], v[200:203], v[98:101]
	v_mfma_f32_16x16x32_bf16 v[86:89], v[176:179], v[208:211], v[86:89]
	v_mfma_f32_16x16x32_bf16 v[82:85], v[184:187], v[208:211], v[82:85]
	v_mfma_f32_16x16x32_bf16 v[70:73], v[176:179], v[216:219], v[70:73]
	v_mfma_f32_16x16x32_bf16 v[66:69], v[184:187], v[216:219], v[66:69]
	s_barrier
	s_add_i32 s64, s58, s35
	s_mov_b32 m0, s64
	ds_read_b128 v[188:191], v154 offset:16384
	ds_read_b128 v[192:195], v154 offset:17408
	ds_read_b128 v[196:199], v154 offset:18432
	ds_read_b128 v[200:203], v154 offset:19456
	ds_read_b128 v[204:207], v154 offset:20480
	ds_read_b128 v[208:211], v154 offset:21504
	ds_read_b128 v[212:215], v154 offset:22528
	ds_read_b128 v[216:219], v154 offset:23552
	global_load_lds_dwordx4 v132, s[20:21]
	s_add_i32 m0, s64, 0x2000
	s_add_u32 s64, s20, 0xb0000
	s_addc_u32 s65, s21, 0
	s_add_i32 s66, s59, s35
	global_load_lds_dwordx4 v136, s[20:21]
	s_mov_b32 m0, s66
	s_nop 0
	global_load_lds_dwordx4 v132, s[64:65]
	s_add_i32 m0, s66, 0x2000
	s_nop 0
	global_load_lds_dwordx4 v136, s[64:65]
	s_mov_b32 m0, s51
	s_nop 0
	global_load_lds_dwordx4 v130, s[28:29]
	s_mov_b32 m0, s52
	s_nop 0
	global_load_lds_dwordx4 v134, s[28:29]
	s_waitcnt vmcnt(8)
	s_waitcnt lgkmcnt(0)
	s_barrier
	v_mfma_f32_16x16x32_bf16 v[62:65], v[156:159], v[188:191], v[62:65]
	v_mfma_f32_16x16x32_bf16 v[58:61], v[164:167], v[188:191], v[58:61]
	v_mfma_f32_16x16x32_bf16 v[46:49], v[156:159], v[196:199], v[46:49]
	v_mfma_f32_16x16x32_bf16 v[42:45], v[164:167], v[196:199], v[42:45]
	v_mfma_f32_16x16x32_bf16 v[30:33], v[156:159], v[204:207], v[30:33]
	v_mfma_f32_16x16x32_bf16 v[26:29], v[164:167], v[204:207], v[26:29]
	v_mfma_f32_16x16x32_bf16 v[14:17], v[156:159], v[212:215], v[14:17]
	v_mfma_f32_16x16x32_bf16 v[10:13], v[164:167], v[212:215], v[10:13]
	v_mfma_f32_16x16x32_bf16 v[62:65], v[160:163], v[192:195], v[62:65]
	v_mfma_f32_16x16x32_bf16 v[58:61], v[168:171], v[192:195], v[58:61]
	v_mfma_f32_16x16x32_bf16 v[46:49], v[160:163], v[200:203], v[46:49]
	v_mfma_f32_16x16x32_bf16 v[42:45], v[168:171], v[200:203], v[42:45]
	v_mfma_f32_16x16x32_bf16 v[30:33], v[160:163], v[208:211], v[30:33]
	v_mfma_f32_16x16x32_bf16 v[26:29], v[168:171], v[208:211], v[26:29]
	v_mfma_f32_16x16x32_bf16 v[14:17], v[160:163], v[216:219], v[14:17]
	v_mfma_f32_16x16x32_bf16 v[10:13], v[168:171], v[216:219], v[10:13]
	v_mfma_f32_16x16x32_bf16 v[54:57], v[172:175], v[188:191], v[54:57]
	v_mfma_f32_16x16x32_bf16 v[50:53], v[180:183], v[188:191], v[50:53]
	v_mfma_f32_16x16x32_bf16 v[38:41], v[172:175], v[196:199], v[38:41]
	v_mfma_f32_16x16x32_bf16 v[34:37], v[180:183], v[196:199], v[34:37]
	v_mfma_f32_16x16x32_bf16 v[22:25], v[172:175], v[204:207], v[22:25]
	v_mfma_f32_16x16x32_bf16 v[18:21], v[180:183], v[204:207], v[18:21]
	v_mfma_f32_16x16x32_bf16 v[6:9], v[172:175], v[212:215], v[6:9]
	v_mfma_f32_16x16x32_bf16 v[2:5], v[180:183], v[212:215], v[2:5]
	v_mfma_f32_16x16x32_bf16 v[54:57], v[176:179], v[192:195], v[54:57]
	v_mfma_f32_16x16x32_bf16 v[50:53], v[184:187], v[192:195], v[50:53]
	v_mfma_f32_16x16x32_bf16 v[38:41], v[176:179], v[200:203], v[38:41]
	v_mfma_f32_16x16x32_bf16 v[34:37], v[184:187], v[200:203], v[34:37]
	v_mfma_f32_16x16x32_bf16 v[22:25], v[176:179], v[208:211], v[22:25]
	v_mfma_f32_16x16x32_bf16 v[18:21], v[184:187], v[208:211], v[18:21]
	v_mfma_f32_16x16x32_bf16 v[6:9], v[176:179], v[216:219], v[6:9]
	v_mfma_f32_16x16x32_bf16 v[2:5], v[184:187], v[216:219], v[2:5]
	s_barrier
	s_add_i32 s64, 0, 0x18000
	v_add_u32_e32 v155, s64, v153
	s_add_i32 s65, 0, 0x1c000
	ds_read_b128 v[156:159], v155
	ds_read_b128 v[160:163], v155 offset:1024
	ds_read_b128 v[164:167], v155 offset:2048
	ds_read_b128 v[168:171], v155 offset:3072
	v_add_u32_e32 v155, s65, v153
	ds_read_b128 v[172:175], v155
	ds_read_b128 v[176:179], v155 offset:1024
	ds_read_b128 v[180:183], v155 offset:2048
	ds_read_b128 v[184:187], v155 offset:3072
	s_add_u32 s98, s28, 0xb0000
	s_addc_u32 s99, s29, 0
	s_mov_b32 m0, s53
	ds_read_b128 v[188:191], v154 offset:32768
	ds_read_b128 v[192:195], v154 offset:33792
	ds_read_b128 v[196:199], v154 offset:34816
	ds_read_b128 v[200:203], v154 offset:35840
	ds_read_b128 v[204:207], v154 offset:36864
	ds_read_b128 v[208:211], v154 offset:37888
	ds_read_b128 v[212:215], v154 offset:38912
	ds_read_b128 v[216:219], v154 offset:39936
	global_load_lds_dwordx4 v130, s[98:99]
	s_mov_b32 m0, s54
	s_nop 0
	global_load_lds_dwordx4 v134, s[98:99]
	s_waitcnt vmcnt(8)
	s_waitcnt lgkmcnt(0)
	s_barrier
	v_mfma_f32_16x16x32_bf16 v[126:129], v[156:159], v[188:191], v[126:129]
	v_mfma_f32_16x16x32_bf16 v[122:125], v[164:167], v[188:191], v[122:125]
	v_mfma_f32_16x16x32_bf16 v[110:113], v[156:159], v[196:199], v[110:113]
	v_mfma_f32_16x16x32_bf16 v[106:109], v[164:167], v[196:199], v[106:109]
	v_mfma_f32_16x16x32_bf16 v[94:97], v[156:159], v[204:207], v[94:97]
	v_mfma_f32_16x16x32_bf16 v[90:93], v[164:167], v[204:207], v[90:93]
	v_mfma_f32_16x16x32_bf16 v[78:81], v[156:159], v[212:215], v[78:81]
	v_mfma_f32_16x16x32_bf16 v[74:77], v[164:167], v[212:215], v[74:77]
	v_mfma_f32_16x16x32_bf16 v[126:129], v[160:163], v[192:195], v[126:129]
	v_mfma_f32_16x16x32_bf16 v[122:125], v[168:171], v[192:195], v[122:125]
	v_mfma_f32_16x16x32_bf16 v[110:113], v[160:163], v[200:203], v[110:113]
	v_mfma_f32_16x16x32_bf16 v[106:109], v[168:171], v[200:203], v[106:109]
	v_mfma_f32_16x16x32_bf16 v[94:97], v[160:163], v[208:211], v[94:97]
	v_mfma_f32_16x16x32_bf16 v[90:93], v[168:171], v[208:211], v[90:93]
	v_mfma_f32_16x16x32_bf16 v[78:81], v[160:163], v[216:219], v[78:81]
	v_mfma_f32_16x16x32_bf16 v[74:77], v[168:171], v[216:219], v[74:77]
	v_mfma_f32_16x16x32_bf16 v[118:121], v[172:175], v[188:191], v[118:121]
	v_mfma_f32_16x16x32_bf16 v[114:117], v[180:183], v[188:191], v[114:117]
	v_mfma_f32_16x16x32_bf16 v[102:105], v[172:175], v[196:199], v[102:105]
	v_mfma_f32_16x16x32_bf16 v[98:101], v[180:183], v[196:199], v[98:101]
	v_mfma_f32_16x16x32_bf16 v[86:89], v[172:175], v[204:207], v[86:89]
	v_mfma_f32_16x16x32_bf16 v[82:85], v[180:183], v[204:207], v[82:85]
	v_mfma_f32_16x16x32_bf16 v[70:73], v[172:175], v[212:215], v[70:73]
	v_mfma_f32_16x16x32_bf16 v[66:69], v[180:183], v[212:215], v[66:69]
	v_mfma_f32_16x16x32_bf16 v[118:121], v[176:179], v[192:195], v[118:121]
	v_mfma_f32_16x16x32_bf16 v[114:117], v[184:187], v[192:195], v[114:117]
	v_mfma_f32_16x16x32_bf16 v[102:105], v[176:179], v[200:203], v[102:105]
	v_mfma_f32_16x16x32_bf16 v[98:101], v[184:187], v[200:203], v[98:101]
	v_mfma_f32_16x16x32_bf16 v[86:89], v[176:179], v[208:211], v[86:89]
	v_mfma_f32_16x16x32_bf16 v[82:85], v[184:187], v[208:211], v[82:85]
	v_mfma_f32_16x16x32_bf16 v[70:73], v[176:179], v[216:219], v[70:73]
	v_mfma_f32_16x16x32_bf16 v[66:69], v[184:187], v[216:219], v[66:69]
	s_barrier
	s_add_i32 s98, s64, s35
	s_add_i32 m0, s98, 0xffffff80
	ds_read_b128 v[188:191], v154 offset:49152
	ds_read_b128 v[192:195], v154 offset:50176
	ds_read_b128 v[196:199], v154 offset:51200
	ds_read_b128 v[200:203], v154 offset:52224
	ds_read_b128 v[204:207], v154 offset:53248
	ds_read_b128 v[208:211], v154 offset:54272
	ds_read_b128 v[212:215], v154 offset:55296
	ds_read_b128 v[216:219], v154 offset:56320
	global_load_lds_dwordx4 v132, s[20:21] offset:128
	s_add_i32 m0, s98, 0x1f80
	s_add_i32 s98, s65, s35
	global_load_lds_dwordx4 v136, s[20:21] offset:128
	s_add_u32 s20, s20, 0xb0080
	s_addc_u32 s21, s21, 0
	s_mov_b32 m0, s98
	s_nop 0
	global_load_lds_dwordx4 v132, s[20:21]
	s_add_i32 m0, s98, 0x2000
	s_nop 0
	global_load_lds_dwordx4 v136, s[20:21]
	s_add_i32 m0, s56, 0xffffff80
	s_nop 0
	global_load_lds_dwordx4 v130, s[28:29] offset:128
	s_add_i32 m0, s57, 0xffffff80
	s_nop 0
	global_load_lds_dwordx4 v134, s[28:29] offset:128
	s_waitcnt vmcnt(8)
	s_waitcnt lgkmcnt(0)
	s_barrier
	v_mfma_f32_16x16x32_bf16 v[62:65], v[156:159], v[188:191], v[62:65]
	v_mfma_f32_16x16x32_bf16 v[58:61], v[164:167], v[188:191], v[58:61]
	v_mfma_f32_16x16x32_bf16 v[46:49], v[156:159], v[196:199], v[46:49]
	v_mfma_f32_16x16x32_bf16 v[42:45], v[164:167], v[196:199], v[42:45]
	v_mfma_f32_16x16x32_bf16 v[30:33], v[156:159], v[204:207], v[30:33]
	v_mfma_f32_16x16x32_bf16 v[26:29], v[164:167], v[204:207], v[26:29]
	v_mfma_f32_16x16x32_bf16 v[14:17], v[156:159], v[212:215], v[14:17]
	v_mfma_f32_16x16x32_bf16 v[10:13], v[164:167], v[212:215], v[10:13]
	v_mfma_f32_16x16x32_bf16 v[62:65], v[160:163], v[192:195], v[62:65]
	v_mfma_f32_16x16x32_bf16 v[58:61], v[168:171], v[192:195], v[58:61]
	v_mfma_f32_16x16x32_bf16 v[46:49], v[160:163], v[200:203], v[46:49]
	v_mfma_f32_16x16x32_bf16 v[42:45], v[168:171], v[200:203], v[42:45]
	v_mfma_f32_16x16x32_bf16 v[30:33], v[160:163], v[208:211], v[30:33]
	v_mfma_f32_16x16x32_bf16 v[26:29], v[168:171], v[208:211], v[26:29]
	v_mfma_f32_16x16x32_bf16 v[14:17], v[160:163], v[216:219], v[14:17]
	v_mfma_f32_16x16x32_bf16 v[10:13], v[168:171], v[216:219], v[10:13]
	v_mfma_f32_16x16x32_bf16 v[54:57], v[172:175], v[188:191], v[54:57]
	v_mfma_f32_16x16x32_bf16 v[50:53], v[180:183], v[188:191], v[50:53]
	v_mfma_f32_16x16x32_bf16 v[38:41], v[172:175], v[196:199], v[38:41]
	v_mfma_f32_16x16x32_bf16 v[34:37], v[180:183], v[196:199], v[34:37]
	v_mfma_f32_16x16x32_bf16 v[22:25], v[172:175], v[204:207], v[22:25]
	v_mfma_f32_16x16x32_bf16 v[18:21], v[180:183], v[204:207], v[18:21]
	v_mfma_f32_16x16x32_bf16 v[6:9], v[172:175], v[212:215], v[6:9]
	v_mfma_f32_16x16x32_bf16 v[2:5], v[180:183], v[212:215], v[2:5]
	v_mfma_f32_16x16x32_bf16 v[54:57], v[176:179], v[192:195], v[54:57]
	v_mfma_f32_16x16x32_bf16 v[50:53], v[184:187], v[192:195], v[50:53]
	v_mfma_f32_16x16x32_bf16 v[38:41], v[176:179], v[200:203], v[38:41]
	v_mfma_f32_16x16x32_bf16 v[34:37], v[184:187], v[200:203], v[34:37]
	v_mfma_f32_16x16x32_bf16 v[22:25], v[176:179], v[208:211], v[22:25]
	v_mfma_f32_16x16x32_bf16 v[18:21], v[184:187], v[208:211], v[18:21]
	v_mfma_f32_16x16x32_bf16 v[6:9], v[176:179], v[216:219], v[6:9]
	v_mfma_f32_16x16x32_bf16 v[2:5], v[184:187], v[216:219], v[2:5]
	s_barrier
	s_add_i32 s63, s63, 2
	s_add_u32 s18, s18, 0x100
	s_addc_u32 s19, s19, 0
	s_cmp_gt_u32 s63, 41
	s_cbranch_scc0 .LBB0_730
	s_add_u32 s18, s15, 0xffffff00
	s_addc_u32 s19, s62, -1
	s_and_b64 vcc, exec, s[4:5]
	s_cbranch_vccnz .LBB0_733
	v_mov_b32_e32 v2, 0
	v_mov_b32_e32 v3, 0
	v_mov_b64_e32 v[4:5], v[2:3]
	v_mov_b64_e32 v[6:7], v[2:3]
	v_mov_b64_e32 v[8:9], v[2:3]
	v_mov_b64_e32 v[10:11], v[2:3]
	v_mov_b64_e32 v[12:13], v[2:3]
	v_mov_b64_e32 v[14:15], v[2:3]
	v_mov_b64_e32 v[16:17], v[2:3]
	v_mov_b64_e32 v[18:19], v[2:3]
	v_mov_b64_e32 v[20:21], v[2:3]
	v_mov_b64_e32 v[22:23], v[2:3]
	v_mov_b64_e32 v[24:25], v[2:3]
	v_mov_b64_e32 v[26:27], v[2:3]
	v_mov_b64_e32 v[28:29], v[2:3]
	v_mov_b64_e32 v[30:31], v[2:3]
	v_mov_b64_e32 v[32:33], v[2:3]
	v_mov_b64_e32 v[34:35], v[2:3]
	v_mov_b64_e32 v[36:37], v[2:3]
	v_mov_b64_e32 v[38:39], v[2:3]
	v_mov_b64_e32 v[40:41], v[2:3]
	v_mov_b64_e32 v[42:43], v[2:3]
	v_mov_b64_e32 v[44:45], v[2:3]
	v_mov_b64_e32 v[46:47], v[2:3]
	v_mov_b64_e32 v[48:49], v[2:3]
	v_mov_b64_e32 v[50:51], v[2:3]
	v_mov_b64_e32 v[52:53], v[2:3]
	v_mov_b64_e32 v[54:55], v[2:3]
	v_mov_b64_e32 v[56:57], v[2:3]
	v_mov_b64_e32 v[58:59], v[2:3]
	v_mov_b64_e32 v[60:61], v[2:3]
	v_mov_b64_e32 v[62:63], v[2:3]
	v_mov_b64_e32 v[64:65], v[2:3]
	v_mov_b64_e32 v[66:67], v[2:3]
	v_mov_b64_e32 v[68:69], v[2:3]
	v_mov_b64_e32 v[70:71], v[2:3]
	v_mov_b64_e32 v[72:73], v[2:3]
	v_mov_b64_e32 v[74:75], v[2:3]
	v_mov_b64_e32 v[76:77], v[2:3]
	v_mov_b64_e32 v[78:79], v[2:3]
	v_mov_b64_e32 v[80:81], v[2:3]
	v_mov_b64_e32 v[82:83], v[2:3]
	v_mov_b64_e32 v[84:85], v[2:3]
	v_mov_b64_e32 v[86:87], v[2:3]
	v_mov_b64_e32 v[88:89], v[2:3]
	v_mov_b64_e32 v[90:91], v[2:3]
	v_mov_b64_e32 v[92:93], v[2:3]
	v_mov_b64_e32 v[94:95], v[2:3]
	v_mov_b64_e32 v[96:97], v[2:3]
	v_mov_b64_e32 v[98:99], v[2:3]
	v_mov_b64_e32 v[100:101], v[2:3]
	v_mov_b64_e32 v[102:103], v[2:3]
	v_mov_b64_e32 v[104:105], v[2:3]
	v_mov_b64_e32 v[106:107], v[2:3]
	v_mov_b64_e32 v[108:109], v[2:3]
	v_mov_b64_e32 v[110:111], v[2:3]
	v_mov_b64_e32 v[112:113], v[2:3]
	v_mov_b64_e32 v[114:115], v[2:3]
	v_mov_b64_e32 v[116:117], v[2:3]
	v_mov_b64_e32 v[118:119], v[2:3]
	v_mov_b64_e32 v[120:121], v[2:3]
	v_mov_b64_e32 v[122:123], v[2:3]
	v_mov_b64_e32 v[124:125], v[2:3]
	v_mov_b64_e32 v[126:127], v[2:3]
	v_mov_b64_e32 v[128:129], v[2:3]
	s_mov_b32 s8, s60
	s_mov_b32 s50, s61
	s_mov_b64 s[10:11], s[16:17]
	s_mov_b32 s55, s14
	s_branch .LBB0_734

.LBB0_862:
	ds_read_b128 v[154:157], v141
	ds_read_b128 v[158:161], v141 offset:1024
	ds_read_b128 v[162:165], v141 offset:2048
	ds_read_b128 v[166:169], v141 offset:3072
	ds_read_b128 v[170:173], v182
	ds_read_b128 v[174:177], v182 offset:1024
	ds_read_b128 v[178:181], v182 offset:2048
	ds_read_b128 v[186:189], v182 offset:3072
	s_add_u32 s28, s12, 0xfffc0080
	s_addc_u32 s29, s13, -1
	s_cmp_eq_u32 s34, 12
	s_cselect_b32 s31, s9, s29
	s_cselect_b32 s30, s11, s28
	s_cselect_b32 s29, s14, s24
	s_cselect_b32 s28, s22, s23
	s_add_i32 m0, s87, 0xc000
	ds_read_b128 v[190:193], v183
	ds_read_b128 v[194:197], v183 offset:1024
	ds_read_b128 v[198:201], v183 offset:2048
	ds_read_b128 v[202:205], v183 offset:3072
	ds_read_b128 v[206:209], v183 offset:4096
	ds_read_b128 v[210:213], v183 offset:5120
	ds_read_b128 v[214:217], v183 offset:6144
	ds_read_b128 v[218:221], v183 offset:7168
	global_load_lds_dwordx4 v146, s[12:13]
	s_add_i32 m0, s87, 0xe000
	s_nop 0
	global_load_lds_dwordx4 v148, s[12:13]
	s_waitcnt vmcnt(8)
	s_waitcnt lgkmcnt(0)
	s_barrier
	v_mfma_f32_16x16x32_bf16 v[126:129], v[154:157], v[190:193], v[126:129]
	v_mfma_f32_16x16x32_bf16 v[122:125], v[162:165], v[190:193], v[122:125]
	v_mfma_f32_16x16x32_bf16 v[118:121], v[154:157], v[198:201], v[118:121]
	v_mfma_f32_16x16x32_bf16 v[114:117], v[162:165], v[198:201], v[114:117]
	v_mfma_f32_16x16x32_bf16 v[110:113], v[154:157], v[206:209], v[110:113]
	v_mfma_f32_16x16x32_bf16 v[106:109], v[162:165], v[206:209], v[106:109]
	v_mfma_f32_16x16x32_bf16 v[102:105], v[154:157], v[214:217], v[102:105]
	v_mfma_f32_16x16x32_bf16 v[98:101], v[162:165], v[214:217], v[98:101]
	v_mfma_f32_16x16x32_bf16 v[126:129], v[158:161], v[194:197], v[126:129]
	v_mfma_f32_16x16x32_bf16 v[122:125], v[166:169], v[194:197], v[122:125]
	v_mfma_f32_16x16x32_bf16 v[118:121], v[158:161], v[202:205], v[118:121]
	v_mfma_f32_16x16x32_bf16 v[114:117], v[166:169], v[202:205], v[114:117]
	v_mfma_f32_16x16x32_bf16 v[110:113], v[158:161], v[210:213], v[110:113]
	v_mfma_f32_16x16x32_bf16 v[106:109], v[166:169], v[210:213], v[106:109]
	v_mfma_f32_16x16x32_bf16 v[102:105], v[158:161], v[218:221], v[102:105]
	v_mfma_f32_16x16x32_bf16 v[98:101], v[166:169], v[218:221], v[98:101]
	v_mfma_f32_16x16x32_bf16 v[62:65], v[170:173], v[190:193], v[62:65]
	v_mfma_f32_16x16x32_bf16 v[58:61], v[178:181], v[190:193], v[58:61]
	v_mfma_f32_16x16x32_bf16 v[54:57], v[170:173], v[198:201], v[54:57]
	v_mfma_f32_16x16x32_bf16 v[50:53], v[178:181], v[198:201], v[50:53]
	v_mfma_f32_16x16x32_bf16 v[46:49], v[170:173], v[206:209], v[46:49]
	v_mfma_f32_16x16x32_bf16 v[42:45], v[178:181], v[206:209], v[42:45]
	v_mfma_f32_16x16x32_bf16 v[38:41], v[170:173], v[214:217], v[38:41]
	v_mfma_f32_16x16x32_bf16 v[34:37], v[178:181], v[214:217], v[34:37]
	v_mfma_f32_16x16x32_bf16 v[62:65], v[174:177], v[194:197], v[62:65]
	v_mfma_f32_16x16x32_bf16 v[58:61], v[186:189], v[194:197], v[58:61]
	v_mfma_f32_16x16x32_bf16 v[54:57], v[174:177], v[202:205], v[54:57]
	v_mfma_f32_16x16x32_bf16 v[50:53], v[186:189], v[202:205], v[50:53]
	v_mfma_f32_16x16x32_bf16 v[46:49], v[174:177], v[210:213], v[46:49]
	v_mfma_f32_16x16x32_bf16 v[42:45], v[186:189], v[210:213], v[42:45]
	v_mfma_f32_16x16x32_bf16 v[38:41], v[174:177], v[218:221], v[38:41]
	v_mfma_f32_16x16x32_bf16 v[34:37], v[186:189], v[218:221], v[34:37]
	s_barrier
	s_add_i32 s35, s97, s77
	s_mov_b32 m0, s35
	ds_read_b128 v[190:193], v183 offset:16384
	ds_read_b128 v[194:197], v183 offset:17408
	ds_read_b128 v[198:201], v183 offset:18432
	ds_read_b128 v[202:205], v183 offset:19456
	ds_read_b128 v[206:209], v183 offset:20480
	ds_read_b128 v[210:213], v183 offset:21504
	ds_read_b128 v[214:217], v183 offset:22528
	ds_read_b128 v[218:221], v183 offset:23552
	global_load_lds_dwordx4 v132, s[28:29]
	s_add_i32 m0, s35, 0x2000
	s_add_u32 s68, s28, 0x40000
	s_addc_u32 s69, s29, 0
	s_add_i32 s35, s74, s77
	global_load_lds_dwordx4 v136, s[28:29]
	s_mov_b32 m0, s35
	s_nop 0
	global_load_lds_dwordx4 v132, s[68:69]
	s_add_i32 m0, s35, 0x2000
	s_nop 0
	global_load_lds_dwordx4 v136, s[68:69]
	s_mov_b32 m0, s87
	s_nop 0
	global_load_lds_dwordx4 v130, s[30:31]
	s_mov_b32 m0, s88
	s_nop 0
	global_load_lds_dwordx4 v134, s[30:31]
	s_waitcnt vmcnt(8)
	s_waitcnt lgkmcnt(0)
	s_barrier
	v_mfma_f32_16x16x32_bf16 v[94:97], v[154:157], v[190:193], v[94:97]
	v_mfma_f32_16x16x32_bf16 v[90:93], v[162:165], v[190:193], v[90:93]
	v_mfma_f32_16x16x32_bf16 v[86:89], v[154:157], v[198:201], v[86:89]
	v_mfma_f32_16x16x32_bf16 v[82:85], v[162:165], v[198:201], v[82:85]
	v_mfma_f32_16x16x32_bf16 v[78:81], v[154:157], v[206:209], v[78:81]
	v_mfma_f32_16x16x32_bf16 v[74:77], v[162:165], v[206:209], v[74:77]
	v_mfma_f32_16x16x32_bf16 v[70:73], v[154:157], v[214:217], v[70:73]
	v_mfma_f32_16x16x32_bf16 v[66:69], v[162:165], v[214:217], v[66:69]
	v_mfma_f32_16x16x32_bf16 v[94:97], v[158:161], v[194:197], v[94:97]
	v_mfma_f32_16x16x32_bf16 v[90:93], v[166:169], v[194:197], v[90:93]
	v_mfma_f32_16x16x32_bf16 v[86:89], v[158:161], v[202:205], v[86:89]
	v_mfma_f32_16x16x32_bf16 v[82:85], v[166:169], v[202:205], v[82:85]
	v_mfma_f32_16x16x32_bf16 v[78:81], v[158:161], v[210:213], v[78:81]
	v_mfma_f32_16x16x32_bf16 v[74:77], v[166:169], v[210:213], v[74:77]
	v_mfma_f32_16x16x32_bf16 v[70:73], v[158:161], v[218:221], v[70:73]
	v_mfma_f32_16x16x32_bf16 v[66:69], v[166:169], v[218:221], v[66:69]
	v_mfma_f32_16x16x32_bf16 v[30:33], v[170:173], v[190:193], v[30:33]
	v_mfma_f32_16x16x32_bf16 v[26:29], v[178:181], v[190:193], v[26:29]
	v_mfma_f32_16x16x32_bf16 v[22:25], v[170:173], v[198:201], v[22:25]
	v_mfma_f32_16x16x32_bf16 v[18:21], v[178:181], v[198:201], v[18:21]
	v_mfma_f32_16x16x32_bf16 v[14:17], v[170:173], v[206:209], v[14:17]
	v_mfma_f32_16x16x32_bf16 v[10:13], v[178:181], v[206:209], v[10:13]
	v_mfma_f32_16x16x32_bf16 v[6:9], v[170:173], v[214:217], v[6:9]
	v_mfma_f32_16x16x32_bf16 v[2:5], v[178:181], v[214:217], v[2:5]
	v_mfma_f32_16x16x32_bf16 v[30:33], v[174:177], v[194:197], v[30:33]
	v_mfma_f32_16x16x32_bf16 v[26:29], v[186:189], v[194:197], v[26:29]
	v_mfma_f32_16x16x32_bf16 v[22:25], v[174:177], v[202:205], v[22:25]
	v_mfma_f32_16x16x32_bf16 v[18:21], v[186:189], v[202:205], v[18:21]
	v_mfma_f32_16x16x32_bf16 v[14:17], v[174:177], v[210:213], v[14:17]
	v_mfma_f32_16x16x32_bf16 v[10:13], v[186:189], v[210:213], v[10:13]
	v_mfma_f32_16x16x32_bf16 v[6:9], v[174:177], v[218:221], v[6:9]
	v_mfma_f32_16x16x32_bf16 v[2:5], v[186:189], v[218:221], v[2:5]
	s_barrier
	s_add_i32 s35, 0, 0x18000
	s_add_i32 s63, 0, 0x1c000
	v_add_u32_e32 v166, s35, v139
	v_add_u32_e32 v185, s63, v139
	ds_read_b128 v[154:157], v166
	ds_read_b128 v[158:161], v166 offset:1024
	ds_read_b128 v[162:165], v166 offset:2048
	ds_read_b128 v[166:169], v166 offset:3072
	ds_read_b128 v[170:173], v185
	ds_read_b128 v[174:177], v185 offset:1024
	ds_read_b128 v[178:181], v185 offset:2048
	ds_read_b128 v[186:189], v185 offset:3072
	s_add_u32 s98, s30, 0x40000
	s_addc_u32 s99, s31, 0
	s_mov_b32 m0, s89
	ds_read_b128 v[190:193], v183 offset:32768
	ds_read_b128 v[194:197], v183 offset:33792
	ds_read_b128 v[198:201], v183 offset:34816
	ds_read_b128 v[202:205], v183 offset:35840
	ds_read_b128 v[206:209], v183 offset:36864
	ds_read_b128 v[210:213], v183 offset:37888
	ds_read_b128 v[214:217], v183 offset:38912
	ds_read_b128 v[218:221], v183 offset:39936
	global_load_lds_dwordx4 v130, s[98:99]
	s_mov_b32 m0, s90
	s_nop 0
	global_load_lds_dwordx4 v134, s[98:99]
	s_waitcnt vmcnt(8)
	s_waitcnt lgkmcnt(0)
	s_barrier
	v_mfma_f32_16x16x32_bf16 v[126:129], v[154:157], v[190:193], v[126:129]
	v_mfma_f32_16x16x32_bf16 v[122:125], v[162:165], v[190:193], v[122:125]
	v_mfma_f32_16x16x32_bf16 v[118:121], v[154:157], v[198:201], v[118:121]
	v_mfma_f32_16x16x32_bf16 v[114:117], v[162:165], v[198:201], v[114:117]
	v_mfma_f32_16x16x32_bf16 v[110:113], v[154:157], v[206:209], v[110:113]
	v_mfma_f32_16x16x32_bf16 v[106:109], v[162:165], v[206:209], v[106:109]
	v_mfma_f32_16x16x32_bf16 v[102:105], v[154:157], v[214:217], v[102:105]
	v_mfma_f32_16x16x32_bf16 v[98:101], v[162:165], v[214:217], v[98:101]
	v_mfma_f32_16x16x32_bf16 v[126:129], v[158:161], v[194:197], v[126:129]
	v_mfma_f32_16x16x32_bf16 v[122:125], v[166:169], v[194:197], v[122:125]
	v_mfma_f32_16x16x32_bf16 v[118:121], v[158:161], v[202:205], v[118:121]
	v_mfma_f32_16x16x32_bf16 v[114:117], v[166:169], v[202:205], v[114:117]
	v_mfma_f32_16x16x32_bf16 v[110:113], v[158:161], v[210:213], v[110:113]
	v_mfma_f32_16x16x32_bf16 v[106:109], v[166:169], v[210:213], v[106:109]
	v_mfma_f32_16x16x32_bf16 v[102:105], v[158:161], v[218:221], v[102:105]
	v_mfma_f32_16x16x32_bf16 v[98:101], v[166:169], v[218:221], v[98:101]
	v_mfma_f32_16x16x32_bf16 v[62:65], v[170:173], v[190:193], v[62:65]
	v_mfma_f32_16x16x32_bf16 v[58:61], v[178:181], v[190:193], v[58:61]
	v_mfma_f32_16x16x32_bf16 v[54:57], v[170:173], v[198:201], v[54:57]
	v_mfma_f32_16x16x32_bf16 v[50:53], v[178:181], v[198:201], v[50:53]
	v_mfma_f32_16x16x32_bf16 v[46:49], v[170:173], v[206:209], v[46:49]
	v_mfma_f32_16x16x32_bf16 v[42:45], v[178:181], v[206:209], v[42:45]
	v_mfma_f32_16x16x32_bf16 v[38:41], v[170:173], v[214:217], v[38:41]
	v_mfma_f32_16x16x32_bf16 v[34:37], v[178:181], v[214:217], v[34:37]
	v_mfma_f32_16x16x32_bf16 v[62:65], v[174:177], v[194:197], v[62:65]
	v_mfma_f32_16x16x32_bf16 v[58:61], v[186:189], v[194:197], v[58:61]
	v_mfma_f32_16x16x32_bf16 v[54:57], v[174:177], v[202:205], v[54:57]
	v_mfma_f32_16x16x32_bf16 v[50:53], v[186:189], v[202:205], v[50:53]
	v_mfma_f32_16x16x32_bf16 v[46:49], v[174:177], v[210:213], v[46:49]
	v_mfma_f32_16x16x32_bf16 v[42:45], v[186:189], v[210:213], v[42:45]
	v_mfma_f32_16x16x32_bf16 v[38:41], v[174:177], v[218:221], v[38:41]
	v_mfma_f32_16x16x32_bf16 v[34:37], v[186:189], v[218:221], v[34:37]
	s_barrier
	s_add_i32 s98, s35, s77
	s_add_i32 m0, s98, 0xffffff80
	ds_read_b128 v[190:193], v183 offset:49152
	ds_read_b128 v[194:197], v183 offset:50176
	ds_read_b128 v[198:201], v183 offset:51200
	ds_read_b128 v[202:205], v183 offset:52224
	ds_read_b128 v[206:209], v183 offset:53248
	ds_read_b128 v[210:213], v183 offset:54272
	ds_read_b128 v[214:217], v183 offset:55296
	ds_read_b128 v[218:221], v183 offset:56320
	global_load_lds_dwordx4 v132, s[28:29] offset:128
	s_add_i32 m0, s98, 0x1f80
	s_add_i32 s98, s63, s77
	global_load_lds_dwordx4 v136, s[28:29] offset:128
	s_add_u32 s28, s28, 0x40080
	s_addc_u32 s29, s29, 0
	s_mov_b32 m0, s98
	s_nop 0
	global_load_lds_dwordx4 v132, s[28:29]
	s_add_i32 m0, s98, 0x2000
	s_nop 0
	global_load_lds_dwordx4 v136, s[28:29]
	s_add_i32 m0, s92, 0xffffff80
	s_nop 0
	global_load_lds_dwordx4 v130, s[30:31] offset:128
	s_add_i32 m0, s93, 0xffffff80
	s_nop 0
	global_load_lds_dwordx4 v134, s[30:31] offset:128
	s_waitcnt vmcnt(8)
	s_waitcnt lgkmcnt(0)
	s_barrier
	v_mfma_f32_16x16x32_bf16 v[94:97], v[154:157], v[190:193], v[94:97]
	v_mfma_f32_16x16x32_bf16 v[90:93], v[162:165], v[190:193], v[90:93]
	v_mfma_f32_16x16x32_bf16 v[86:89], v[154:157], v[198:201], v[86:89]
	v_mfma_f32_16x16x32_bf16 v[82:85], v[162:165], v[198:201], v[82:85]
	v_mfma_f32_16x16x32_bf16 v[78:81], v[154:157], v[206:209], v[78:81]
	v_mfma_f32_16x16x32_bf16 v[74:77], v[162:165], v[206:209], v[74:77]
	v_mfma_f32_16x16x32_bf16 v[70:73], v[154:157], v[214:217], v[70:73]
	v_mfma_f32_16x16x32_bf16 v[66:69], v[162:165], v[214:217], v[66:69]
	v_mfma_f32_16x16x32_bf16 v[94:97], v[158:161], v[194:197], v[94:97]
	v_mfma_f32_16x16x32_bf16 v[90:93], v[166:169], v[194:197], v[90:93]
	v_mfma_f32_16x16x32_bf16 v[86:89], v[158:161], v[202:205], v[86:89]
	v_mfma_f32_16x16x32_bf16 v[82:85], v[166:169], v[202:205], v[82:85]
	v_mfma_f32_16x16x32_bf16 v[78:81], v[158:161], v[210:213], v[78:81]
	v_mfma_f32_16x16x32_bf16 v[74:77], v[166:169], v[210:213], v[74:77]
	v_mfma_f32_16x16x32_bf16 v[70:73], v[158:161], v[218:221], v[70:73]
	v_mfma_f32_16x16x32_bf16 v[66:69], v[166:169], v[218:221], v[66:69]
	v_mfma_f32_16x16x32_bf16 v[30:33], v[170:173], v[190:193], v[30:33]
	v_mfma_f32_16x16x32_bf16 v[26:29], v[178:181], v[190:193], v[26:29]
	v_mfma_f32_16x16x32_bf16 v[22:25], v[170:173], v[198:201], v[22:25]
	v_mfma_f32_16x16x32_bf16 v[18:21], v[178:181], v[198:201], v[18:21]
	v_mfma_f32_16x16x32_bf16 v[14:17], v[170:173], v[206:209], v[14:17]
	v_mfma_f32_16x16x32_bf16 v[10:13], v[178:181], v[206:209], v[10:13]
	v_mfma_f32_16x16x32_bf16 v[6:9], v[170:173], v[214:217], v[6:9]
	v_mfma_f32_16x16x32_bf16 v[2:5], v[178:181], v[214:217], v[2:5]
	v_mfma_f32_16x16x32_bf16 v[30:33], v[174:177], v[194:197], v[30:33]
	v_mfma_f32_16x16x32_bf16 v[26:29], v[186:189], v[194:197], v[26:29]
	v_mfma_f32_16x16x32_bf16 v[22:25], v[174:177], v[202:205], v[22:25]
	v_mfma_f32_16x16x32_bf16 v[18:21], v[186:189], v[202:205], v[18:21]
	v_mfma_f32_16x16x32_bf16 v[14:17], v[174:177], v[210:213], v[14:17]
	v_mfma_f32_16x16x32_bf16 v[10:13], v[186:189], v[210:213], v[10:13]
	v_mfma_f32_16x16x32_bf16 v[6:9], v[174:177], v[218:221], v[6:9]
	v_mfma_f32_16x16x32_bf16 v[2:5], v[186:189], v[218:221], v[2:5]
	s_barrier
	s_add_i32 s34, s34, 2
	s_add_u32 s12, s12, 0x100
	s_addc_u32 s13, s13, 0
	s_add_u32 s23, s23, 0x100
	s_addc_u32 s24, s24, 0
	s_cmp_gt_u32 s34, 13
	s_cbranch_scc0 .LBB0_862
	s_and_b64 vcc, exec, s[54:55]
	s_cbranch_vccz .LBB0_865
	s_barrier

.LBB0_1654:
	ds_read_b128 v[152:155], v131
	ds_read_b128 v[156:159], v131 offset:1024
	ds_read_b128 v[160:163], v131 offset:2048
	ds_read_b128 v[180:183], v131 offset:3072
	ds_read_b128 v[184:187], v176
	ds_read_b128 v[188:191], v176 offset:1024
	ds_read_b128 v[192:195], v176 offset:2048
	ds_read_b128 v[196:199], v176 offset:3072
	s_add_u32 s28, s36, 0xfffc0080
	s_addc_u32 s29, s37, -1
	s_cmp_eq_u32 s51, 12
	s_cselect_b32 s31, s15, s29
	s_cselect_b32 s30, s47, s28
	s_cselect_b32 s29, s13, s50
	s_cselect_b32 s28, s48, s49
	s_add_i32 m0, s33, 0xc000
	ds_read_b128 v[200:203], v177
	ds_read_b128 v[204:207], v177 offset:1024
	ds_read_b128 v[208:211], v177 offset:2048
	ds_read_b128 v[212:215], v177 offset:3072
	ds_read_b128 v[216:219], v177 offset:4096
	ds_read_b128 v[220:223], v177 offset:5120
	ds_read_b128 v[224:227], v177 offset:6144
	ds_read_b128 v[228:231], v177 offset:7168
	global_load_lds_dwordx4 v144, s[36:37]
	s_add_i32 m0, s33, 0xe000
	s_nop 0
	global_load_lds_dwordx4 v146, s[36:37]
	s_waitcnt vmcnt(8)
	s_waitcnt lgkmcnt(0)
	s_barrier
	v_mfma_f32_16x16x32_bf16 v[126:129], v[152:155], v[200:203], v[126:129]
	v_mfma_f32_16x16x32_bf16 v[122:125], v[160:163], v[200:203], v[122:125]
	v_mfma_f32_16x16x32_bf16 v[110:113], v[152:155], v[208:211], v[110:113]
	v_mfma_f32_16x16x32_bf16 v[106:109], v[160:163], v[208:211], v[106:109]
	v_mfma_f32_16x16x32_bf16 v[94:97], v[152:155], v[216:219], v[94:97]
	v_mfma_f32_16x16x32_bf16 v[90:93], v[160:163], v[216:219], v[90:93]
	v_mfma_f32_16x16x32_bf16 v[78:81], v[152:155], v[224:227], v[78:81]
	v_mfma_f32_16x16x32_bf16 v[74:77], v[160:163], v[224:227], v[74:77]
	v_mfma_f32_16x16x32_bf16 v[126:129], v[156:159], v[204:207], v[126:129]
	v_mfma_f32_16x16x32_bf16 v[122:125], v[180:183], v[204:207], v[122:125]
	v_mfma_f32_16x16x32_bf16 v[110:113], v[156:159], v[212:215], v[110:113]
	v_mfma_f32_16x16x32_bf16 v[106:109], v[180:183], v[212:215], v[106:109]
	v_mfma_f32_16x16x32_bf16 v[94:97], v[156:159], v[220:223], v[94:97]
	v_mfma_f32_16x16x32_bf16 v[90:93], v[180:183], v[220:223], v[90:93]
	v_mfma_f32_16x16x32_bf16 v[78:81], v[156:159], v[228:231], v[78:81]
	v_mfma_f32_16x16x32_bf16 v[74:77], v[180:183], v[228:231], v[74:77]
	v_mfma_f32_16x16x32_bf16 v[118:121], v[184:187], v[200:203], v[118:121]
	v_mfma_f32_16x16x32_bf16 v[114:117], v[192:195], v[200:203], v[114:117]
	v_mfma_f32_16x16x32_bf16 v[102:105], v[184:187], v[208:211], v[102:105]
	v_mfma_f32_16x16x32_bf16 v[98:101], v[192:195], v[208:211], v[98:101]
	v_mfma_f32_16x16x32_bf16 v[86:89], v[184:187], v[216:219], v[86:89]
	v_mfma_f32_16x16x32_bf16 v[82:85], v[192:195], v[216:219], v[82:85]
	v_mfma_f32_16x16x32_bf16 v[70:73], v[184:187], v[224:227], v[70:73]
	v_mfma_f32_16x16x32_bf16 v[66:69], v[192:195], v[224:227], v[66:69]
	v_mfma_f32_16x16x32_bf16 v[118:121], v[188:191], v[204:207], v[118:121]
	v_mfma_f32_16x16x32_bf16 v[114:117], v[196:199], v[204:207], v[114:117]
	v_mfma_f32_16x16x32_bf16 v[102:105], v[188:191], v[212:215], v[102:105]
	v_mfma_f32_16x16x32_bf16 v[98:101], v[196:199], v[212:215], v[98:101]
	v_mfma_f32_16x16x32_bf16 v[86:89], v[188:191], v[220:223], v[86:89]
	v_mfma_f32_16x16x32_bf16 v[82:85], v[196:199], v[220:223], v[82:85]
	v_mfma_f32_16x16x32_bf16 v[70:73], v[188:191], v[228:231], v[70:73]
	v_mfma_f32_16x16x32_bf16 v[66:69], v[196:199], v[228:231], v[66:69]
	s_barrier
	s_add_i32 s52, s45, s25
	s_mov_b32 m0, s52
	ds_read_b128 v[200:203], v177 offset:16384
	ds_read_b128 v[204:207], v177 offset:17408
	ds_read_b128 v[208:211], v177 offset:18432
	ds_read_b128 v[212:215], v177 offset:19456
	ds_read_b128 v[216:219], v177 offset:20480
	ds_read_b128 v[220:223], v177 offset:21504
	ds_read_b128 v[224:227], v177 offset:22528
	ds_read_b128 v[228:231], v177 offset:23552
	global_load_lds_dwordx4 v134, s[28:29]
	s_add_i32 m0, s52, 0x2000
	s_add_u32 s52, s28, 0x40000
	s_addc_u32 s53, s29, 0
	s_add_i32 s54, s46, s25
	global_load_lds_dwordx4 v140, s[28:29]
	s_mov_b32 m0, s54
	s_nop 0
	global_load_lds_dwordx4 v134, s[52:53]
	s_add_i32 m0, s54, 0x2000
	s_nop 0
	global_load_lds_dwordx4 v140, s[52:53]
	s_mov_b32 m0, s33
	s_nop 0
	global_load_lds_dwordx4 v132, s[30:31]
	s_mov_b32 m0, s34
	s_nop 0
	global_load_lds_dwordx4 v136, s[30:31]
	s_waitcnt vmcnt(8)
	s_waitcnt lgkmcnt(0)
	s_barrier
	v_mfma_f32_16x16x32_bf16 v[62:65], v[152:155], v[200:203], v[62:65]
	v_mfma_f32_16x16x32_bf16 v[58:61], v[160:163], v[200:203], v[58:61]
	v_mfma_f32_16x16x32_bf16 v[46:49], v[152:155], v[208:211], v[46:49]
	v_mfma_f32_16x16x32_bf16 v[42:45], v[160:163], v[208:211], v[42:45]
	v_mfma_f32_16x16x32_bf16 v[30:33], v[152:155], v[216:219], v[30:33]
	v_mfma_f32_16x16x32_bf16 v[26:29], v[160:163], v[216:219], v[26:29]
	v_mfma_f32_16x16x32_bf16 v[14:17], v[152:155], v[224:227], v[14:17]
	v_mfma_f32_16x16x32_bf16 v[10:13], v[160:163], v[224:227], v[10:13]
	v_mfma_f32_16x16x32_bf16 v[62:65], v[156:159], v[204:207], v[62:65]
	v_mfma_f32_16x16x32_bf16 v[58:61], v[180:183], v[204:207], v[58:61]
	v_mfma_f32_16x16x32_bf16 v[46:49], v[156:159], v[212:215], v[46:49]
	v_mfma_f32_16x16x32_bf16 v[42:45], v[180:183], v[212:215], v[42:45]
	v_mfma_f32_16x16x32_bf16 v[30:33], v[156:159], v[220:223], v[30:33]
	v_mfma_f32_16x16x32_bf16 v[26:29], v[180:183], v[220:223], v[26:29]
	v_mfma_f32_16x16x32_bf16 v[14:17], v[156:159], v[228:231], v[14:17]
	v_mfma_f32_16x16x32_bf16 v[10:13], v[180:183], v[228:231], v[10:13]
	v_mfma_f32_16x16x32_bf16 v[54:57], v[184:187], v[200:203], v[54:57]
	v_mfma_f32_16x16x32_bf16 v[50:53], v[192:195], v[200:203], v[50:53]
	v_mfma_f32_16x16x32_bf16 v[38:41], v[184:187], v[208:211], v[38:41]
	v_mfma_f32_16x16x32_bf16 v[34:37], v[192:195], v[208:211], v[34:37]
	v_mfma_f32_16x16x32_bf16 v[22:25], v[184:187], v[216:219], v[22:25]
	v_mfma_f32_16x16x32_bf16 v[18:21], v[192:195], v[216:219], v[18:21]
	v_mfma_f32_16x16x32_bf16 v[6:9], v[184:187], v[224:227], v[6:9]
	v_mfma_f32_16x16x32_bf16 v[2:5], v[192:195], v[224:227], v[2:5]
	v_mfma_f32_16x16x32_bf16 v[54:57], v[188:191], v[204:207], v[54:57]
	v_mfma_f32_16x16x32_bf16 v[50:53], v[196:199], v[204:207], v[50:53]
	v_mfma_f32_16x16x32_bf16 v[38:41], v[188:191], v[212:215], v[38:41]
	v_mfma_f32_16x16x32_bf16 v[34:37], v[196:199], v[212:215], v[34:37]
	v_mfma_f32_16x16x32_bf16 v[22:25], v[188:191], v[220:223], v[22:25]
	v_mfma_f32_16x16x32_bf16 v[18:21], v[196:199], v[220:223], v[18:21]
	v_mfma_f32_16x16x32_bf16 v[6:9], v[188:191], v[228:231], v[6:9]
	v_mfma_f32_16x16x32_bf16 v[2:5], v[196:199], v[228:231], v[2:5]
	s_barrier
	s_add_i32 s52, 0, 0x18000
	v_add_u32_e32 v179, s52, v175
	s_add_i32 s53, 0, 0x1c000
	ds_read_b128 v[152:155], v179
	ds_read_b128 v[156:159], v179 offset:1024
	ds_read_b128 v[160:163], v179 offset:2048
	ds_read_b128 v[180:183], v179 offset:3072
	v_add_u32_e32 v179, s53, v175
	ds_read_b128 v[184:187], v179
	ds_read_b128 v[188:191], v179 offset:1024
	ds_read_b128 v[192:195], v179 offset:2048
	ds_read_b128 v[196:199], v179 offset:3072
	s_add_u32 s98, s30, 0x40000
	s_addc_u32 s99, s31, 0
	s_mov_b32 m0, s35
	ds_read_b128 v[200:203], v177 offset:32768
	ds_read_b128 v[204:207], v177 offset:33792
	ds_read_b128 v[208:211], v177 offset:34816
	ds_read_b128 v[212:215], v177 offset:35840
	ds_read_b128 v[216:219], v177 offset:36864
	ds_read_b128 v[220:223], v177 offset:37888
	ds_read_b128 v[224:227], v177 offset:38912
	ds_read_b128 v[228:231], v177 offset:39936
	global_load_lds_dwordx4 v132, s[98:99]
	s_mov_b32 m0, s38
	s_nop 0
	global_load_lds_dwordx4 v136, s[98:99]
	s_waitcnt vmcnt(8)
	s_waitcnt lgkmcnt(0)
	s_barrier
	v_mfma_f32_16x16x32_bf16 v[126:129], v[152:155], v[200:203], v[126:129]
	v_mfma_f32_16x16x32_bf16 v[122:125], v[160:163], v[200:203], v[122:125]
	v_mfma_f32_16x16x32_bf16 v[110:113], v[152:155], v[208:211], v[110:113]
	v_mfma_f32_16x16x32_bf16 v[106:109], v[160:163], v[208:211], v[106:109]
	v_mfma_f32_16x16x32_bf16 v[94:97], v[152:155], v[216:219], v[94:97]
	v_mfma_f32_16x16x32_bf16 v[90:93], v[160:163], v[216:219], v[90:93]
	v_mfma_f32_16x16x32_bf16 v[78:81], v[152:155], v[224:227], v[78:81]
	v_mfma_f32_16x16x32_bf16 v[74:77], v[160:163], v[224:227], v[74:77]
	v_mfma_f32_16x16x32_bf16 v[126:129], v[156:159], v[204:207], v[126:129]
	v_mfma_f32_16x16x32_bf16 v[122:125], v[180:183], v[204:207], v[122:125]
	v_mfma_f32_16x16x32_bf16 v[110:113], v[156:159], v[212:215], v[110:113]
	v_mfma_f32_16x16x32_bf16 v[106:109], v[180:183], v[212:215], v[106:109]
	v_mfma_f32_16x16x32_bf16 v[94:97], v[156:159], v[220:223], v[94:97]
	v_mfma_f32_16x16x32_bf16 v[90:93], v[180:183], v[220:223], v[90:93]
	v_mfma_f32_16x16x32_bf16 v[78:81], v[156:159], v[228:231], v[78:81]
	v_mfma_f32_16x16x32_bf16 v[74:77], v[180:183], v[228:231], v[74:77]
	v_mfma_f32_16x16x32_bf16 v[118:121], v[184:187], v[200:203], v[118:121]
	v_mfma_f32_16x16x32_bf16 v[114:117], v[192:195], v[200:203], v[114:117]
	v_mfma_f32_16x16x32_bf16 v[102:105], v[184:187], v[208:211], v[102:105]
	v_mfma_f32_16x16x32_bf16 v[98:101], v[192:195], v[208:211], v[98:101]
	v_mfma_f32_16x16x32_bf16 v[86:89], v[184:187], v[216:219], v[86:89]
	v_mfma_f32_16x16x32_bf16 v[82:85], v[192:195], v[216:219], v[82:85]
	v_mfma_f32_16x16x32_bf16 v[70:73], v[184:187], v[224:227], v[70:73]
	v_mfma_f32_16x16x32_bf16 v[66:69], v[192:195], v[224:227], v[66:69]
	v_mfma_f32_16x16x32_bf16 v[118:121], v[188:191], v[204:207], v[118:121]
	v_mfma_f32_16x16x32_bf16 v[114:117], v[196:199], v[204:207], v[114:117]
	v_mfma_f32_16x16x32_bf16 v[102:105], v[188:191], v[212:215], v[102:105]
	v_mfma_f32_16x16x32_bf16 v[98:101], v[196:199], v[212:215], v[98:101]
	v_mfma_f32_16x16x32_bf16 v[86:89], v[188:191], v[220:223], v[86:89]
	v_mfma_f32_16x16x32_bf16 v[82:85], v[196:199], v[220:223], v[82:85]
	v_mfma_f32_16x16x32_bf16 v[70:73], v[188:191], v[228:231], v[70:73]
	v_mfma_f32_16x16x32_bf16 v[66:69], v[196:199], v[228:231], v[66:69]
	s_barrier
	s_add_i32 s98, s52, s25
	s_add_i32 m0, s98, 0xffffff80
	ds_read_b128 v[200:203], v177 offset:49152
	ds_read_b128 v[204:207], v177 offset:50176
	ds_read_b128 v[208:211], v177 offset:51200
	ds_read_b128 v[212:215], v177 offset:52224
	ds_read_b128 v[216:219], v177 offset:53248
	ds_read_b128 v[220:223], v177 offset:54272
	ds_read_b128 v[224:227], v177 offset:55296
	ds_read_b128 v[228:231], v177 offset:56320
	global_load_lds_dwordx4 v134, s[28:29] offset:128
	s_add_i32 m0, s98, 0x1f80
	s_add_i32 s98, s53, s25
	global_load_lds_dwordx4 v140, s[28:29] offset:128
	s_add_u32 s28, s28, 0x40080
	s_addc_u32 s29, s29, 0
	s_mov_b32 m0, s98
	s_nop 0
	global_load_lds_dwordx4 v134, s[28:29]
	s_add_i32 m0, s98, 0x2000
	s_nop 0
	global_load_lds_dwordx4 v140, s[28:29]
	s_add_i32 m0, s42, 0xffffff80
	s_nop 0
	global_load_lds_dwordx4 v132, s[30:31] offset:128
	s_add_i32 m0, s43, 0xffffff80
	s_nop 0
	global_load_lds_dwordx4 v136, s[30:31] offset:128
	s_waitcnt vmcnt(8)
	s_waitcnt lgkmcnt(0)
	s_barrier
	v_mfma_f32_16x16x32_bf16 v[62:65], v[152:155], v[200:203], v[62:65]
	v_mfma_f32_16x16x32_bf16 v[58:61], v[160:163], v[200:203], v[58:61]
	v_mfma_f32_16x16x32_bf16 v[46:49], v[152:155], v[208:211], v[46:49]
	v_mfma_f32_16x16x32_bf16 v[42:45], v[160:163], v[208:211], v[42:45]
	v_mfma_f32_16x16x32_bf16 v[30:33], v[152:155], v[216:219], v[30:33]
	v_mfma_f32_16x16x32_bf16 v[26:29], v[160:163], v[216:219], v[26:29]
	v_mfma_f32_16x16x32_bf16 v[14:17], v[152:155], v[224:227], v[14:17]
	v_mfma_f32_16x16x32_bf16 v[10:13], v[160:163], v[224:227], v[10:13]
	v_mfma_f32_16x16x32_bf16 v[62:65], v[156:159], v[204:207], v[62:65]
	v_mfma_f32_16x16x32_bf16 v[58:61], v[180:183], v[204:207], v[58:61]
	v_mfma_f32_16x16x32_bf16 v[46:49], v[156:159], v[212:215], v[46:49]
	v_mfma_f32_16x16x32_bf16 v[42:45], v[180:183], v[212:215], v[42:45]
	v_mfma_f32_16x16x32_bf16 v[30:33], v[156:159], v[220:223], v[30:33]
	v_mfma_f32_16x16x32_bf16 v[26:29], v[180:183], v[220:223], v[26:29]
	v_mfma_f32_16x16x32_bf16 v[14:17], v[156:159], v[228:231], v[14:17]
	v_mfma_f32_16x16x32_bf16 v[10:13], v[180:183], v[228:231], v[10:13]
	v_mfma_f32_16x16x32_bf16 v[54:57], v[184:187], v[200:203], v[54:57]
	v_mfma_f32_16x16x32_bf16 v[50:53], v[192:195], v[200:203], v[50:53]
	v_mfma_f32_16x16x32_bf16 v[38:41], v[184:187], v[208:211], v[38:41]
	v_mfma_f32_16x16x32_bf16 v[34:37], v[192:195], v[208:211], v[34:37]
	v_mfma_f32_16x16x32_bf16 v[22:25], v[184:187], v[216:219], v[22:25]
	v_mfma_f32_16x16x32_bf16 v[18:21], v[192:195], v[216:219], v[18:21]
	v_mfma_f32_16x16x32_bf16 v[6:9], v[184:187], v[224:227], v[6:9]
	v_mfma_f32_16x16x32_bf16 v[2:5], v[192:195], v[224:227], v[2:5]
	v_mfma_f32_16x16x32_bf16 v[54:57], v[188:191], v[204:207], v[54:57]
	v_mfma_f32_16x16x32_bf16 v[50:53], v[196:199], v[204:207], v[50:53]
	v_mfma_f32_16x16x32_bf16 v[38:41], v[188:191], v[212:215], v[38:41]
	v_mfma_f32_16x16x32_bf16 v[34:37], v[196:199], v[212:215], v[34:37]
	v_mfma_f32_16x16x32_bf16 v[22:25], v[188:191], v[220:223], v[22:25]
	v_mfma_f32_16x16x32_bf16 v[18:21], v[196:199], v[220:223], v[18:21]
	v_mfma_f32_16x16x32_bf16 v[6:9], v[188:191], v[228:231], v[6:9]
	v_mfma_f32_16x16x32_bf16 v[2:5], v[196:199], v[228:231], v[2:5]
	s_barrier
	s_add_i32 s51, s51, 2
	s_add_u32 s36, s36, 0x100
	s_addc_u32 s37, s37, 0
	s_add_u32 s49, s49, 0x100
	s_addc_u32 s50, s50, 0
	s_cmp_gt_u32 s51, 13
	s_cbranch_scc0 .LBB0_1654
	s_and_b64 vcc, exec, s[10:11]
	s_cbranch_vccz .LBB0_1657
	s_barrier

.LBB0_1687:
	ds_read_b128 v[150:153], v131
	ds_read_b128 v[154:157], v131 offset:1024
	ds_read_b128 v[158:161], v131 offset:2048
	ds_read_b128 v[162:165], v131 offset:3072
	ds_read_b128 v[170:173], v146
	ds_read_b128 v[174:177], v146 offset:1024
	ds_read_b128 v[178:181], v146 offset:2048
	ds_read_b128 v[182:185], v146 offset:3072
	s_add_u32 s14, s10, s12
	s_addc_u32 s15, s11, s13
	s_add_u32 s14, s14, 0xd600100
	s_addc_u32 s15, s15, 0
	s_add_u32 s51, s38, s12
	s_addc_u32 s52, s39, s13
	s_cmpk_eq_i32 s12, 0x300
	s_cselect_b32 s17, s7, s15
	s_cselect_b32 s16, s6, s14
	s_cselect_b32 s15, s5, s52
	s_cselect_b32 s14, s4, s51
	s_mov_b32 m0, s41
	v_lshl_add_u64 v[166:167], v[142:143], 0, s[12:13]
	ds_read_b128 v[186:189], v147
	ds_read_b128 v[190:193], v147 offset:1024
	ds_read_b128 v[194:197], v147 offset:2048
	ds_read_b128 v[198:201], v147 offset:3072
	ds_read_b128 v[202:205], v147 offset:4096
	ds_read_b128 v[206:209], v147 offset:5120
	ds_read_b128 v[210:213], v147 offset:6144
	ds_read_b128 v[214:217], v147 offset:7168
	global_load_lds_dwordx4 v[166:167], off
	v_lshl_add_u64 v[166:167], v[144:145], 0, s[12:13]
	s_mov_b32 m0, s42
	s_nop 0
	global_load_lds_dwordx4 v[166:167], off
	s_waitcnt vmcnt(8)
	s_waitcnt lgkmcnt(0)
	s_barrier
	v_mfma_f32_16x16x32_bf16 v[50:53], v[150:153], v[186:189], v[50:53]
	v_mfma_f32_16x16x32_bf16 v[54:57], v[158:161], v[186:189], v[54:57]
	v_mfma_f32_16x16x32_bf16 v[82:85], v[150:153], v[194:197], v[82:85]
	v_mfma_f32_16x16x32_bf16 v[86:89], v[158:161], v[194:197], v[86:89]
	v_mfma_f32_16x16x32_bf16 v[114:117], v[150:153], v[202:205], v[114:117]
	v_mfma_f32_16x16x32_bf16 v[118:121], v[158:161], v[202:205], v[118:121]
	v_mfma_f32_16x16x32_bf16 v[110:113], v[150:153], v[210:213], v[110:113]
	v_mfma_f32_16x16x32_bf16 v[106:109], v[158:161], v[210:213], v[106:109]
	v_mfma_f32_16x16x32_bf16 v[50:53], v[154:157], v[190:193], v[50:53]
	v_mfma_f32_16x16x32_bf16 v[54:57], v[162:165], v[190:193], v[54:57]
	v_mfma_f32_16x16x32_bf16 v[82:85], v[154:157], v[198:201], v[82:85]
	v_mfma_f32_16x16x32_bf16 v[86:89], v[162:165], v[198:201], v[86:89]
	v_mfma_f32_16x16x32_bf16 v[114:117], v[154:157], v[206:209], v[114:117]
	v_mfma_f32_16x16x32_bf16 v[118:121], v[162:165], v[206:209], v[118:121]
	v_mfma_f32_16x16x32_bf16 v[110:113], v[154:157], v[214:217], v[110:113]
	v_mfma_f32_16x16x32_bf16 v[106:109], v[162:165], v[214:217], v[106:109]
	v_mfma_f32_16x16x32_bf16 v[58:61], v[170:173], v[186:189], v[58:61]
	v_mfma_f32_16x16x32_bf16 v[62:65], v[178:181], v[186:189], v[62:65]
	v_mfma_f32_16x16x32_bf16 v[90:93], v[170:173], v[194:197], v[90:93]
	v_mfma_f32_16x16x32_bf16 v[98:101], v[178:181], v[194:197], v[98:101]
	v_mfma_f32_16x16x32_bf16 v[122:125], v[170:173], v[202:205], v[122:125]
	v_mfma_f32_16x16x32_bf16 v[126:129], v[178:181], v[202:205], v[126:129]
	v_mfma_f32_16x16x32_bf16 v[102:105], v[170:173], v[210:213], v[102:105]
	v_mfma_f32_16x16x32_bf16 v[94:97], v[178:181], v[210:213], v[94:97]
	v_mfma_f32_16x16x32_bf16 v[58:61], v[174:177], v[190:193], v[58:61]
	v_mfma_f32_16x16x32_bf16 v[62:65], v[182:185], v[190:193], v[62:65]
	v_mfma_f32_16x16x32_bf16 v[90:93], v[174:177], v[198:201], v[90:93]
	v_mfma_f32_16x16x32_bf16 v[98:101], v[182:185], v[198:201], v[98:101]
	v_mfma_f32_16x16x32_bf16 v[122:125], v[174:177], v[206:209], v[122:125]
	v_mfma_f32_16x16x32_bf16 v[126:129], v[182:185], v[206:209], v[126:129]
	v_mfma_f32_16x16x32_bf16 v[102:105], v[174:177], v[214:217], v[102:105]
	v_mfma_f32_16x16x32_bf16 v[94:97], v[182:185], v[214:217], v[94:97]
	s_barrier
	s_mov_b32 m0, s43
	v_lshl_add_u64 v[166:167], s[14:15], 0, v[136:137]
	s_add_u32 s52, s14, 0x30000
	ds_read_b128 v[186:189], v147 offset:16384
	ds_read_b128 v[190:193], v147 offset:17408
	ds_read_b128 v[194:197], v147 offset:18432
	ds_read_b128 v[198:201], v147 offset:19456
	ds_read_b128 v[202:205], v147 offset:20480
	ds_read_b128 v[206:209], v147 offset:21504
	ds_read_b128 v[210:213], v147 offset:22528
	ds_read_b128 v[214:217], v147 offset:23552
	global_load_lds_dwordx4 v[166:167], off
	v_lshl_add_u64 v[218:219], s[14:15], 0, v[140:141]
	s_mov_b32 m0, s44
	s_addc_u32 s53, s15, 0
	global_load_lds_dwordx4 v[218:219], off
	v_lshl_add_u64 v[220:221], s[52:53], 0, v[136:137]
	s_mov_b32 m0, s45
	v_lshl_add_u64 v[222:223], s[16:17], 0, v[134:135]
	global_load_lds_dwordx4 v[220:221], off
	v_lshl_add_u64 v[220:221], s[52:53], 0, v[140:141]
	s_mov_b32 m0, s46
	s_nop 0
	global_load_lds_dwordx4 v[220:221], off
	v_lshl_add_u64 v[220:221], s[16:17], 0, v[132:133]
	s_mov_b32 m0, s29
	s_nop 0
	global_load_lds_dwordx4 v[220:221], off
	s_mov_b32 m0, s30
	s_nop 0
	global_load_lds_dwordx4 v[222:223], off
	s_waitcnt vmcnt(8)
	s_waitcnt lgkmcnt(0)
	s_barrier
	v_mfma_f32_16x16x32_bf16 v[78:81], v[150:153], v[186:189], v[78:81]
	v_mfma_f32_16x16x32_bf16 v[74:77], v[158:161], v[186:189], v[74:77]
	v_mfma_f32_16x16x32_bf16 v[46:49], v[150:153], v[194:197], v[46:49]
	v_mfma_f32_16x16x32_bf16 v[42:45], v[158:161], v[194:197], v[42:45]
	v_mfma_f32_16x16x32_bf16 v[30:33], v[150:153], v[202:205], v[30:33]
	v_mfma_f32_16x16x32_bf16 v[26:29], v[158:161], v[202:205], v[26:29]
	v_mfma_f32_16x16x32_bf16 v[14:17], v[150:153], v[210:213], v[14:17]
	v_mfma_f32_16x16x32_bf16 v[10:13], v[158:161], v[210:213], v[10:13]
	v_mfma_f32_16x16x32_bf16 v[78:81], v[154:157], v[190:193], v[78:81]
	v_mfma_f32_16x16x32_bf16 v[74:77], v[162:165], v[190:193], v[74:77]
	v_mfma_f32_16x16x32_bf16 v[46:49], v[154:157], v[198:201], v[46:49]
	v_mfma_f32_16x16x32_bf16 v[42:45], v[162:165], v[198:201], v[42:45]
	v_mfma_f32_16x16x32_bf16 v[30:33], v[154:157], v[206:209], v[30:33]
	v_mfma_f32_16x16x32_bf16 v[26:29], v[162:165], v[206:209], v[26:29]
	v_mfma_f32_16x16x32_bf16 v[14:17], v[154:157], v[214:217], v[14:17]
	v_mfma_f32_16x16x32_bf16 v[10:13], v[162:165], v[214:217], v[10:13]
	v_mfma_f32_16x16x32_bf16 v[70:73], v[170:173], v[186:189], v[70:73]
	v_mfma_f32_16x16x32_bf16 v[66:69], v[178:181], v[186:189], v[66:69]
	v_mfma_f32_16x16x32_bf16 v[38:41], v[170:173], v[194:197], v[38:41]
	v_mfma_f32_16x16x32_bf16 v[34:37], v[178:181], v[194:197], v[34:37]
	v_mfma_f32_16x16x32_bf16 v[22:25], v[170:173], v[202:205], v[22:25]
	v_mfma_f32_16x16x32_bf16 v[18:21], v[178:181], v[202:205], v[18:21]
	v_mfma_f32_16x16x32_bf16 v[6:9], v[170:173], v[210:213], v[6:9]
	v_mfma_f32_16x16x32_bf16 v[2:5], v[178:181], v[210:213], v[2:5]
	v_mfma_f32_16x16x32_bf16 v[70:73], v[174:177], v[190:193], v[70:73]
	v_mfma_f32_16x16x32_bf16 v[66:69], v[182:185], v[190:193], v[66:69]
	v_mfma_f32_16x16x32_bf16 v[38:41], v[174:177], v[198:201], v[38:41]
	v_mfma_f32_16x16x32_bf16 v[34:37], v[182:185], v[198:201], v[34:37]
	v_mfma_f32_16x16x32_bf16 v[22:25], v[174:177], v[206:209], v[22:25]
	v_mfma_f32_16x16x32_bf16 v[18:21], v[182:185], v[206:209], v[18:21]
	v_mfma_f32_16x16x32_bf16 v[6:9], v[174:177], v[214:217], v[6:9]
	v_mfma_f32_16x16x32_bf16 v[2:5], v[182:185], v[214:217], v[2:5]
	s_barrier
	ds_read_b128 v[150:153], v148
	ds_read_b128 v[154:157], v148 offset:1024
	ds_read_b128 v[158:161], v148 offset:2048
	ds_read_b128 v[162:165], v148 offset:3072
	ds_read_b128 v[170:173], v149
	ds_read_b128 v[174:177], v149 offset:1024
	ds_read_b128 v[178:181], v149 offset:2048
	ds_read_b128 v[182:185], v149 offset:3072
	s_add_u32 s16, s16, 0x30000
	s_addc_u32 s17, s17, 0
	s_mov_b32 m0, s31
	v_lshl_add_u64 v[224:225], s[16:17], 0, v[132:133]
	ds_read_b128 v[186:189], v147 offset:32768
	ds_read_b128 v[190:193], v147 offset:33792
	ds_read_b128 v[194:197], v147 offset:34816
	ds_read_b128 v[198:201], v147 offset:35840
	ds_read_b128 v[202:205], v147 offset:36864
	ds_read_b128 v[206:209], v147 offset:37888
	ds_read_b128 v[210:213], v147 offset:38912
	ds_read_b128 v[214:217], v147 offset:39936
	global_load_lds_dwordx4 v[224:225], off
	v_lshl_add_u64 v[224:225], s[16:17], 0, v[134:135]
	s_mov_b32 m0, s33
	s_nop 0
	global_load_lds_dwordx4 v[224:225], off
	s_waitcnt vmcnt(8)
	s_waitcnt lgkmcnt(0)
	s_barrier
	v_mfma_f32_16x16x32_bf16 v[50:53], v[150:153], v[186:189], v[50:53]
	v_mfma_f32_16x16x32_bf16 v[54:57], v[158:161], v[186:189], v[54:57]
	v_mfma_f32_16x16x32_bf16 v[82:85], v[150:153], v[194:197], v[82:85]
	v_mfma_f32_16x16x32_bf16 v[86:89], v[158:161], v[194:197], v[86:89]
	v_mfma_f32_16x16x32_bf16 v[114:117], v[150:153], v[202:205], v[114:117]
	v_mfma_f32_16x16x32_bf16 v[118:121], v[158:161], v[202:205], v[118:121]
	v_mfma_f32_16x16x32_bf16 v[110:113], v[150:153], v[210:213], v[110:113]
	v_mfma_f32_16x16x32_bf16 v[106:109], v[158:161], v[210:213], v[106:109]
	v_mfma_f32_16x16x32_bf16 v[50:53], v[154:157], v[190:193], v[50:53]
	v_mfma_f32_16x16x32_bf16 v[54:57], v[162:165], v[190:193], v[54:57]
	v_mfma_f32_16x16x32_bf16 v[82:85], v[154:157], v[198:201], v[82:85]
	v_mfma_f32_16x16x32_bf16 v[86:89], v[162:165], v[198:201], v[86:89]
	v_mfma_f32_16x16x32_bf16 v[114:117], v[154:157], v[206:209], v[114:117]
	v_mfma_f32_16x16x32_bf16 v[118:121], v[162:165], v[206:209], v[118:121]
	v_mfma_f32_16x16x32_bf16 v[110:113], v[154:157], v[214:217], v[110:113]
	v_mfma_f32_16x16x32_bf16 v[106:109], v[162:165], v[214:217], v[106:109]
	v_mfma_f32_16x16x32_bf16 v[58:61], v[170:173], v[186:189], v[58:61]
	v_mfma_f32_16x16x32_bf16 v[62:65], v[178:181], v[186:189], v[62:65]
	v_mfma_f32_16x16x32_bf16 v[90:93], v[170:173], v[194:197], v[90:93]
	v_mfma_f32_16x16x32_bf16 v[98:101], v[178:181], v[194:197], v[98:101]
	v_mfma_f32_16x16x32_bf16 v[122:125], v[170:173], v[202:205], v[122:125]
	v_mfma_f32_16x16x32_bf16 v[126:129], v[178:181], v[202:205], v[126:129]
	v_mfma_f32_16x16x32_bf16 v[102:105], v[170:173], v[210:213], v[102:105]
	v_mfma_f32_16x16x32_bf16 v[94:97], v[178:181], v[210:213], v[94:97]
	v_mfma_f32_16x16x32_bf16 v[58:61], v[174:177], v[190:193], v[58:61]
	v_mfma_f32_16x16x32_bf16 v[62:65], v[182:185], v[190:193], v[62:65]
	v_mfma_f32_16x16x32_bf16 v[90:93], v[174:177], v[198:201], v[90:93]
	v_mfma_f32_16x16x32_bf16 v[98:101], v[182:185], v[198:201], v[98:101]
	v_mfma_f32_16x16x32_bf16 v[122:125], v[174:177], v[206:209], v[122:125]
	v_mfma_f32_16x16x32_bf16 v[126:129], v[182:185], v[206:209], v[126:129]
	v_mfma_f32_16x16x32_bf16 v[102:105], v[174:177], v[214:217], v[102:105]
	v_mfma_f32_16x16x32_bf16 v[94:97], v[182:185], v[214:217], v[94:97]
	s_barrier
	s_mov_b32 m0, s47
	v_lshl_add_u64 v[166:167], v[166:167], 0, s[8:9]
	s_add_u32 s14, s14, 0x30080
	ds_read_b128 v[186:189], v147 offset:49152
	ds_read_b128 v[190:193], v147 offset:50176
	ds_read_b128 v[194:197], v147 offset:51200
	ds_read_b128 v[198:201], v147 offset:52224
	ds_read_b128 v[202:205], v147 offset:53248
	ds_read_b128 v[206:209], v147 offset:54272
	ds_read_b128 v[210:213], v147 offset:55296
	ds_read_b128 v[214:217], v147 offset:56320
	global_load_lds_dwordx4 v[166:167], off
	v_lshl_add_u64 v[166:167], v[218:219], 0, s[8:9]
	s_mov_b32 m0, s48
	s_addc_u32 s15, s15, 0
	global_load_lds_dwordx4 v[166:167], off
	v_lshl_add_u64 v[166:167], s[14:15], 0, v[136:137]
	s_mov_b32 m0, s49
	s_nop 0
	global_load_lds_dwordx4 v[166:167], off
	v_lshl_add_u64 v[166:167], s[14:15], 0, v[140:141]
	s_mov_b32 m0, s50
	s_nop 0
	global_load_lds_dwordx4 v[166:167], off
	v_lshl_add_u64 v[166:167], v[220:221], 0, s[8:9]
	s_mov_b32 m0, s36
	s_nop 0
	global_load_lds_dwordx4 v[166:167], off
	v_lshl_add_u64 v[166:167], v[222:223], 0, s[8:9]
	s_mov_b32 m0, s37
	s_nop 0
	global_load_lds_dwordx4 v[166:167], off
	s_waitcnt vmcnt(8)
	s_waitcnt lgkmcnt(0)
	s_barrier
	v_mfma_f32_16x16x32_bf16 v[78:81], v[150:153], v[186:189], v[78:81]
	v_mfma_f32_16x16x32_bf16 v[74:77], v[158:161], v[186:189], v[74:77]
	v_mfma_f32_16x16x32_bf16 v[46:49], v[150:153], v[194:197], v[46:49]
	v_mfma_f32_16x16x32_bf16 v[42:45], v[158:161], v[194:197], v[42:45]
	v_mfma_f32_16x16x32_bf16 v[30:33], v[150:153], v[202:205], v[30:33]
	v_mfma_f32_16x16x32_bf16 v[26:29], v[158:161], v[202:205], v[26:29]
	v_mfma_f32_16x16x32_bf16 v[14:17], v[150:153], v[210:213], v[14:17]
	v_mfma_f32_16x16x32_bf16 v[10:13], v[158:161], v[210:213], v[10:13]
	v_mfma_f32_16x16x32_bf16 v[78:81], v[154:157], v[190:193], v[78:81]
	v_mfma_f32_16x16x32_bf16 v[74:77], v[162:165], v[190:193], v[74:77]
	v_mfma_f32_16x16x32_bf16 v[46:49], v[154:157], v[198:201], v[46:49]
	v_mfma_f32_16x16x32_bf16 v[42:45], v[162:165], v[198:201], v[42:45]
	v_mfma_f32_16x16x32_bf16 v[30:33], v[154:157], v[206:209], v[30:33]
	v_mfma_f32_16x16x32_bf16 v[26:29], v[162:165], v[206:209], v[26:29]
	v_mfma_f32_16x16x32_bf16 v[14:17], v[154:157], v[214:217], v[14:17]
	v_mfma_f32_16x16x32_bf16 v[10:13], v[162:165], v[214:217], v[10:13]
	v_mfma_f32_16x16x32_bf16 v[70:73], v[170:173], v[186:189], v[70:73]
	v_mfma_f32_16x16x32_bf16 v[66:69], v[178:181], v[186:189], v[66:69]
	v_mfma_f32_16x16x32_bf16 v[38:41], v[170:173], v[194:197], v[38:41]
	v_mfma_f32_16x16x32_bf16 v[34:37], v[178:181], v[194:197], v[34:37]
	v_mfma_f32_16x16x32_bf16 v[22:25], v[170:173], v[202:205], v[22:25]
	v_mfma_f32_16x16x32_bf16 v[18:21], v[178:181], v[202:205], v[18:21]
	v_mfma_f32_16x16x32_bf16 v[6:9], v[170:173], v[210:213], v[6:9]
	v_mfma_f32_16x16x32_bf16 v[2:5], v[178:181], v[210:213], v[2:5]
	v_mfma_f32_16x16x32_bf16 v[70:73], v[174:177], v[190:193], v[70:73]
	v_mfma_f32_16x16x32_bf16 v[66:69], v[182:185], v[190:193], v[66:69]
	v_mfma_f32_16x16x32_bf16 v[38:41], v[174:177], v[198:201], v[38:41]
	v_mfma_f32_16x16x32_bf16 v[34:37], v[182:185], v[198:201], v[34:37]
	v_mfma_f32_16x16x32_bf16 v[22:25], v[174:177], v[206:209], v[22:25]
	v_mfma_f32_16x16x32_bf16 v[18:21], v[182:185], v[206:209], v[18:21]
	v_mfma_f32_16x16x32_bf16 v[6:9], v[174:177], v[214:217], v[6:9]
	v_mfma_f32_16x16x32_bf16 v[2:5], v[182:185], v[214:217], v[2:5]
	s_barrier
	s_add_i32 s40, s40, 2
	s_add_u32 s12, s12, 0x100
	s_addc_u32 s13, s13, 0
	s_cmp_lt_u32 s40, 6
	s_cbranch_scc1 .LBB0_1687
	s_waitcnt vmcnt(0)
	s_cmpk_gt_u32 s28, 0xff
	s_cbranch_scc1 .LBB0_1690
	s_barrier

.LBB0_1786:
	v_add_u32_e32 v155, s48, v153
	ds_read_b128 v[156:159], v155
	ds_read_b128 v[160:163], v155 offset:1024
	ds_read_b128 v[164:167], v155 offset:2048
	ds_read_b128 v[168:171], v155 offset:3072
	v_add_u32_e32 v155, s49, v153
	s_add_u32 s28, s10, s38
	ds_read_b128 v[172:175], v155
	ds_read_b128 v[176:179], v155 offset:1024
	ds_read_b128 v[180:183], v155 offset:2048
	ds_read_b128 v[184:187], v155 offset:3072
	s_addc_u32 s29, s11, s39
	s_add_u32 s28, s28, 0x100
	s_addc_u32 s29, s29, 0
	s_add_u32 s54, s21, s38
	s_addc_u32 s55, s50, s39
	s_cmpk_eq_i32 s38, 0x700
	s_cselect_b32 s31, s17, s29
	s_cselect_b32 s30, s51, s28
	s_cselect_b32 s29, s15, s55
	s_cselect_b32 s28, s52, s54
	v_lshl_add_u64 v[220:221], v[148:149], 0, s[38:39]
	s_add_i32 m0, s1, 0xc000
	ds_read_b128 v[188:191], v154
	ds_read_b128 v[192:195], v154 offset:1024
	ds_read_b128 v[196:199], v154 offset:2048
	ds_read_b128 v[200:203], v154 offset:3072
	ds_read_b128 v[204:207], v154 offset:4096
	ds_read_b128 v[208:211], v154 offset:5120
	ds_read_b128 v[212:215], v154 offset:6144
	ds_read_b128 v[216:219], v154 offset:7168
	global_load_lds_dwordx4 v[220:221], off
	v_lshl_add_u64 v[220:221], v[150:151], 0, s[38:39]
	s_add_i32 m0, s1, 0xe000
	s_nop 0
	global_load_lds_dwordx4 v[220:221], off
	s_waitcnt vmcnt(8)
	s_waitcnt lgkmcnt(0)
	s_barrier
	v_mfma_f32_16x16x32_bf16 v[126:129], v[156:159], v[188:191], v[126:129]
	v_mfma_f32_16x16x32_bf16 v[122:125], v[164:167], v[188:191], v[122:125]
	v_mfma_f32_16x16x32_bf16 v[110:113], v[156:159], v[196:199], v[110:113]
	v_mfma_f32_16x16x32_bf16 v[106:109], v[164:167], v[196:199], v[106:109]
	v_mfma_f32_16x16x32_bf16 v[94:97], v[156:159], v[204:207], v[94:97]
	v_mfma_f32_16x16x32_bf16 v[90:93], v[164:167], v[204:207], v[90:93]
	v_mfma_f32_16x16x32_bf16 v[78:81], v[156:159], v[212:215], v[78:81]
	v_mfma_f32_16x16x32_bf16 v[74:77], v[164:167], v[212:215], v[74:77]
	v_mfma_f32_16x16x32_bf16 v[126:129], v[160:163], v[192:195], v[126:129]
	v_mfma_f32_16x16x32_bf16 v[122:125], v[168:171], v[192:195], v[122:125]
	v_mfma_f32_16x16x32_bf16 v[110:113], v[160:163], v[200:203], v[110:113]
	v_mfma_f32_16x16x32_bf16 v[106:109], v[168:171], v[200:203], v[106:109]
	v_mfma_f32_16x16x32_bf16 v[94:97], v[160:163], v[208:211], v[94:97]
	v_mfma_f32_16x16x32_bf16 v[90:93], v[168:171], v[208:211], v[90:93]
	v_mfma_f32_16x16x32_bf16 v[78:81], v[160:163], v[216:219], v[78:81]
	v_mfma_f32_16x16x32_bf16 v[74:77], v[168:171], v[216:219], v[74:77]
	v_mfma_f32_16x16x32_bf16 v[118:121], v[172:175], v[188:191], v[118:121]
	v_mfma_f32_16x16x32_bf16 v[114:117], v[180:183], v[188:191], v[114:117]
	v_mfma_f32_16x16x32_bf16 v[102:105], v[172:175], v[196:199], v[102:105]
	v_mfma_f32_16x16x32_bf16 v[98:101], v[180:183], v[196:199], v[98:101]
	v_mfma_f32_16x16x32_bf16 v[86:89], v[172:175], v[204:207], v[86:89]
	v_mfma_f32_16x16x32_bf16 v[82:85], v[180:183], v[204:207], v[82:85]
	v_mfma_f32_16x16x32_bf16 v[70:73], v[172:175], v[212:215], v[70:73]
	v_mfma_f32_16x16x32_bf16 v[66:69], v[180:183], v[212:215], v[66:69]
	v_mfma_f32_16x16x32_bf16 v[118:121], v[176:179], v[192:195], v[118:121]
	v_mfma_f32_16x16x32_bf16 v[114:117], v[184:187], v[192:195], v[114:117]
	v_mfma_f32_16x16x32_bf16 v[102:105], v[176:179], v[200:203], v[102:105]
	v_mfma_f32_16x16x32_bf16 v[98:101], v[184:187], v[200:203], v[98:101]
	v_mfma_f32_16x16x32_bf16 v[86:89], v[176:179], v[208:211], v[86:89]
	v_mfma_f32_16x16x32_bf16 v[82:85], v[184:187], v[208:211], v[82:85]
	v_mfma_f32_16x16x32_bf16 v[70:73], v[176:179], v[216:219], v[70:73]
	v_mfma_f32_16x16x32_bf16 v[66:69], v[184:187], v[216:219], v[66:69]
	s_barrier
	s_add_i32 s54, s48, s41
	s_mov_b32 m0, s54
	ds_read_b128 v[188:191], v154 offset:16384
	ds_read_b128 v[192:195], v154 offset:17408
	ds_read_b128 v[196:199], v154 offset:18432
	ds_read_b128 v[200:203], v154 offset:19456
	ds_read_b128 v[204:207], v154 offset:20480
	ds_read_b128 v[208:211], v154 offset:21504
	ds_read_b128 v[212:215], v154 offset:22528
	ds_read_b128 v[216:219], v154 offset:23552
	global_load_lds_dwordx4 v132, s[28:29]
	s_add_i32 m0, s54, 0x2000
	s_add_u32 s54, s28, 0x40000
	s_addc_u32 s55, s29, 0
	s_add_i32 s56, s49, s41
	global_load_lds_dwordx4 v136, s[28:29]
	s_mov_b32 m0, s56
	s_nop 0
	global_load_lds_dwordx4 v132, s[54:55]
	s_add_i32 m0, s56, 0x2000
	s_nop 0
	global_load_lds_dwordx4 v136, s[54:55]
	s_mov_b32 m0, s1
	s_nop 0
	global_load_lds_dwordx4 v130, s[30:31]
	s_mov_b32 m0, s42
	s_nop 0
	global_load_lds_dwordx4 v134, s[30:31]
	s_waitcnt vmcnt(8)
	s_waitcnt lgkmcnt(0)
	s_barrier
	v_mfma_f32_16x16x32_bf16 v[62:65], v[156:159], v[188:191], v[62:65]
	v_mfma_f32_16x16x32_bf16 v[58:61], v[164:167], v[188:191], v[58:61]
	v_mfma_f32_16x16x32_bf16 v[46:49], v[156:159], v[196:199], v[46:49]
	v_mfma_f32_16x16x32_bf16 v[42:45], v[164:167], v[196:199], v[42:45]
	v_mfma_f32_16x16x32_bf16 v[30:33], v[156:159], v[204:207], v[30:33]
	v_mfma_f32_16x16x32_bf16 v[26:29], v[164:167], v[204:207], v[26:29]
	v_mfma_f32_16x16x32_bf16 v[14:17], v[156:159], v[212:215], v[14:17]
	v_mfma_f32_16x16x32_bf16 v[10:13], v[164:167], v[212:215], v[10:13]
	v_mfma_f32_16x16x32_bf16 v[62:65], v[160:163], v[192:195], v[62:65]
	v_mfma_f32_16x16x32_bf16 v[58:61], v[168:171], v[192:195], v[58:61]
	v_mfma_f32_16x16x32_bf16 v[46:49], v[160:163], v[200:203], v[46:49]
	v_mfma_f32_16x16x32_bf16 v[42:45], v[168:171], v[200:203], v[42:45]
	v_mfma_f32_16x16x32_bf16 v[30:33], v[160:163], v[208:211], v[30:33]
	v_mfma_f32_16x16x32_bf16 v[26:29], v[168:171], v[208:211], v[26:29]
	v_mfma_f32_16x16x32_bf16 v[14:17], v[160:163], v[216:219], v[14:17]
	v_mfma_f32_16x16x32_bf16 v[10:13], v[168:171], v[216:219], v[10:13]
	v_mfma_f32_16x16x32_bf16 v[54:57], v[172:175], v[188:191], v[54:57]
	v_mfma_f32_16x16x32_bf16 v[50:53], v[180:183], v[188:191], v[50:53]
	v_mfma_f32_16x16x32_bf16 v[38:41], v[172:175], v[196:199], v[38:41]
	v_mfma_f32_16x16x32_bf16 v[34:37], v[180:183], v[196:199], v[34:37]
	v_mfma_f32_16x16x32_bf16 v[22:25], v[172:175], v[204:207], v[22:25]
	v_mfma_f32_16x16x32_bf16 v[18:21], v[180:183], v[204:207], v[18:21]
	v_mfma_f32_16x16x32_bf16 v[6:9], v[172:175], v[212:215], v[6:9]
	v_mfma_f32_16x16x32_bf16 v[2:5], v[180:183], v[212:215], v[2:5]
	v_mfma_f32_16x16x32_bf16 v[54:57], v[176:179], v[192:195], v[54:57]
	v_mfma_f32_16x16x32_bf16 v[50:53], v[184:187], v[192:195], v[50:53]
	v_mfma_f32_16x16x32_bf16 v[38:41], v[176:179], v[200:203], v[38:41]
	v_mfma_f32_16x16x32_bf16 v[34:37], v[184:187], v[200:203], v[34:37]
	v_mfma_f32_16x16x32_bf16 v[22:25], v[176:179], v[208:211], v[22:25]
	v_mfma_f32_16x16x32_bf16 v[18:21], v[184:187], v[208:211], v[18:21]
	v_mfma_f32_16x16x32_bf16 v[6:9], v[176:179], v[216:219], v[6:9]
	v_mfma_f32_16x16x32_bf16 v[2:5], v[184:187], v[216:219], v[2:5]
	s_barrier
	s_add_i32 s54, 0, 0x18000
	v_add_u32_e32 v155, s54, v153
	s_add_i32 s55, 0, 0x1c000
	ds_read_b128 v[156:159], v155
	ds_read_b128 v[160:163], v155 offset:1024
	ds_read_b128 v[164:167], v155 offset:2048
	ds_read_b128 v[168:171], v155 offset:3072
	v_add_u32_e32 v155, s55, v153
	ds_read_b128 v[172:175], v155
	ds_read_b128 v[176:179], v155 offset:1024
	ds_read_b128 v[180:183], v155 offset:2048
	ds_read_b128 v[184:187], v155 offset:3072
	s_add_u32 s98, s30, 0x40000
	s_addc_u32 s99, s31, 0
	s_mov_b32 m0, s43
	ds_read_b128 v[188:191], v154 offset:32768
	ds_read_b128 v[192:195], v154 offset:33792
	ds_read_b128 v[196:199], v154 offset:34816
	ds_read_b128 v[200:203], v154 offset:35840
	ds_read_b128 v[204:207], v154 offset:36864
	ds_read_b128 v[208:211], v154 offset:37888
	ds_read_b128 v[212:215], v154 offset:38912
	ds_read_b128 v[216:219], v154 offset:39936
	global_load_lds_dwordx4 v130, s[98:99]
	s_mov_b32 m0, s44
	s_nop 0
	global_load_lds_dwordx4 v134, s[98:99]
	s_waitcnt vmcnt(8)
	s_waitcnt lgkmcnt(0)
	s_barrier
	v_mfma_f32_16x16x32_bf16 v[126:129], v[156:159], v[188:191], v[126:129]
	v_mfma_f32_16x16x32_bf16 v[122:125], v[164:167], v[188:191], v[122:125]
	v_mfma_f32_16x16x32_bf16 v[110:113], v[156:159], v[196:199], v[110:113]
	v_mfma_f32_16x16x32_bf16 v[106:109], v[164:167], v[196:199], v[106:109]
	v_mfma_f32_16x16x32_bf16 v[94:97], v[156:159], v[204:207], v[94:97]
	v_mfma_f32_16x16x32_bf16 v[90:93], v[164:167], v[204:207], v[90:93]
	v_mfma_f32_16x16x32_bf16 v[78:81], v[156:159], v[212:215], v[78:81]
	v_mfma_f32_16x16x32_bf16 v[74:77], v[164:167], v[212:215], v[74:77]
	v_mfma_f32_16x16x32_bf16 v[126:129], v[160:163], v[192:195], v[126:129]
	v_mfma_f32_16x16x32_bf16 v[122:125], v[168:171], v[192:195], v[122:125]
	v_mfma_f32_16x16x32_bf16 v[110:113], v[160:163], v[200:203], v[110:113]
	v_mfma_f32_16x16x32_bf16 v[106:109], v[168:171], v[200:203], v[106:109]
	v_mfma_f32_16x16x32_bf16 v[94:97], v[160:163], v[208:211], v[94:97]
	v_mfma_f32_16x16x32_bf16 v[90:93], v[168:171], v[208:211], v[90:93]
	v_mfma_f32_16x16x32_bf16 v[78:81], v[160:163], v[216:219], v[78:81]
	v_mfma_f32_16x16x32_bf16 v[74:77], v[168:171], v[216:219], v[74:77]
	v_mfma_f32_16x16x32_bf16 v[118:121], v[172:175], v[188:191], v[118:121]
	v_mfma_f32_16x16x32_bf16 v[114:117], v[180:183], v[188:191], v[114:117]
	v_mfma_f32_16x16x32_bf16 v[102:105], v[172:175], v[196:199], v[102:105]
	v_mfma_f32_16x16x32_bf16 v[98:101], v[180:183], v[196:199], v[98:101]
	v_mfma_f32_16x16x32_bf16 v[86:89], v[172:175], v[204:207], v[86:89]
	v_mfma_f32_16x16x32_bf16 v[82:85], v[180:183], v[204:207], v[82:85]
	v_mfma_f32_16x16x32_bf16 v[70:73], v[172:175], v[212:215], v[70:73]
	v_mfma_f32_16x16x32_bf16 v[66:69], v[180:183], v[212:215], v[66:69]
	v_mfma_f32_16x16x32_bf16 v[118:121], v[176:179], v[192:195], v[118:121]
	v_mfma_f32_16x16x32_bf16 v[114:117], v[184:187], v[192:195], v[114:117]
	v_mfma_f32_16x16x32_bf16 v[102:105], v[176:179], v[200:203], v[102:105]
	v_mfma_f32_16x16x32_bf16 v[98:101], v[184:187], v[200:203], v[98:101]
	v_mfma_f32_16x16x32_bf16 v[86:89], v[176:179], v[208:211], v[86:89]
	v_mfma_f32_16x16x32_bf16 v[82:85], v[184:187], v[208:211], v[82:85]
	v_mfma_f32_16x16x32_bf16 v[70:73], v[176:179], v[216:219], v[70:73]
	v_mfma_f32_16x16x32_bf16 v[66:69], v[184:187], v[216:219], v[66:69]
	s_barrier
	s_add_i32 s98, s54, s41
	s_add_i32 m0, s98, 0xffffff80
	ds_read_b128 v[188:191], v154 offset:49152
	ds_read_b128 v[192:195], v154 offset:50176
	ds_read_b128 v[196:199], v154 offset:51200
	ds_read_b128 v[200:203], v154 offset:52224
	ds_read_b128 v[204:207], v154 offset:53248
	ds_read_b128 v[208:211], v154 offset:54272
	ds_read_b128 v[212:215], v154 offset:55296
	ds_read_b128 v[216:219], v154 offset:56320
	global_load_lds_dwordx4 v132, s[28:29] offset:128
	s_add_i32 m0, s98, 0x1f80
	s_add_i32 s98, s55, s41
	global_load_lds_dwordx4 v136, s[28:29] offset:128
	s_add_u32 s28, s28, 0x40080
	s_addc_u32 s29, s29, 0
	s_mov_b32 m0, s98
	s_nop 0
	global_load_lds_dwordx4 v132, s[28:29]
	s_add_i32 m0, s98, 0x2000
	s_nop 0
	global_load_lds_dwordx4 v136, s[28:29]
	s_add_i32 m0, s46, 0xffffff80
	s_nop 0
	global_load_lds_dwordx4 v130, s[30:31] offset:128
	s_add_i32 m0, s47, 0xffffff80
	s_nop 0
	global_load_lds_dwordx4 v134, s[30:31] offset:128
	s_waitcnt vmcnt(8)
	s_waitcnt lgkmcnt(0)
	s_barrier
	v_mfma_f32_16x16x32_bf16 v[62:65], v[156:159], v[188:191], v[62:65]
	v_mfma_f32_16x16x32_bf16 v[58:61], v[164:167], v[188:191], v[58:61]
	v_mfma_f32_16x16x32_bf16 v[46:49], v[156:159], v[196:199], v[46:49]
	v_mfma_f32_16x16x32_bf16 v[42:45], v[164:167], v[196:199], v[42:45]
	v_mfma_f32_16x16x32_bf16 v[30:33], v[156:159], v[204:207], v[30:33]
	v_mfma_f32_16x16x32_bf16 v[26:29], v[164:167], v[204:207], v[26:29]
	v_mfma_f32_16x16x32_bf16 v[14:17], v[156:159], v[212:215], v[14:17]
	v_mfma_f32_16x16x32_bf16 v[10:13], v[164:167], v[212:215], v[10:13]
	v_mfma_f32_16x16x32_bf16 v[62:65], v[160:163], v[192:195], v[62:65]
	v_mfma_f32_16x16x32_bf16 v[58:61], v[168:171], v[192:195], v[58:61]
	v_mfma_f32_16x16x32_bf16 v[46:49], v[160:163], v[200:203], v[46:49]
	v_mfma_f32_16x16x32_bf16 v[42:45], v[168:171], v[200:203], v[42:45]
	v_mfma_f32_16x16x32_bf16 v[30:33], v[160:163], v[208:211], v[30:33]
	v_mfma_f32_16x16x32_bf16 v[26:29], v[168:171], v[208:211], v[26:29]
	v_mfma_f32_16x16x32_bf16 v[14:17], v[160:163], v[216:219], v[14:17]
	v_mfma_f32_16x16x32_bf16 v[10:13], v[168:171], v[216:219], v[10:13]
	v_mfma_f32_16x16x32_bf16 v[54:57], v[172:175], v[188:191], v[54:57]
	v_mfma_f32_16x16x32_bf16 v[50:53], v[180:183], v[188:191], v[50:53]
	v_mfma_f32_16x16x32_bf16 v[38:41], v[172:175], v[196:199], v[38:41]
	v_mfma_f32_16x16x32_bf16 v[34:37], v[180:183], v[196:199], v[34:37]
	v_mfma_f32_16x16x32_bf16 v[22:25], v[172:175], v[204:207], v[22:25]
	v_mfma_f32_16x16x32_bf16 v[18:21], v[180:183], v[204:207], v[18:21]
	v_mfma_f32_16x16x32_bf16 v[6:9], v[172:175], v[212:215], v[6:9]
	v_mfma_f32_16x16x32_bf16 v[2:5], v[180:183], v[212:215], v[2:5]
	v_mfma_f32_16x16x32_bf16 v[54:57], v[176:179], v[192:195], v[54:57]
	v_mfma_f32_16x16x32_bf16 v[50:53], v[184:187], v[192:195], v[50:53]
	v_mfma_f32_16x16x32_bf16 v[38:41], v[176:179], v[200:203], v[38:41]
	v_mfma_f32_16x16x32_bf16 v[34:37], v[184:187], v[200:203], v[34:37]
	v_mfma_f32_16x16x32_bf16 v[22:25], v[176:179], v[208:211], v[22:25]
	v_mfma_f32_16x16x32_bf16 v[18:21], v[184:187], v[208:211], v[18:21]
	v_mfma_f32_16x16x32_bf16 v[6:9], v[176:179], v[216:219], v[6:9]
	v_mfma_f32_16x16x32_bf16 v[2:5], v[184:187], v[216:219], v[2:5]
	s_barrier
	s_add_i32 s53, s53, 2
	s_add_u32 s38, s38, 0x100
	s_addc_u32 s39, s39, 0
	s_cmp_gt_u32 s53, 13
	s_cbranch_scc0 .LBB0_1786
	s_add_u32 s28, s21, 0xffffff00
	s_addc_u32 s29, s50, -1
	s_andn2_b64 vcc, exec, s[4:5]
	s_cbranch_vccnz .LBB0_1789
	v_mov_b32_e32 v2, 0
	v_mov_b32_e32 v3, 0
	v_mov_b64_e32 v[4:5], v[2:3]
	v_mov_b64_e32 v[6:7], v[2:3]
	v_mov_b64_e32 v[8:9], v[2:3]
	v_mov_b64_e32 v[10:11], v[2:3]
	v_mov_b64_e32 v[12:13], v[2:3]
	v_mov_b64_e32 v[14:15], v[2:3]
	v_mov_b64_e32 v[16:17], v[2:3]
	v_mov_b64_e32 v[18:19], v[2:3]
	v_mov_b64_e32 v[20:21], v[2:3]
	v_mov_b64_e32 v[22:23], v[2:3]
	v_mov_b64_e32 v[24:25], v[2:3]
	v_mov_b64_e32 v[26:27], v[2:3]
	v_mov_b64_e32 v[28:29], v[2:3]
	v_mov_b64_e32 v[30:31], v[2:3]
	v_mov_b64_e32 v[32:33], v[2:3]
	v_mov_b64_e32 v[34:35], v[2:3]
	v_mov_b64_e32 v[36:37], v[2:3]
	v_mov_b64_e32 v[38:39], v[2:3]
	v_mov_b64_e32 v[40:41], v[2:3]
	v_mov_b64_e32 v[42:43], v[2:3]
	v_mov_b64_e32 v[44:45], v[2:3]
	v_mov_b64_e32 v[46:47], v[2:3]
	v_mov_b64_e32 v[48:49], v[2:3]
	v_mov_b64_e32 v[50:51], v[2:3]
	v_mov_b64_e32 v[52:53], v[2:3]
	v_mov_b64_e32 v[54:55], v[2:3]
	v_mov_b64_e32 v[56:57], v[2:3]
	v_mov_b64_e32 v[58:59], v[2:3]
	v_mov_b64_e32 v[60:61], v[2:3]
	v_mov_b64_e32 v[62:63], v[2:3]
	v_mov_b64_e32 v[64:65], v[2:3]
	v_mov_b64_e32 v[66:67], v[2:3]
	v_mov_b64_e32 v[68:69], v[2:3]
	v_mov_b64_e32 v[70:71], v[2:3]
	v_mov_b64_e32 v[72:73], v[2:3]
	v_mov_b64_e32 v[74:75], v[2:3]
	v_mov_b64_e32 v[76:77], v[2:3]
	v_mov_b64_e32 v[78:79], v[2:3]
	v_mov_b64_e32 v[80:81], v[2:3]
	v_mov_b64_e32 v[82:83], v[2:3]
	v_mov_b64_e32 v[84:85], v[2:3]
	v_mov_b64_e32 v[86:87], v[2:3]
	v_mov_b64_e32 v[88:89], v[2:3]
	v_mov_b64_e32 v[90:91], v[2:3]
	v_mov_b64_e32 v[92:93], v[2:3]
	v_mov_b64_e32 v[94:95], v[2:3]
	v_mov_b64_e32 v[96:97], v[2:3]
	v_mov_b64_e32 v[98:99], v[2:3]
	v_mov_b64_e32 v[100:101], v[2:3]
	v_mov_b64_e32 v[102:103], v[2:3]
	v_mov_b64_e32 v[104:105], v[2:3]
	v_mov_b64_e32 v[106:107], v[2:3]
	v_mov_b64_e32 v[108:109], v[2:3]
	v_mov_b64_e32 v[110:111], v[2:3]
	v_mov_b64_e32 v[112:113], v[2:3]
	v_mov_b64_e32 v[114:115], v[2:3]
	v_mov_b64_e32 v[116:117], v[2:3]
	v_mov_b64_e32 v[118:119], v[2:3]
	v_mov_b64_e32 v[120:121], v[2:3]
	v_mov_b64_e32 v[122:123], v[2:3]
	v_mov_b64_e32 v[124:125], v[2:3]
	v_mov_b64_e32 v[126:127], v[2:3]
	v_mov_b64_e32 v[128:129], v[2:3]
	s_mov_b32 s6, s14
	s_mov_b32 s0, s16
	s_mov_b64 s[10:11], s[36:37]
	s_mov_b32 s45, s20
	s_andn2_b64 vcc, exec, s[2:3]
	s_cbranch_vccnz .LBB0_1790
	s_branch .LBB0_1791

.LBB0_1905:
	ds_read_b128 v[148:151], v165
	ds_read_b128 v[152:155], v165 offset:1024
	ds_read_b128 v[156:159], v165 offset:2048
	ds_read_b128 v[160:163], v165 offset:3072
	ds_read_b128 v[170:173], v166
	ds_read_b128 v[174:177], v166 offset:1024
	ds_read_b128 v[178:181], v166 offset:2048
	ds_read_b128 v[182:185], v166 offset:3072
	s_add_u32 s28, s58, 0xfffc0080
	s_addc_u32 s29, s59, -1
	s_cmp_eq_u32 s74, 12
	s_cselect_b32 s31, s51, s29
	s_cselect_b32 s30, s60, s28
	s_cselect_b32 s29, s49, s73
	s_cselect_b32 s28, s61, s72
	s_add_i32 m0, s33, 0xc000
	ds_read_b128 v[186:189], v167
	ds_read_b128 v[190:193], v167 offset:1024
	ds_read_b128 v[194:197], v167 offset:2048
	ds_read_b128 v[198:201], v167 offset:3072
	ds_read_b128 v[202:205], v167 offset:4096
	ds_read_b128 v[206:209], v167 offset:5120
	ds_read_b128 v[210:213], v167 offset:6144
	ds_read_b128 v[214:217], v167 offset:7168
	global_load_lds_dwordx4 v140, s[58:59]
	s_add_i32 m0, s33, 0xe000
	s_nop 0
	global_load_lds_dwordx4 v142, s[58:59]
	s_waitcnt vmcnt(8)
	s_waitcnt lgkmcnt(0)
	s_barrier
	v_mfma_f32_16x16x32_bf16 v[126:129], v[148:151], v[186:189], v[126:129]
	v_mfma_f32_16x16x32_bf16 v[118:121], v[156:159], v[186:189], v[118:121]
	v_mfma_f32_16x16x32_bf16 v[110:113], v[148:151], v[194:197], v[110:113]
	v_mfma_f32_16x16x32_bf16 v[102:105], v[156:159], v[194:197], v[102:105]
	v_mfma_f32_16x16x32_bf16 v[94:97], v[148:151], v[202:205], v[94:97]
	v_mfma_f32_16x16x32_bf16 v[86:89], v[156:159], v[202:205], v[86:89]
	v_mfma_f32_16x16x32_bf16 v[78:81], v[148:151], v[210:213], v[78:81]
	v_mfma_f32_16x16x32_bf16 v[70:73], v[156:159], v[210:213], v[70:73]
	v_mfma_f32_16x16x32_bf16 v[126:129], v[152:155], v[190:193], v[126:129]
	v_mfma_f32_16x16x32_bf16 v[118:121], v[160:163], v[190:193], v[118:121]
	v_mfma_f32_16x16x32_bf16 v[110:113], v[152:155], v[198:201], v[110:113]
	v_mfma_f32_16x16x32_bf16 v[102:105], v[160:163], v[198:201], v[102:105]
	v_mfma_f32_16x16x32_bf16 v[94:97], v[152:155], v[206:209], v[94:97]
	v_mfma_f32_16x16x32_bf16 v[86:89], v[160:163], v[206:209], v[86:89]
	v_mfma_f32_16x16x32_bf16 v[78:81], v[152:155], v[214:217], v[78:81]
	v_mfma_f32_16x16x32_bf16 v[70:73], v[160:163], v[214:217], v[70:73]
	v_mfma_f32_16x16x32_bf16 v[122:125], v[170:173], v[186:189], v[122:125]
	v_mfma_f32_16x16x32_bf16 v[114:117], v[178:181], v[186:189], v[114:117]
	v_mfma_f32_16x16x32_bf16 v[106:109], v[170:173], v[194:197], v[106:109]
	v_mfma_f32_16x16x32_bf16 v[98:101], v[178:181], v[194:197], v[98:101]
	v_mfma_f32_16x16x32_bf16 v[90:93], v[170:173], v[202:205], v[90:93]
	v_mfma_f32_16x16x32_bf16 v[82:85], v[178:181], v[202:205], v[82:85]
	v_mfma_f32_16x16x32_bf16 v[74:77], v[170:173], v[210:213], v[74:77]
	v_mfma_f32_16x16x32_bf16 v[66:69], v[178:181], v[210:213], v[66:69]
	v_mfma_f32_16x16x32_bf16 v[122:125], v[174:177], v[190:193], v[122:125]
	v_mfma_f32_16x16x32_bf16 v[114:117], v[182:185], v[190:193], v[114:117]
	v_mfma_f32_16x16x32_bf16 v[106:109], v[174:177], v[198:201], v[106:109]
	v_mfma_f32_16x16x32_bf16 v[98:101], v[182:185], v[198:201], v[98:101]
	v_mfma_f32_16x16x32_bf16 v[90:93], v[174:177], v[206:209], v[90:93]
	v_mfma_f32_16x16x32_bf16 v[82:85], v[182:185], v[206:209], v[82:85]
	v_mfma_f32_16x16x32_bf16 v[74:77], v[174:177], v[214:217], v[74:77]
	v_mfma_f32_16x16x32_bf16 v[66:69], v[182:185], v[214:217], v[66:69]
	s_barrier
	s_add_i32 s75, s67, s23
	s_mov_b32 m0, s75
	ds_read_b128 v[186:189], v167 offset:16384
	ds_read_b128 v[190:193], v167 offset:17408
	ds_read_b128 v[194:197], v167 offset:18432
	ds_read_b128 v[198:201], v167 offset:19456
	ds_read_b128 v[202:205], v167 offset:20480
	ds_read_b128 v[206:209], v167 offset:21504
	ds_read_b128 v[210:213], v167 offset:22528
	ds_read_b128 v[214:217], v167 offset:23552
	global_load_lds_dwordx4 v132, s[28:29]
	s_add_i32 m0, s75, 0x2000
	s_add_u32 s76, s28, 0x40000
	s_addc_u32 s77, s29, 0
	s_add_i32 s75, s68, s23
	global_load_lds_dwordx4 v136, s[28:29]
	s_mov_b32 m0, s75
	s_nop 0
	global_load_lds_dwordx4 v132, s[76:77]
	s_add_i32 m0, s75, 0x2000
	s_nop 0
	global_load_lds_dwordx4 v136, s[76:77]
	s_mov_b32 m0, s33
	s_nop 0
	global_load_lds_dwordx4 v130, s[30:31]
	s_mov_b32 m0, s34
	s_nop 0
	global_load_lds_dwordx4 v134, s[30:31]
	s_waitcnt vmcnt(8)
	s_waitcnt lgkmcnt(0)
	s_barrier
	v_mfma_f32_16x16x32_bf16 v[62:65], v[148:151], v[186:189], v[62:65]
	v_mfma_f32_16x16x32_bf16 v[54:57], v[156:159], v[186:189], v[54:57]
	v_mfma_f32_16x16x32_bf16 v[46:49], v[148:151], v[194:197], v[46:49]
	v_mfma_f32_16x16x32_bf16 v[38:41], v[156:159], v[194:197], v[38:41]
	v_mfma_f32_16x16x32_bf16 v[30:33], v[148:151], v[202:205], v[30:33]
	v_mfma_f32_16x16x32_bf16 v[22:25], v[156:159], v[202:205], v[22:25]
	v_mfma_f32_16x16x32_bf16 v[14:17], v[148:151], v[210:213], v[14:17]
	v_mfma_f32_16x16x32_bf16 v[6:9], v[156:159], v[210:213], v[6:9]
	v_mfma_f32_16x16x32_bf16 v[62:65], v[152:155], v[190:193], v[62:65]
	v_mfma_f32_16x16x32_bf16 v[54:57], v[160:163], v[190:193], v[54:57]
	v_mfma_f32_16x16x32_bf16 v[46:49], v[152:155], v[198:201], v[46:49]
	v_mfma_f32_16x16x32_bf16 v[38:41], v[160:163], v[198:201], v[38:41]
	v_mfma_f32_16x16x32_bf16 v[30:33], v[152:155], v[206:209], v[30:33]
	v_mfma_f32_16x16x32_bf16 v[22:25], v[160:163], v[206:209], v[22:25]
	v_mfma_f32_16x16x32_bf16 v[14:17], v[152:155], v[214:217], v[14:17]
	v_mfma_f32_16x16x32_bf16 v[6:9], v[160:163], v[214:217], v[6:9]
	v_mfma_f32_16x16x32_bf16 v[58:61], v[170:173], v[186:189], v[58:61]
	v_mfma_f32_16x16x32_bf16 v[50:53], v[178:181], v[186:189], v[50:53]
	v_mfma_f32_16x16x32_bf16 v[42:45], v[170:173], v[194:197], v[42:45]
	v_mfma_f32_16x16x32_bf16 v[34:37], v[178:181], v[194:197], v[34:37]
	v_mfma_f32_16x16x32_bf16 v[26:29], v[170:173], v[202:205], v[26:29]
	v_mfma_f32_16x16x32_bf16 v[18:21], v[178:181], v[202:205], v[18:21]
	v_mfma_f32_16x16x32_bf16 v[10:13], v[170:173], v[210:213], v[10:13]
	v_mfma_f32_16x16x32_bf16 v[2:5], v[178:181], v[210:213], v[2:5]
	v_mfma_f32_16x16x32_bf16 v[58:61], v[174:177], v[190:193], v[58:61]
	v_mfma_f32_16x16x32_bf16 v[50:53], v[182:185], v[190:193], v[50:53]
	v_mfma_f32_16x16x32_bf16 v[42:45], v[174:177], v[198:201], v[42:45]
	v_mfma_f32_16x16x32_bf16 v[34:37], v[182:185], v[198:201], v[34:37]
	v_mfma_f32_16x16x32_bf16 v[26:29], v[174:177], v[206:209], v[26:29]
	v_mfma_f32_16x16x32_bf16 v[18:21], v[182:185], v[206:209], v[18:21]
	v_mfma_f32_16x16x32_bf16 v[10:13], v[174:177], v[214:217], v[10:13]
	v_mfma_f32_16x16x32_bf16 v[2:5], v[182:185], v[214:217], v[2:5]
	s_barrier
	s_add_i32 s75, 0, 0x18000
	s_add_i32 s76, 0, 0x1c000
	v_add_u32_e32 v160, s75, v139
	v_add_u32_e32 v169, s76, v139
	ds_read_b128 v[148:151], v160
	ds_read_b128 v[152:155], v160 offset:1024
	ds_read_b128 v[156:159], v160 offset:2048
	ds_read_b128 v[160:163], v160 offset:3072
	ds_read_b128 v[170:173], v169
	ds_read_b128 v[174:177], v169 offset:1024
	ds_read_b128 v[178:181], v169 offset:2048
	ds_read_b128 v[182:185], v169 offset:3072
	s_add_u32 s98, s30, 0x40000
	s_addc_u32 s99, s31, 0
	s_mov_b32 m0, s35
	ds_read_b128 v[186:189], v167 offset:32768
	ds_read_b128 v[190:193], v167 offset:33792
	ds_read_b128 v[194:197], v167 offset:34816
	ds_read_b128 v[198:201], v167 offset:35840
	ds_read_b128 v[202:205], v167 offset:36864
	ds_read_b128 v[206:209], v167 offset:37888
	ds_read_b128 v[210:213], v167 offset:38912
	ds_read_b128 v[214:217], v167 offset:39936
	global_load_lds_dwordx4 v130, s[98:99]
	s_mov_b32 m0, s57
	s_nop 0
	global_load_lds_dwordx4 v134, s[98:99]
	s_waitcnt vmcnt(8)
	s_waitcnt lgkmcnt(0)
	s_barrier
	v_mfma_f32_16x16x32_bf16 v[126:129], v[148:151], v[186:189], v[126:129]
	v_mfma_f32_16x16x32_bf16 v[118:121], v[156:159], v[186:189], v[118:121]
	v_mfma_f32_16x16x32_bf16 v[110:113], v[148:151], v[194:197], v[110:113]
	v_mfma_f32_16x16x32_bf16 v[102:105], v[156:159], v[194:197], v[102:105]
	v_mfma_f32_16x16x32_bf16 v[94:97], v[148:151], v[202:205], v[94:97]
	v_mfma_f32_16x16x32_bf16 v[86:89], v[156:159], v[202:205], v[86:89]
	v_mfma_f32_16x16x32_bf16 v[78:81], v[148:151], v[210:213], v[78:81]
	v_mfma_f32_16x16x32_bf16 v[70:73], v[156:159], v[210:213], v[70:73]
	v_mfma_f32_16x16x32_bf16 v[126:129], v[152:155], v[190:193], v[126:129]
	v_mfma_f32_16x16x32_bf16 v[118:121], v[160:163], v[190:193], v[118:121]
	v_mfma_f32_16x16x32_bf16 v[110:113], v[152:155], v[198:201], v[110:113]
	v_mfma_f32_16x16x32_bf16 v[102:105], v[160:163], v[198:201], v[102:105]
	v_mfma_f32_16x16x32_bf16 v[94:97], v[152:155], v[206:209], v[94:97]
	v_mfma_f32_16x16x32_bf16 v[86:89], v[160:163], v[206:209], v[86:89]
	v_mfma_f32_16x16x32_bf16 v[78:81], v[152:155], v[214:217], v[78:81]
	v_mfma_f32_16x16x32_bf16 v[70:73], v[160:163], v[214:217], v[70:73]
	v_mfma_f32_16x16x32_bf16 v[122:125], v[170:173], v[186:189], v[122:125]
	v_mfma_f32_16x16x32_bf16 v[114:117], v[178:181], v[186:189], v[114:117]
	v_mfma_f32_16x16x32_bf16 v[106:109], v[170:173], v[194:197], v[106:109]
	v_mfma_f32_16x16x32_bf16 v[98:101], v[178:181], v[194:197], v[98:101]
	v_mfma_f32_16x16x32_bf16 v[90:93], v[170:173], v[202:205], v[90:93]
	v_mfma_f32_16x16x32_bf16 v[82:85], v[178:181], v[202:205], v[82:85]
	v_mfma_f32_16x16x32_bf16 v[74:77], v[170:173], v[210:213], v[74:77]
	v_mfma_f32_16x16x32_bf16 v[66:69], v[178:181], v[210:213], v[66:69]
	v_mfma_f32_16x16x32_bf16 v[122:125], v[174:177], v[190:193], v[122:125]
	v_mfma_f32_16x16x32_bf16 v[114:117], v[182:185], v[190:193], v[114:117]
	v_mfma_f32_16x16x32_bf16 v[106:109], v[174:177], v[198:201], v[106:109]
	v_mfma_f32_16x16x32_bf16 v[98:101], v[182:185], v[198:201], v[98:101]
	v_mfma_f32_16x16x32_bf16 v[90:93], v[174:177], v[206:209], v[90:93]
	v_mfma_f32_16x16x32_bf16 v[82:85], v[182:185], v[206:209], v[82:85]
	v_mfma_f32_16x16x32_bf16 v[74:77], v[174:177], v[214:217], v[74:77]
	v_mfma_f32_16x16x32_bf16 v[66:69], v[182:185], v[214:217], v[66:69]
	s_barrier
	s_add_i32 s98, s75, s23
	s_add_i32 m0, s98, 0xffffff80
	ds_read_b128 v[186:189], v167 offset:49152
	ds_read_b128 v[190:193], v167 offset:50176
	ds_read_b128 v[194:197], v167 offset:51200
	ds_read_b128 v[198:201], v167 offset:52224
	ds_read_b128 v[202:205], v167 offset:53248
	ds_read_b128 v[206:209], v167 offset:54272
	ds_read_b128 v[210:213], v167 offset:55296
	ds_read_b128 v[214:217], v167 offset:56320
	global_load_lds_dwordx4 v132, s[28:29] offset:128
	s_add_i32 m0, s98, 0x1f80
	s_add_i32 s98, s76, s23
	global_load_lds_dwordx4 v136, s[28:29] offset:128
	s_add_u32 s28, s28, 0x40080
	s_addc_u32 s29, s29, 0
	s_mov_b32 m0, s98
	s_nop 0
	global_load_lds_dwordx4 v132, s[28:29]
	s_add_i32 m0, s98, 0x2000
	s_nop 0
	global_load_lds_dwordx4 v136, s[28:29]
	s_add_i32 m0, s62, 0xffffff80
	s_nop 0
	global_load_lds_dwordx4 v130, s[30:31] offset:128
	s_add_i32 m0, s63, 0xffffff80
	s_nop 0
	global_load_lds_dwordx4 v134, s[30:31] offset:128
	s_waitcnt vmcnt(8)
	s_waitcnt lgkmcnt(0)
	s_barrier
	v_mfma_f32_16x16x32_bf16 v[62:65], v[148:151], v[186:189], v[62:65]
	v_mfma_f32_16x16x32_bf16 v[54:57], v[156:159], v[186:189], v[54:57]
	v_mfma_f32_16x16x32_bf16 v[46:49], v[148:151], v[194:197], v[46:49]
	v_mfma_f32_16x16x32_bf16 v[38:41], v[156:159], v[194:197], v[38:41]
	v_mfma_f32_16x16x32_bf16 v[30:33], v[148:151], v[202:205], v[30:33]
	v_mfma_f32_16x16x32_bf16 v[22:25], v[156:159], v[202:205], v[22:25]
	v_mfma_f32_16x16x32_bf16 v[14:17], v[148:151], v[210:213], v[14:17]
	v_mfma_f32_16x16x32_bf16 v[6:9], v[156:159], v[210:213], v[6:9]
	v_mfma_f32_16x16x32_bf16 v[62:65], v[152:155], v[190:193], v[62:65]
	v_mfma_f32_16x16x32_bf16 v[54:57], v[160:163], v[190:193], v[54:57]
	v_mfma_f32_16x16x32_bf16 v[46:49], v[152:155], v[198:201], v[46:49]
	v_mfma_f32_16x16x32_bf16 v[38:41], v[160:163], v[198:201], v[38:41]
	v_mfma_f32_16x16x32_bf16 v[30:33], v[152:155], v[206:209], v[30:33]
	v_mfma_f32_16x16x32_bf16 v[22:25], v[160:163], v[206:209], v[22:25]
	v_mfma_f32_16x16x32_bf16 v[14:17], v[152:155], v[214:217], v[14:17]
	v_mfma_f32_16x16x32_bf16 v[6:9], v[160:163], v[214:217], v[6:9]
	v_mfma_f32_16x16x32_bf16 v[58:61], v[170:173], v[186:189], v[58:61]
	v_mfma_f32_16x16x32_bf16 v[50:53], v[178:181], v[186:189], v[50:53]
	v_mfma_f32_16x16x32_bf16 v[42:45], v[170:173], v[194:197], v[42:45]
	v_mfma_f32_16x16x32_bf16 v[34:37], v[178:181], v[194:197], v[34:37]
	v_mfma_f32_16x16x32_bf16 v[26:29], v[170:173], v[202:205], v[26:29]
	v_mfma_f32_16x16x32_bf16 v[18:21], v[178:181], v[202:205], v[18:21]
	v_mfma_f32_16x16x32_bf16 v[10:13], v[170:173], v[210:213], v[10:13]
	v_mfma_f32_16x16x32_bf16 v[2:5], v[178:181], v[210:213], v[2:5]
	v_mfma_f32_16x16x32_bf16 v[58:61], v[174:177], v[190:193], v[58:61]
	v_mfma_f32_16x16x32_bf16 v[50:53], v[182:185], v[190:193], v[50:53]
	v_mfma_f32_16x16x32_bf16 v[42:45], v[174:177], v[198:201], v[42:45]
	v_mfma_f32_16x16x32_bf16 v[34:37], v[182:185], v[198:201], v[34:37]
	v_mfma_f32_16x16x32_bf16 v[26:29], v[174:177], v[206:209], v[26:29]
	v_mfma_f32_16x16x32_bf16 v[18:21], v[182:185], v[206:209], v[18:21]
	v_mfma_f32_16x16x32_bf16 v[10:13], v[174:177], v[214:217], v[10:13]
	v_mfma_f32_16x16x32_bf16 v[2:5], v[182:185], v[214:217], v[2:5]
	s_barrier
	s_add_i32 s74, s74, 2
	s_add_u32 s58, s58, 0x100
	s_addc_u32 s59, s59, 0
	s_add_u32 s72, s72, 0x100
	s_addc_u32 s73, s73, 0
	s_cmp_gt_u32 s74, 13
	s_cbranch_scc0 .LBB0_1905
	s_and_b64 vcc, exec, s[42:43]
	s_cbranch_vccz .LBB0_1908
	s_barrier

.LBB0_2031:
	v_add_u32_e32 v155, s48, v153
	ds_read_b128 v[156:159], v155
	ds_read_b128 v[160:163], v155 offset:1024
	ds_read_b128 v[164:167], v155 offset:2048
	ds_read_b128 v[168:171], v155 offset:3072
	v_add_u32_e32 v155, s49, v153
	s_add_u32 s28, s12, s20
	ds_read_b128 v[172:175], v155
	ds_read_b128 v[176:179], v155 offset:1024
	ds_read_b128 v[180:183], v155 offset:2048
	ds_read_b128 v[184:187], v155 offset:3072
	s_addc_u32 s29, s13, s21
	s_add_u32 s28, s28, 0x100
	s_addc_u32 s29, s29, 0
	s_add_u32 s54, s17, s20
	s_addc_u32 s55, s52, s21
	s_cmpk_eq_i32 s20, 0x1500
	s_cselect_b32 s31, s19, s29
	s_cselect_b32 s30, s18, s28
	s_cselect_b32 s29, s1, s55
	s_cselect_b32 s28, s0, s54
	v_lshl_add_u64 v[220:221], v[148:149], 0, s[20:21]
	s_add_i32 m0, s41, 0xc000
	ds_read_b128 v[188:191], v154
	ds_read_b128 v[192:195], v154 offset:1024
	ds_read_b128 v[196:199], v154 offset:2048
	ds_read_b128 v[200:203], v154 offset:3072
	ds_read_b128 v[204:207], v154 offset:4096
	ds_read_b128 v[208:211], v154 offset:5120
	ds_read_b128 v[212:215], v154 offset:6144
	ds_read_b128 v[216:219], v154 offset:7168
	global_load_lds_dwordx4 v[220:221], off
	v_lshl_add_u64 v[220:221], v[150:151], 0, s[20:21]
	s_add_i32 m0, s41, 0xe000
	s_nop 0
	global_load_lds_dwordx4 v[220:221], off
	s_waitcnt vmcnt(8)
	s_waitcnt lgkmcnt(0)
	s_barrier
	v_mfma_f32_16x16x32_bf16 v[126:129], v[156:159], v[188:191], v[126:129]
	v_mfma_f32_16x16x32_bf16 v[122:125], v[164:167], v[188:191], v[122:125]
	v_mfma_f32_16x16x32_bf16 v[110:113], v[156:159], v[196:199], v[110:113]
	v_mfma_f32_16x16x32_bf16 v[106:109], v[164:167], v[196:199], v[106:109]
	v_mfma_f32_16x16x32_bf16 v[94:97], v[156:159], v[204:207], v[94:97]
	v_mfma_f32_16x16x32_bf16 v[90:93], v[164:167], v[204:207], v[90:93]
	v_mfma_f32_16x16x32_bf16 v[78:81], v[156:159], v[212:215], v[78:81]
	v_mfma_f32_16x16x32_bf16 v[74:77], v[164:167], v[212:215], v[74:77]
	v_mfma_f32_16x16x32_bf16 v[126:129], v[160:163], v[192:195], v[126:129]
	v_mfma_f32_16x16x32_bf16 v[122:125], v[168:171], v[192:195], v[122:125]
	v_mfma_f32_16x16x32_bf16 v[110:113], v[160:163], v[200:203], v[110:113]
	v_mfma_f32_16x16x32_bf16 v[106:109], v[168:171], v[200:203], v[106:109]
	v_mfma_f32_16x16x32_bf16 v[94:97], v[160:163], v[208:211], v[94:97]
	v_mfma_f32_16x16x32_bf16 v[90:93], v[168:171], v[208:211], v[90:93]
	v_mfma_f32_16x16x32_bf16 v[78:81], v[160:163], v[216:219], v[78:81]
	v_mfma_f32_16x16x32_bf16 v[74:77], v[168:171], v[216:219], v[74:77]
	v_mfma_f32_16x16x32_bf16 v[118:121], v[172:175], v[188:191], v[118:121]
	v_mfma_f32_16x16x32_bf16 v[114:117], v[180:183], v[188:191], v[114:117]
	v_mfma_f32_16x16x32_bf16 v[102:105], v[172:175], v[196:199], v[102:105]
	v_mfma_f32_16x16x32_bf16 v[98:101], v[180:183], v[196:199], v[98:101]
	v_mfma_f32_16x16x32_bf16 v[86:89], v[172:175], v[204:207], v[86:89]
	v_mfma_f32_16x16x32_bf16 v[82:85], v[180:183], v[204:207], v[82:85]
	v_mfma_f32_16x16x32_bf16 v[70:73], v[172:175], v[212:215], v[70:73]
	v_mfma_f32_16x16x32_bf16 v[66:69], v[180:183], v[212:215], v[66:69]
	v_mfma_f32_16x16x32_bf16 v[118:121], v[176:179], v[192:195], v[118:121]
	v_mfma_f32_16x16x32_bf16 v[114:117], v[184:187], v[192:195], v[114:117]
	v_mfma_f32_16x16x32_bf16 v[102:105], v[176:179], v[200:203], v[102:105]
	v_mfma_f32_16x16x32_bf16 v[98:101], v[184:187], v[200:203], v[98:101]
	v_mfma_f32_16x16x32_bf16 v[86:89], v[176:179], v[208:211], v[86:89]
	v_mfma_f32_16x16x32_bf16 v[82:85], v[184:187], v[208:211], v[82:85]
	v_mfma_f32_16x16x32_bf16 v[70:73], v[176:179], v[216:219], v[70:73]
	v_mfma_f32_16x16x32_bf16 v[66:69], v[184:187], v[216:219], v[66:69]
	s_barrier
	s_add_i32 s54, s48, s35
	s_mov_b32 m0, s54
	ds_read_b128 v[188:191], v154 offset:16384
	ds_read_b128 v[192:195], v154 offset:17408
	ds_read_b128 v[196:199], v154 offset:18432
	ds_read_b128 v[200:203], v154 offset:19456
	ds_read_b128 v[204:207], v154 offset:20480
	ds_read_b128 v[208:211], v154 offset:21504
	ds_read_b128 v[212:215], v154 offset:22528
	ds_read_b128 v[216:219], v154 offset:23552
	global_load_lds_dwordx4 v132, s[28:29]
	s_add_i32 m0, s54, 0x2000
	s_add_u32 s54, s28, 0xb0000
	s_addc_u32 s55, s29, 0
	s_add_i32 s56, s49, s35
	global_load_lds_dwordx4 v136, s[28:29]
	s_mov_b32 m0, s56
	s_nop 0
	global_load_lds_dwordx4 v132, s[54:55]
	s_add_i32 m0, s56, 0x2000
	s_nop 0
	global_load_lds_dwordx4 v136, s[54:55]
	s_mov_b32 m0, s41
	s_nop 0
	global_load_lds_dwordx4 v130, s[30:31]
	s_mov_b32 m0, s42
	s_nop 0
	global_load_lds_dwordx4 v134, s[30:31]
	s_waitcnt vmcnt(8)
	s_waitcnt lgkmcnt(0)
	s_barrier
	v_mfma_f32_16x16x32_bf16 v[62:65], v[156:159], v[188:191], v[62:65]
	v_mfma_f32_16x16x32_bf16 v[58:61], v[164:167], v[188:191], v[58:61]
	v_mfma_f32_16x16x32_bf16 v[46:49], v[156:159], v[196:199], v[46:49]
	v_mfma_f32_16x16x32_bf16 v[42:45], v[164:167], v[196:199], v[42:45]
	v_mfma_f32_16x16x32_bf16 v[30:33], v[156:159], v[204:207], v[30:33]
	v_mfma_f32_16x16x32_bf16 v[26:29], v[164:167], v[204:207], v[26:29]
	v_mfma_f32_16x16x32_bf16 v[14:17], v[156:159], v[212:215], v[14:17]
	v_mfma_f32_16x16x32_bf16 v[10:13], v[164:167], v[212:215], v[10:13]
	v_mfma_f32_16x16x32_bf16 v[62:65], v[160:163], v[192:195], v[62:65]
	v_mfma_f32_16x16x32_bf16 v[58:61], v[168:171], v[192:195], v[58:61]
	v_mfma_f32_16x16x32_bf16 v[46:49], v[160:163], v[200:203], v[46:49]
	v_mfma_f32_16x16x32_bf16 v[42:45], v[168:171], v[200:203], v[42:45]
	v_mfma_f32_16x16x32_bf16 v[30:33], v[160:163], v[208:211], v[30:33]
	v_mfma_f32_16x16x32_bf16 v[26:29], v[168:171], v[208:211], v[26:29]
	v_mfma_f32_16x16x32_bf16 v[14:17], v[160:163], v[216:219], v[14:17]
	v_mfma_f32_16x16x32_bf16 v[10:13], v[168:171], v[216:219], v[10:13]
	v_mfma_f32_16x16x32_bf16 v[54:57], v[172:175], v[188:191], v[54:57]
	v_mfma_f32_16x16x32_bf16 v[50:53], v[180:183], v[188:191], v[50:53]
	v_mfma_f32_16x16x32_bf16 v[38:41], v[172:175], v[196:199], v[38:41]
	v_mfma_f32_16x16x32_bf16 v[34:37], v[180:183], v[196:199], v[34:37]
	v_mfma_f32_16x16x32_bf16 v[22:25], v[172:175], v[204:207], v[22:25]
	v_mfma_f32_16x16x32_bf16 v[18:21], v[180:183], v[204:207], v[18:21]
	v_mfma_f32_16x16x32_bf16 v[6:9], v[172:175], v[212:215], v[6:9]
	v_mfma_f32_16x16x32_bf16 v[2:5], v[180:183], v[212:215], v[2:5]
	v_mfma_f32_16x16x32_bf16 v[54:57], v[176:179], v[192:195], v[54:57]
	v_mfma_f32_16x16x32_bf16 v[50:53], v[184:187], v[192:195], v[50:53]
	v_mfma_f32_16x16x32_bf16 v[38:41], v[176:179], v[200:203], v[38:41]
	v_mfma_f32_16x16x32_bf16 v[34:37], v[184:187], v[200:203], v[34:37]
	v_mfma_f32_16x16x32_bf16 v[22:25], v[176:179], v[208:211], v[22:25]
	v_mfma_f32_16x16x32_bf16 v[18:21], v[184:187], v[208:211], v[18:21]
	v_mfma_f32_16x16x32_bf16 v[6:9], v[176:179], v[216:219], v[6:9]
	v_mfma_f32_16x16x32_bf16 v[2:5], v[184:187], v[216:219], v[2:5]
	s_barrier
	s_add_i32 s54, 0, 0x18000
	v_add_u32_e32 v155, s54, v153
	s_add_i32 s55, 0, 0x1c000
	ds_read_b128 v[156:159], v155
	ds_read_b128 v[160:163], v155 offset:1024
	ds_read_b128 v[164:167], v155 offset:2048
	ds_read_b128 v[168:171], v155 offset:3072
	v_add_u32_e32 v155, s55, v153
	ds_read_b128 v[172:175], v155
	ds_read_b128 v[176:179], v155 offset:1024
	ds_read_b128 v[180:183], v155 offset:2048
	ds_read_b128 v[184:187], v155 offset:3072
	s_add_u32 s98, s30, 0xb0000
	s_addc_u32 s99, s31, 0
	s_mov_b32 m0, s43
	ds_read_b128 v[188:191], v154 offset:32768
	ds_read_b128 v[192:195], v154 offset:33792
	ds_read_b128 v[196:199], v154 offset:34816
	ds_read_b128 v[200:203], v154 offset:35840
	ds_read_b128 v[204:207], v154 offset:36864
	ds_read_b128 v[208:211], v154 offset:37888
	ds_read_b128 v[212:215], v154 offset:38912
	ds_read_b128 v[216:219], v154 offset:39936
	global_load_lds_dwordx4 v130, s[98:99]
	s_mov_b32 m0, s44
	s_nop 0
	global_load_lds_dwordx4 v134, s[98:99]
	s_waitcnt vmcnt(8)
	s_waitcnt lgkmcnt(0)
	s_barrier
	v_mfma_f32_16x16x32_bf16 v[126:129], v[156:159], v[188:191], v[126:129]
	v_mfma_f32_16x16x32_bf16 v[122:125], v[164:167], v[188:191], v[122:125]
	v_mfma_f32_16x16x32_bf16 v[110:113], v[156:159], v[196:199], v[110:113]
	v_mfma_f32_16x16x32_bf16 v[106:109], v[164:167], v[196:199], v[106:109]
	v_mfma_f32_16x16x32_bf16 v[94:97], v[156:159], v[204:207], v[94:97]
	v_mfma_f32_16x16x32_bf16 v[90:93], v[164:167], v[204:207], v[90:93]
	v_mfma_f32_16x16x32_bf16 v[78:81], v[156:159], v[212:215], v[78:81]
	v_mfma_f32_16x16x32_bf16 v[74:77], v[164:167], v[212:215], v[74:77]
	v_mfma_f32_16x16x32_bf16 v[126:129], v[160:163], v[192:195], v[126:129]
	v_mfma_f32_16x16x32_bf16 v[122:125], v[168:171], v[192:195], v[122:125]
	v_mfma_f32_16x16x32_bf16 v[110:113], v[160:163], v[200:203], v[110:113]
	v_mfma_f32_16x16x32_bf16 v[106:109], v[168:171], v[200:203], v[106:109]
	v_mfma_f32_16x16x32_bf16 v[94:97], v[160:163], v[208:211], v[94:97]
	v_mfma_f32_16x16x32_bf16 v[90:93], v[168:171], v[208:211], v[90:93]
	v_mfma_f32_16x16x32_bf16 v[78:81], v[160:163], v[216:219], v[78:81]
	v_mfma_f32_16x16x32_bf16 v[74:77], v[168:171], v[216:219], v[74:77]
	v_mfma_f32_16x16x32_bf16 v[118:121], v[172:175], v[188:191], v[118:121]
	v_mfma_f32_16x16x32_bf16 v[114:117], v[180:183], v[188:191], v[114:117]
	v_mfma_f32_16x16x32_bf16 v[102:105], v[172:175], v[196:199], v[102:105]
	v_mfma_f32_16x16x32_bf16 v[98:101], v[180:183], v[196:199], v[98:101]
	v_mfma_f32_16x16x32_bf16 v[86:89], v[172:175], v[204:207], v[86:89]
	v_mfma_f32_16x16x32_bf16 v[82:85], v[180:183], v[204:207], v[82:85]
	v_mfma_f32_16x16x32_bf16 v[70:73], v[172:175], v[212:215], v[70:73]
	v_mfma_f32_16x16x32_bf16 v[66:69], v[180:183], v[212:215], v[66:69]
	v_mfma_f32_16x16x32_bf16 v[118:121], v[176:179], v[192:195], v[118:121]
	v_mfma_f32_16x16x32_bf16 v[114:117], v[184:187], v[192:195], v[114:117]
	v_mfma_f32_16x16x32_bf16 v[102:105], v[176:179], v[200:203], v[102:105]
	v_mfma_f32_16x16x32_bf16 v[98:101], v[184:187], v[200:203], v[98:101]
	v_mfma_f32_16x16x32_bf16 v[86:89], v[176:179], v[208:211], v[86:89]
	v_mfma_f32_16x16x32_bf16 v[82:85], v[184:187], v[208:211], v[82:85]
	v_mfma_f32_16x16x32_bf16 v[70:73], v[176:179], v[216:219], v[70:73]
	v_mfma_f32_16x16x32_bf16 v[66:69], v[184:187], v[216:219], v[66:69]
	s_barrier
	s_add_i32 s98, s54, s35
	s_add_i32 m0, s98, 0xffffff80
	ds_read_b128 v[188:191], v154 offset:49152
	ds_read_b128 v[192:195], v154 offset:50176
	ds_read_b128 v[196:199], v154 offset:51200
	ds_read_b128 v[200:203], v154 offset:52224
	ds_read_b128 v[204:207], v154 offset:53248
	ds_read_b128 v[208:211], v154 offset:54272
	ds_read_b128 v[212:215], v154 offset:55296
	ds_read_b128 v[216:219], v154 offset:56320
	global_load_lds_dwordx4 v132, s[28:29] offset:128
	s_add_i32 m0, s98, 0x1f80
	s_add_i32 s98, s55, s35
	global_load_lds_dwordx4 v136, s[28:29] offset:128
	s_add_u32 s28, s28, 0xb0080
	s_addc_u32 s29, s29, 0
	s_mov_b32 m0, s98
	s_nop 0
	global_load_lds_dwordx4 v132, s[28:29]
	s_add_i32 m0, s98, 0x2000
	s_nop 0
	global_load_lds_dwordx4 v136, s[28:29]
	s_add_i32 m0, s46, 0xffffff80
	s_nop 0
	global_load_lds_dwordx4 v130, s[30:31] offset:128
	s_add_i32 m0, s47, 0xffffff80
	s_nop 0
	global_load_lds_dwordx4 v134, s[30:31] offset:128
	s_waitcnt vmcnt(8)
	s_waitcnt lgkmcnt(0)
	s_barrier
	v_mfma_f32_16x16x32_bf16 v[62:65], v[156:159], v[188:191], v[62:65]
	v_mfma_f32_16x16x32_bf16 v[58:61], v[164:167], v[188:191], v[58:61]
	v_mfma_f32_16x16x32_bf16 v[46:49], v[156:159], v[196:199], v[46:49]
	v_mfma_f32_16x16x32_bf16 v[42:45], v[164:167], v[196:199], v[42:45]
	v_mfma_f32_16x16x32_bf16 v[30:33], v[156:159], v[204:207], v[30:33]
	v_mfma_f32_16x16x32_bf16 v[26:29], v[164:167], v[204:207], v[26:29]
	v_mfma_f32_16x16x32_bf16 v[14:17], v[156:159], v[212:215], v[14:17]
	v_mfma_f32_16x16x32_bf16 v[10:13], v[164:167], v[212:215], v[10:13]
	v_mfma_f32_16x16x32_bf16 v[62:65], v[160:163], v[192:195], v[62:65]
	v_mfma_f32_16x16x32_bf16 v[58:61], v[168:171], v[192:195], v[58:61]
	v_mfma_f32_16x16x32_bf16 v[46:49], v[160:163], v[200:203], v[46:49]
	v_mfma_f32_16x16x32_bf16 v[42:45], v[168:171], v[200:203], v[42:45]
	v_mfma_f32_16x16x32_bf16 v[30:33], v[160:163], v[208:211], v[30:33]
	v_mfma_f32_16x16x32_bf16 v[26:29], v[168:171], v[208:211], v[26:29]
	v_mfma_f32_16x16x32_bf16 v[14:17], v[160:163], v[216:219], v[14:17]
	v_mfma_f32_16x16x32_bf16 v[10:13], v[168:171], v[216:219], v[10:13]
	v_mfma_f32_16x16x32_bf16 v[54:57], v[172:175], v[188:191], v[54:57]
	v_mfma_f32_16x16x32_bf16 v[50:53], v[180:183], v[188:191], v[50:53]
	v_mfma_f32_16x16x32_bf16 v[38:41], v[172:175], v[196:199], v[38:41]
	v_mfma_f32_16x16x32_bf16 v[34:37], v[180:183], v[196:199], v[34:37]
	v_mfma_f32_16x16x32_bf16 v[22:25], v[172:175], v[204:207], v[22:25]
	v_mfma_f32_16x16x32_bf16 v[18:21], v[180:183], v[204:207], v[18:21]
	v_mfma_f32_16x16x32_bf16 v[6:9], v[172:175], v[212:215], v[6:9]
	v_mfma_f32_16x16x32_bf16 v[2:5], v[180:183], v[212:215], v[2:5]
	v_mfma_f32_16x16x32_bf16 v[54:57], v[176:179], v[192:195], v[54:57]
	v_mfma_f32_16x16x32_bf16 v[50:53], v[184:187], v[192:195], v[50:53]
	v_mfma_f32_16x16x32_bf16 v[38:41], v[176:179], v[200:203], v[38:41]
	v_mfma_f32_16x16x32_bf16 v[34:37], v[184:187], v[200:203], v[34:37]
	v_mfma_f32_16x16x32_bf16 v[22:25], v[176:179], v[208:211], v[22:25]
	v_mfma_f32_16x16x32_bf16 v[18:21], v[184:187], v[208:211], v[18:21]
	v_mfma_f32_16x16x32_bf16 v[6:9], v[176:179], v[216:219], v[6:9]
	v_mfma_f32_16x16x32_bf16 v[2:5], v[184:187], v[216:219], v[2:5]
	s_barrier
	s_add_i32 s53, s53, 2
	s_add_u32 s20, s20, 0x100
	s_addc_u32 s21, s21, 0
	s_cmp_gt_u32 s53, 41
	s_cbranch_scc0 .LBB0_2031
	s_add_u32 s20, s17, 0xffffff00
	s_addc_u32 s21, s52, -1
	s_and_b64 vcc, exec, s[4:5]
	s_cbranch_vccnz .LBB0_2034
	v_mov_b32_e32 v2, 0
	v_mov_b32_e32 v3, 0
	v_mov_b64_e32 v[4:5], v[2:3]
	v_mov_b64_e32 v[6:7], v[2:3]
	v_mov_b64_e32 v[8:9], v[2:3]
	v_mov_b64_e32 v[10:11], v[2:3]
	v_mov_b64_e32 v[12:13], v[2:3]
	v_mov_b64_e32 v[14:15], v[2:3]
	v_mov_b64_e32 v[16:17], v[2:3]
	v_mov_b64_e32 v[18:19], v[2:3]
	v_mov_b64_e32 v[20:21], v[2:3]
	v_mov_b64_e32 v[22:23], v[2:3]
	v_mov_b64_e32 v[24:25], v[2:3]
	v_mov_b64_e32 v[26:27], v[2:3]
	v_mov_b64_e32 v[28:29], v[2:3]
	v_mov_b64_e32 v[30:31], v[2:3]
	v_mov_b64_e32 v[32:33], v[2:3]
	v_mov_b64_e32 v[34:35], v[2:3]
	v_mov_b64_e32 v[36:37], v[2:3]
	v_mov_b64_e32 v[38:39], v[2:3]
	v_mov_b64_e32 v[40:41], v[2:3]
	v_mov_b64_e32 v[42:43], v[2:3]
	v_mov_b64_e32 v[44:45], v[2:3]
	v_mov_b64_e32 v[46:47], v[2:3]
	v_mov_b64_e32 v[48:49], v[2:3]
	v_mov_b64_e32 v[50:51], v[2:3]
	v_mov_b64_e32 v[52:53], v[2:3]
	v_mov_b64_e32 v[54:55], v[2:3]
	v_mov_b64_e32 v[56:57], v[2:3]
	v_mov_b64_e32 v[58:59], v[2:3]
	v_mov_b64_e32 v[60:61], v[2:3]
	v_mov_b64_e32 v[62:63], v[2:3]
	v_mov_b64_e32 v[64:65], v[2:3]
	v_mov_b64_e32 v[66:67], v[2:3]
	v_mov_b64_e32 v[68:69], v[2:3]
	v_mov_b64_e32 v[70:71], v[2:3]
	v_mov_b64_e32 v[72:73], v[2:3]
	v_mov_b64_e32 v[74:75], v[2:3]
	v_mov_b64_e32 v[76:77], v[2:3]
	v_mov_b64_e32 v[78:79], v[2:3]
	v_mov_b64_e32 v[80:81], v[2:3]
	v_mov_b64_e32 v[82:83], v[2:3]
	v_mov_b64_e32 v[84:85], v[2:3]
	v_mov_b64_e32 v[86:87], v[2:3]
	v_mov_b64_e32 v[88:89], v[2:3]
	v_mov_b64_e32 v[90:91], v[2:3]
	v_mov_b64_e32 v[92:93], v[2:3]
	v_mov_b64_e32 v[94:95], v[2:3]
	v_mov_b64_e32 v[96:97], v[2:3]
	v_mov_b64_e32 v[98:99], v[2:3]
	v_mov_b64_e32 v[100:101], v[2:3]
	v_mov_b64_e32 v[102:103], v[2:3]
	v_mov_b64_e32 v[104:105], v[2:3]
	v_mov_b64_e32 v[106:107], v[2:3]
	v_mov_b64_e32 v[108:109], v[2:3]
	v_mov_b64_e32 v[110:111], v[2:3]
	v_mov_b64_e32 v[112:113], v[2:3]
	v_mov_b64_e32 v[114:115], v[2:3]
	v_mov_b64_e32 v[116:117], v[2:3]
	v_mov_b64_e32 v[118:119], v[2:3]
	v_mov_b64_e32 v[120:121], v[2:3]
	v_mov_b64_e32 v[122:123], v[2:3]
	v_mov_b64_e32 v[124:125], v[2:3]
	v_mov_b64_e32 v[126:127], v[2:3]
	v_mov_b64_e32 v[128:129], v[2:3]
	s_mov_b32 s10, s50
	s_mov_b32 s23, s51
	s_mov_b64 s[12:13], s[18:19]
	s_mov_b32 s45, s16
	s_andn2_b64 vcc, exec, s[2:3]
	s_cbranch_vccnz .LBB0_2035
	s_branch .LBB0_2036

.LBB0_2133:
	ds_read_b128 v[154:157], v148
	ds_read_b128 v[158:161], v148 offset:1024
	ds_read_b128 v[162:165], v148 offset:2048
	ds_read_b128 v[166:169], v148 offset:3072
	ds_read_b128 v[170:173], v149
	ds_read_b128 v[174:177], v149 offset:1024
	ds_read_b128 v[178:181], v149 offset:2048
	ds_read_b128 v[182:185], v149 offset:3072
	s_add_u32 s28, s20, 0xfa94fc80
	s_addc_u32 s29, s21, -1
	s_cmp_lg_u32 s46, 32
	s_cselect_b32 s28, s28, 0
	s_cselect_b32 s29, s29, 0
	s_add_u32 s30, s4, s28
	s_addc_u32 s31, s5, s29
	s_add_u32 s28, s2, s28
	s_addc_u32 s29, s3, s29
	s_mov_b32 m0, s47
	v_lshl_add_u64 v[218:219], v[144:145], 0, s[20:21]
	ds_read_b128 v[186:189], v150
	ds_read_b128 v[190:193], v150 offset:1024
	ds_read_b128 v[194:197], v150 offset:2048
	ds_read_b128 v[198:201], v150 offset:3072
	ds_read_b128 v[202:205], v150 offset:4096
	ds_read_b128 v[206:209], v150 offset:5120
	ds_read_b128 v[210:213], v150 offset:6144
	ds_read_b128 v[214:217], v150 offset:7168
	global_load_lds_dwordx4 v[218:219], off
	v_lshl_add_u64 v[218:219], v[146:147], 0, s[20:21]
	s_mov_b32 m0, s48
	s_nop 0
	global_load_lds_dwordx4 v[218:219], off
	s_waitcnt vmcnt(8)
	s_waitcnt lgkmcnt(0)
	s_barrier
	v_mfma_f32_16x16x32_bf16 v[58:61], v[154:157], v[186:189], v[58:61]
	v_mfma_f32_16x16x32_bf16 v[70:73], v[162:165], v[186:189], v[70:73]
	v_mfma_f32_16x16x32_bf16 v[42:45], v[154:157], v[194:197], v[42:45]
	v_mfma_f32_16x16x32_bf16 v[50:53], v[162:165], v[194:197], v[50:53]
	v_mfma_f32_16x16x32_bf16 v[34:37], v[154:157], v[202:205], v[34:37]
	v_mfma_f32_16x16x32_bf16 v[38:41], v[162:165], v[202:205], v[38:41]
	v_mfma_f32_16x16x32_bf16 v[26:29], v[154:157], v[210:213], v[26:29]
	v_mfma_f32_16x16x32_bf16 v[30:33], v[162:165], v[210:213], v[30:33]
	v_mfma_f32_16x16x32_bf16 v[58:61], v[158:161], v[190:193], v[58:61]
	v_mfma_f32_16x16x32_bf16 v[70:73], v[166:169], v[190:193], v[70:73]
	v_mfma_f32_16x16x32_bf16 v[42:45], v[158:161], v[198:201], v[42:45]
	v_mfma_f32_16x16x32_bf16 v[50:53], v[166:169], v[198:201], v[50:53]
	v_mfma_f32_16x16x32_bf16 v[34:37], v[158:161], v[206:209], v[34:37]
	v_mfma_f32_16x16x32_bf16 v[38:41], v[166:169], v[206:209], v[38:41]
	v_mfma_f32_16x16x32_bf16 v[26:29], v[158:161], v[214:217], v[26:29]
	v_mfma_f32_16x16x32_bf16 v[30:33], v[166:169], v[214:217], v[30:33]
	v_mfma_f32_16x16x32_bf16 v[106:109], v[170:173], v[186:189], v[106:109]
	v_mfma_f32_16x16x32_bf16 v[110:113], v[178:181], v[186:189], v[110:113]
	v_mfma_f32_16x16x32_bf16 v[98:101], v[170:173], v[194:197], v[98:101]
	v_mfma_f32_16x16x32_bf16 v[102:105], v[178:181], v[194:197], v[102:105]
	v_mfma_f32_16x16x32_bf16 v[90:93], v[170:173], v[202:205], v[90:93]
	v_mfma_f32_16x16x32_bf16 v[94:97], v[178:181], v[202:205], v[94:97]
	v_mfma_f32_16x16x32_bf16 v[82:85], v[170:173], v[210:213], v[82:85]
	v_mfma_f32_16x16x32_bf16 v[86:89], v[178:181], v[210:213], v[86:89]
	v_mfma_f32_16x16x32_bf16 v[106:109], v[174:177], v[190:193], v[106:109]
	v_mfma_f32_16x16x32_bf16 v[110:113], v[182:185], v[190:193], v[110:113]
	v_mfma_f32_16x16x32_bf16 v[98:101], v[174:177], v[198:201], v[98:101]
	v_mfma_f32_16x16x32_bf16 v[102:105], v[182:185], v[198:201], v[102:105]
	v_mfma_f32_16x16x32_bf16 v[90:93], v[174:177], v[206:209], v[90:93]
	v_mfma_f32_16x16x32_bf16 v[94:97], v[182:185], v[206:209], v[94:97]
	v_mfma_f32_16x16x32_bf16 v[82:85], v[174:177], v[214:217], v[82:85]
	v_mfma_f32_16x16x32_bf16 v[86:89], v[182:185], v[214:217], v[86:89]
	s_barrier
	s_mov_b32 m0, s49
	s_add_u32 s58, s28, 0xb0000
	ds_read_b128 v[186:189], v150 offset:16384
	ds_read_b128 v[190:193], v150 offset:17408
	ds_read_b128 v[194:197], v150 offset:18432
	ds_read_b128 v[198:201], v150 offset:19456
	ds_read_b128 v[202:205], v150 offset:20480
	ds_read_b128 v[206:209], v150 offset:21504
	ds_read_b128 v[210:213], v150 offset:22528
	ds_read_b128 v[214:217], v150 offset:23552
	global_load_lds_dwordx4 v116, s[28:29]
	s_mov_b32 m0, s50
	s_addc_u32 s59, s29, 0
	global_load_lds_dwordx4 v124, s[28:29]
	s_mov_b32 m0, s51
	s_nop 0
	global_load_lds_dwordx4 v116, s[58:59]
	s_mov_b32 m0, s52
	s_nop 0
	global_load_lds_dwordx4 v124, s[58:59]
	s_mov_b32 m0, s25
	s_nop 0
	global_load_lds_dwordx4 v114, s[30:31]
	s_mov_b32 m0, s35
	s_nop 0
	global_load_lds_dwordx4 v122, s[30:31]
	s_waitcnt vmcnt(8)
	s_waitcnt lgkmcnt(0)
	s_barrier
	v_mfma_f32_16x16x32_bf16 v[18:21], v[154:157], v[186:189], v[18:21]
	v_mfma_f32_16x16x32_bf16 v[22:25], v[162:165], v[186:189], v[22:25]
	v_mfma_f32_16x16x32_bf16 v[10:13], v[154:157], v[194:197], v[10:13]
	v_mfma_f32_16x16x32_bf16 v[14:17], v[162:165], v[194:197], v[14:17]
	v_mfma_f32_16x16x32_bf16 v[2:5], v[154:157], v[202:205], v[2:5]
	v_mfma_f32_16x16x32_bf16 v[6:9], v[162:165], v[202:205], v[6:9]
	v_mfma_f32_16x16x32_bf16 v[62:65], v[154:157], v[210:213], v[62:65]
	v_mfma_f32_16x16x32_bf16 v[74:77], v[162:165], v[210:213], v[74:77]
	v_mfma_f32_16x16x32_bf16 v[18:21], v[158:161], v[190:193], v[18:21]
	v_mfma_f32_16x16x32_bf16 v[22:25], v[166:169], v[190:193], v[22:25]
	v_mfma_f32_16x16x32_bf16 v[10:13], v[158:161], v[198:201], v[10:13]
	v_mfma_f32_16x16x32_bf16 v[14:17], v[166:169], v[198:201], v[14:17]
	v_mfma_f32_16x16x32_bf16 v[2:5], v[158:161], v[206:209], v[2:5]
	v_mfma_f32_16x16x32_bf16 v[6:9], v[166:169], v[206:209], v[6:9]
	v_mfma_f32_16x16x32_bf16 v[62:65], v[158:161], v[214:217], v[62:65]
	v_mfma_f32_16x16x32_bf16 v[74:77], v[166:169], v[214:217], v[74:77]
	v_mfma_f32_16x16x32_bf16 v[66:69], v[170:173], v[186:189], v[66:69]
	v_mfma_f32_16x16x32_bf16 v[78:81], v[178:181], v[186:189], v[78:81]
	v_mfma_f32_16x16x32_bf16 v[46:49], v[170:173], v[194:197], v[46:49]
	v_mfma_f32_16x16x32_bf16 v[54:57], v[178:181], v[194:197], v[54:57]
	v_mfma_f32_16x16x32_bf16 v[118:121], v[170:173], v[202:205], v[118:121]
	v_mfma_f32_16x16x32_bf16 v[126:129], v[178:181], v[202:205], v[126:129]
	v_mfma_f32_16x16x32_bf16 v[130:133], v[170:173], v[210:213], v[130:133]
	v_mfma_f32_16x16x32_bf16 v[134:137], v[178:181], v[210:213], v[134:137]
	v_mfma_f32_16x16x32_bf16 v[66:69], v[174:177], v[190:193], v[66:69]
	v_mfma_f32_16x16x32_bf16 v[78:81], v[182:185], v[190:193], v[78:81]
	v_mfma_f32_16x16x32_bf16 v[46:49], v[174:177], v[198:201], v[46:49]
	v_mfma_f32_16x16x32_bf16 v[54:57], v[182:185], v[198:201], v[54:57]
	v_mfma_f32_16x16x32_bf16 v[118:121], v[174:177], v[206:209], v[118:121]
	v_mfma_f32_16x16x32_bf16 v[126:129], v[182:185], v[206:209], v[126:129]
	v_mfma_f32_16x16x32_bf16 v[130:133], v[174:177], v[214:217], v[130:133]
	v_mfma_f32_16x16x32_bf16 v[134:137], v[182:185], v[214:217], v[134:137]
	s_barrier
	ds_read_b128 v[154:157], v151
	ds_read_b128 v[158:161], v151 offset:1024
	ds_read_b128 v[162:165], v151 offset:2048
	ds_read_b128 v[166:169], v151 offset:3072
	ds_read_b128 v[170:173], v152
	ds_read_b128 v[174:177], v152 offset:1024
	ds_read_b128 v[178:181], v152 offset:2048
	ds_read_b128 v[182:185], v152 offset:3072
	s_add_u32 s98, s30, 0xb0000
	s_addc_u32 s99, s31, 0
	s_mov_b32 m0, s42
	ds_read_b128 v[186:189], v150 offset:32768
	ds_read_b128 v[190:193], v150 offset:33792
	ds_read_b128 v[194:197], v150 offset:34816
	ds_read_b128 v[198:201], v150 offset:35840
	ds_read_b128 v[202:205], v150 offset:36864
	ds_read_b128 v[206:209], v150 offset:37888
	ds_read_b128 v[210:213], v150 offset:38912
	ds_read_b128 v[214:217], v150 offset:39936
	global_load_lds_dwordx4 v114, s[98:99]
	s_mov_b32 m0, s43
	s_nop 0
	global_load_lds_dwordx4 v122, s[98:99]
	s_waitcnt vmcnt(8)
	s_waitcnt lgkmcnt(0)
	s_barrier
	v_mfma_f32_16x16x32_bf16 v[58:61], v[154:157], v[186:189], v[58:61]
	v_mfma_f32_16x16x32_bf16 v[70:73], v[162:165], v[186:189], v[70:73]
	v_mfma_f32_16x16x32_bf16 v[42:45], v[154:157], v[194:197], v[42:45]
	v_mfma_f32_16x16x32_bf16 v[50:53], v[162:165], v[194:197], v[50:53]
	v_mfma_f32_16x16x32_bf16 v[34:37], v[154:157], v[202:205], v[34:37]
	v_mfma_f32_16x16x32_bf16 v[38:41], v[162:165], v[202:205], v[38:41]
	v_mfma_f32_16x16x32_bf16 v[26:29], v[154:157], v[210:213], v[26:29]
	v_mfma_f32_16x16x32_bf16 v[30:33], v[162:165], v[210:213], v[30:33]
	v_mfma_f32_16x16x32_bf16 v[58:61], v[158:161], v[190:193], v[58:61]
	v_mfma_f32_16x16x32_bf16 v[70:73], v[166:169], v[190:193], v[70:73]
	v_mfma_f32_16x16x32_bf16 v[42:45], v[158:161], v[198:201], v[42:45]
	v_mfma_f32_16x16x32_bf16 v[50:53], v[166:169], v[198:201], v[50:53]
	v_mfma_f32_16x16x32_bf16 v[34:37], v[158:161], v[206:209], v[34:37]
	v_mfma_f32_16x16x32_bf16 v[38:41], v[166:169], v[206:209], v[38:41]
	v_mfma_f32_16x16x32_bf16 v[26:29], v[158:161], v[214:217], v[26:29]
	v_mfma_f32_16x16x32_bf16 v[30:33], v[166:169], v[214:217], v[30:33]
	v_mfma_f32_16x16x32_bf16 v[106:109], v[170:173], v[186:189], v[106:109]
	v_mfma_f32_16x16x32_bf16 v[110:113], v[178:181], v[186:189], v[110:113]
	v_mfma_f32_16x16x32_bf16 v[98:101], v[170:173], v[194:197], v[98:101]
	v_mfma_f32_16x16x32_bf16 v[102:105], v[178:181], v[194:197], v[102:105]
	v_mfma_f32_16x16x32_bf16 v[90:93], v[170:173], v[202:205], v[90:93]
	v_mfma_f32_16x16x32_bf16 v[94:97], v[178:181], v[202:205], v[94:97]
	v_mfma_f32_16x16x32_bf16 v[82:85], v[170:173], v[210:213], v[82:85]
	v_mfma_f32_16x16x32_bf16 v[86:89], v[178:181], v[210:213], v[86:89]
	v_mfma_f32_16x16x32_bf16 v[106:109], v[174:177], v[190:193], v[106:109]
	v_mfma_f32_16x16x32_bf16 v[110:113], v[182:185], v[190:193], v[110:113]
	v_mfma_f32_16x16x32_bf16 v[98:101], v[174:177], v[198:201], v[98:101]
	v_mfma_f32_16x16x32_bf16 v[102:105], v[182:185], v[198:201], v[102:105]
	v_mfma_f32_16x16x32_bf16 v[90:93], v[174:177], v[206:209], v[90:93]
	v_mfma_f32_16x16x32_bf16 v[94:97], v[182:185], v[206:209], v[94:97]
	v_mfma_f32_16x16x32_bf16 v[82:85], v[174:177], v[214:217], v[82:85]
	v_mfma_f32_16x16x32_bf16 v[86:89], v[182:185], v[214:217], v[86:89]
	s_barrier
	s_add_i32 m0, s53, 0xffffff80
	ds_read_b128 v[186:189], v150 offset:49152
	ds_read_b128 v[190:193], v150 offset:50176
	ds_read_b128 v[194:197], v150 offset:51200
	ds_read_b128 v[198:201], v150 offset:52224
	ds_read_b128 v[202:205], v150 offset:53248
	ds_read_b128 v[206:209], v150 offset:54272
	ds_read_b128 v[210:213], v150 offset:55296
	ds_read_b128 v[214:217], v150 offset:56320
	global_load_lds_dwordx4 v116, s[28:29] offset:128
	s_add_i32 m0, s54, 0xffffff80
	s_nop 0
	global_load_lds_dwordx4 v124, s[28:29] offset:128
	s_add_u32 s28, s28, 0xb0080
	s_addc_u32 s29, s29, 0
	s_mov_b32 m0, s55
	s_nop 0
	global_load_lds_dwordx4 v116, s[28:29]
	s_mov_b32 m0, s56
	s_nop 0
	global_load_lds_dwordx4 v124, s[28:29]
	s_add_i32 m0, s44, 0xffffff80
	s_nop 0
	global_load_lds_dwordx4 v114, s[30:31] offset:128
	s_add_i32 m0, s45, 0xffffff80
	s_nop 0
	global_load_lds_dwordx4 v122, s[30:31] offset:128
	s_waitcnt vmcnt(8)
	s_waitcnt lgkmcnt(0)
	s_barrier
	v_mfma_f32_16x16x32_bf16 v[18:21], v[154:157], v[186:189], v[18:21]
	v_mfma_f32_16x16x32_bf16 v[22:25], v[162:165], v[186:189], v[22:25]
	v_mfma_f32_16x16x32_bf16 v[10:13], v[154:157], v[194:197], v[10:13]
	v_mfma_f32_16x16x32_bf16 v[14:17], v[162:165], v[194:197], v[14:17]
	v_mfma_f32_16x16x32_bf16 v[2:5], v[154:157], v[202:205], v[2:5]
	v_mfma_f32_16x16x32_bf16 v[6:9], v[162:165], v[202:205], v[6:9]
	v_mfma_f32_16x16x32_bf16 v[62:65], v[154:157], v[210:213], v[62:65]
	v_mfma_f32_16x16x32_bf16 v[74:77], v[162:165], v[210:213], v[74:77]
	v_mfma_f32_16x16x32_bf16 v[18:21], v[158:161], v[190:193], v[18:21]
	v_mfma_f32_16x16x32_bf16 v[22:25], v[166:169], v[190:193], v[22:25]
	v_mfma_f32_16x16x32_bf16 v[10:13], v[158:161], v[198:201], v[10:13]
	v_mfma_f32_16x16x32_bf16 v[14:17], v[166:169], v[198:201], v[14:17]
	v_mfma_f32_16x16x32_bf16 v[2:5], v[158:161], v[206:209], v[2:5]
	v_mfma_f32_16x16x32_bf16 v[6:9], v[166:169], v[206:209], v[6:9]
	v_mfma_f32_16x16x32_bf16 v[62:65], v[158:161], v[214:217], v[62:65]
	v_mfma_f32_16x16x32_bf16 v[74:77], v[166:169], v[214:217], v[74:77]
	v_mfma_f32_16x16x32_bf16 v[66:69], v[170:173], v[186:189], v[66:69]
	v_mfma_f32_16x16x32_bf16 v[78:81], v[178:181], v[186:189], v[78:81]
	v_mfma_f32_16x16x32_bf16 v[46:49], v[170:173], v[194:197], v[46:49]
	v_mfma_f32_16x16x32_bf16 v[54:57], v[178:181], v[194:197], v[54:57]
	v_mfma_f32_16x16x32_bf16 v[118:121], v[170:173], v[202:205], v[118:121]
	v_mfma_f32_16x16x32_bf16 v[126:129], v[178:181], v[202:205], v[126:129]
	v_mfma_f32_16x16x32_bf16 v[130:133], v[170:173], v[210:213], v[130:133]
	v_mfma_f32_16x16x32_bf16 v[134:137], v[178:181], v[210:213], v[134:137]
	v_mfma_f32_16x16x32_bf16 v[66:69], v[174:177], v[190:193], v[66:69]
	v_mfma_f32_16x16x32_bf16 v[78:81], v[182:185], v[190:193], v[78:81]
	v_mfma_f32_16x16x32_bf16 v[46:49], v[174:177], v[198:201], v[46:49]
	v_mfma_f32_16x16x32_bf16 v[54:57], v[182:185], v[198:201], v[54:57]
	v_mfma_f32_16x16x32_bf16 v[118:121], v[174:177], v[206:209], v[118:121]
	v_mfma_f32_16x16x32_bf16 v[126:129], v[182:185], v[206:209], v[126:129]
	v_mfma_f32_16x16x32_bf16 v[130:133], v[174:177], v[214:217], v[130:133]
	v_mfma_f32_16x16x32_bf16 v[134:137], v[182:185], v[214:217], v[134:137]
	s_barrier
	s_add_i32 s46, s46, 2
	s_add_u32 s20, s20, 0x100
	s_addc_u32 s21, s21, 0
	s_cmp_lt_u32 s46, 34
	s_cbranch_scc1 .LBB0_2133
	s_waitcnt vmcnt(0)
	s_cmpk_gt_u32 s22, 0xff
	s_cbranch_scc1 .LBB0_2136
	s_barrier

.LBB0_2205:
	ds_read_b128 v[158:161], v152
	ds_read_b128 v[162:165], v152 offset:1024
	ds_read_b128 v[166:169], v152 offset:2048
	ds_read_b128 v[170:173], v152 offset:3072
	ds_read_b128 v[174:177], v153
	ds_read_b128 v[178:181], v153 offset:1024
	ds_read_b128 v[182:185], v153 offset:2048
	ds_read_b128 v[186:189], v153 offset:3072
	s_add_u32 s20, s26, s45
	s_addc_u32 s21, s27, s46
	s_add_u32 s60, s26, s47
	s_addc_u32 s61, s27, s48
	s_cmp_eq_u32 s49, 4
	s_cselect_b32 s25, s3, s21
	s_cselect_b32 s24, s2, s20
	s_cselect_b32 s21, s1, s61
	s_cselect_b32 s20, s0, s60
	s_mov_b32 m0, s50
	v_lshl_add_u64 v[222:223], s[26:27], 0, v[146:147]
	ds_read_b128 v[190:193], v154
	ds_read_b128 v[194:197], v154 offset:1024
	ds_read_b128 v[198:201], v154 offset:2048
	ds_read_b128 v[202:205], v154 offset:3072
	ds_read_b128 v[206:209], v154 offset:4096
	ds_read_b128 v[210:213], v154 offset:5120
	ds_read_b128 v[214:217], v154 offset:6144
	ds_read_b128 v[218:221], v154 offset:7168
	global_load_lds_dwordx4 v[222:223], off
	v_lshl_add_u64 v[222:223], s[26:27], 0, v[148:149]
	s_mov_b32 m0, s51
	s_nop 0
	global_load_lds_dwordx4 v[222:223], off
	s_waitcnt vmcnt(8)
	s_waitcnt lgkmcnt(0)
	s_barrier
	v_mfma_f32_16x16x32_bf16 v[126:129], v[158:161], v[190:193], v[126:129]
	v_mfma_f32_16x16x32_bf16 v[122:125], v[166:169], v[190:193], v[122:125]
	v_mfma_f32_16x16x32_bf16 v[118:121], v[158:161], v[198:201], v[118:121]
	v_mfma_f32_16x16x32_bf16 v[114:117], v[166:169], v[198:201], v[114:117]
	v_mfma_f32_16x16x32_bf16 v[110:113], v[158:161], v[206:209], v[110:113]
	v_mfma_f32_16x16x32_bf16 v[106:109], v[166:169], v[206:209], v[106:109]
	v_mfma_f32_16x16x32_bf16 v[102:105], v[158:161], v[214:217], v[102:105]
	v_mfma_f32_16x16x32_bf16 v[98:101], v[166:169], v[214:217], v[98:101]
	v_mfma_f32_16x16x32_bf16 v[126:129], v[162:165], v[194:197], v[126:129]
	v_mfma_f32_16x16x32_bf16 v[122:125], v[170:173], v[194:197], v[122:125]
	v_mfma_f32_16x16x32_bf16 v[118:121], v[162:165], v[202:205], v[118:121]
	v_mfma_f32_16x16x32_bf16 v[114:117], v[170:173], v[202:205], v[114:117]
	v_mfma_f32_16x16x32_bf16 v[110:113], v[162:165], v[210:213], v[110:113]
	v_mfma_f32_16x16x32_bf16 v[106:109], v[170:173], v[210:213], v[106:109]
	v_mfma_f32_16x16x32_bf16 v[102:105], v[162:165], v[218:221], v[102:105]
	v_mfma_f32_16x16x32_bf16 v[98:101], v[170:173], v[218:221], v[98:101]
	v_mfma_f32_16x16x32_bf16 v[94:97], v[174:177], v[190:193], v[94:97]
	v_mfma_f32_16x16x32_bf16 v[90:93], v[182:185], v[190:193], v[90:93]
	v_mfma_f32_16x16x32_bf16 v[86:89], v[174:177], v[198:201], v[86:89]
	v_mfma_f32_16x16x32_bf16 v[82:85], v[182:185], v[198:201], v[82:85]
	v_mfma_f32_16x16x32_bf16 v[78:81], v[174:177], v[206:209], v[78:81]
	v_mfma_f32_16x16x32_bf16 v[74:77], v[182:185], v[206:209], v[74:77]
	v_mfma_f32_16x16x32_bf16 v[70:73], v[174:177], v[214:217], v[70:73]
	v_mfma_f32_16x16x32_bf16 v[66:69], v[182:185], v[214:217], v[66:69]
	v_mfma_f32_16x16x32_bf16 v[94:97], v[178:181], v[194:197], v[94:97]
	v_mfma_f32_16x16x32_bf16 v[90:93], v[186:189], v[194:197], v[90:93]
	v_mfma_f32_16x16x32_bf16 v[86:89], v[178:181], v[202:205], v[86:89]
	v_mfma_f32_16x16x32_bf16 v[82:85], v[186:189], v[202:205], v[82:85]
	v_mfma_f32_16x16x32_bf16 v[78:81], v[178:181], v[210:213], v[78:81]
	v_mfma_f32_16x16x32_bf16 v[74:77], v[186:189], v[210:213], v[74:77]
	v_mfma_f32_16x16x32_bf16 v[70:73], v[178:181], v[218:221], v[70:73]
	v_mfma_f32_16x16x32_bf16 v[66:69], v[186:189], v[218:221], v[66:69]
	s_barrier
	s_mov_b32 m0, s52
	s_add_u32 s60, s20, 0xb0000
	ds_read_b128 v[190:193], v154 offset:16384
	ds_read_b128 v[194:197], v154 offset:17408
	ds_read_b128 v[198:201], v154 offset:18432
	ds_read_b128 v[202:205], v154 offset:19456
	ds_read_b128 v[206:209], v154 offset:20480
	ds_read_b128 v[210:213], v154 offset:21504
	ds_read_b128 v[214:217], v154 offset:22528
	ds_read_b128 v[218:221], v154 offset:23552
	global_load_lds_dwordx4 v132, s[20:21]
	s_mov_b32 m0, s53
	s_addc_u32 s61, s21, 0
	global_load_lds_dwordx4 v136, s[20:21]
	s_mov_b32 m0, s54
	s_nop 0
	global_load_lds_dwordx4 v132, s[60:61]
	s_mov_b32 m0, s55
	s_nop 0
	global_load_lds_dwordx4 v136, s[60:61]
	s_mov_b32 m0, s31
	s_nop 0
	global_load_lds_dwordx4 v130, s[24:25]
	s_mov_b32 m0, s34
	s_nop 0
	global_load_lds_dwordx4 v134, s[24:25]
	s_waitcnt vmcnt(8)
	s_waitcnt lgkmcnt(0)
	s_barrier
	v_mfma_f32_16x16x32_bf16 v[62:65], v[158:161], v[190:193], v[62:65]
	v_mfma_f32_16x16x32_bf16 v[58:61], v[166:169], v[190:193], v[58:61]
	v_mfma_f32_16x16x32_bf16 v[54:57], v[158:161], v[198:201], v[54:57]
	v_mfma_f32_16x16x32_bf16 v[50:53], v[166:169], v[198:201], v[50:53]
	v_mfma_f32_16x16x32_bf16 v[46:49], v[158:161], v[206:209], v[46:49]
	v_mfma_f32_16x16x32_bf16 v[42:45], v[166:169], v[206:209], v[42:45]
	v_mfma_f32_16x16x32_bf16 v[38:41], v[158:161], v[214:217], v[38:41]
	v_mfma_f32_16x16x32_bf16 v[34:37], v[166:169], v[214:217], v[34:37]
	v_mfma_f32_16x16x32_bf16 v[62:65], v[162:165], v[194:197], v[62:65]
	v_mfma_f32_16x16x32_bf16 v[58:61], v[170:173], v[194:197], v[58:61]
	v_mfma_f32_16x16x32_bf16 v[54:57], v[162:165], v[202:205], v[54:57]
	v_mfma_f32_16x16x32_bf16 v[50:53], v[170:173], v[202:205], v[50:53]
	v_mfma_f32_16x16x32_bf16 v[46:49], v[162:165], v[210:213], v[46:49]
	v_mfma_f32_16x16x32_bf16 v[42:45], v[170:173], v[210:213], v[42:45]
	v_mfma_f32_16x16x32_bf16 v[38:41], v[162:165], v[218:221], v[38:41]
	v_mfma_f32_16x16x32_bf16 v[34:37], v[170:173], v[218:221], v[34:37]
	v_mfma_f32_16x16x32_bf16 v[30:33], v[174:177], v[190:193], v[30:33]
	v_mfma_f32_16x16x32_bf16 v[26:29], v[182:185], v[190:193], v[26:29]
	v_mfma_f32_16x16x32_bf16 v[22:25], v[174:177], v[198:201], v[22:25]
	v_mfma_f32_16x16x32_bf16 v[18:21], v[182:185], v[198:201], v[18:21]
	v_mfma_f32_16x16x32_bf16 v[14:17], v[174:177], v[206:209], v[14:17]
	v_mfma_f32_16x16x32_bf16 v[10:13], v[182:185], v[206:209], v[10:13]
	v_mfma_f32_16x16x32_bf16 v[6:9], v[174:177], v[214:217], v[6:9]
	v_mfma_f32_16x16x32_bf16 v[2:5], v[182:185], v[214:217], v[2:5]
	v_mfma_f32_16x16x32_bf16 v[30:33], v[178:181], v[194:197], v[30:33]
	v_mfma_f32_16x16x32_bf16 v[26:29], v[186:189], v[194:197], v[26:29]
	v_mfma_f32_16x16x32_bf16 v[22:25], v[178:181], v[202:205], v[22:25]
	v_mfma_f32_16x16x32_bf16 v[18:21], v[186:189], v[202:205], v[18:21]
	v_mfma_f32_16x16x32_bf16 v[14:17], v[178:181], v[210:213], v[14:17]
	v_mfma_f32_16x16x32_bf16 v[10:13], v[186:189], v[210:213], v[10:13]
	v_mfma_f32_16x16x32_bf16 v[6:9], v[178:181], v[218:221], v[6:9]
	v_mfma_f32_16x16x32_bf16 v[2:5], v[186:189], v[218:221], v[2:5]
	s_barrier
	ds_read_b128 v[158:161], v155
	ds_read_b128 v[162:165], v155 offset:1024
	ds_read_b128 v[166:169], v155 offset:2048
	ds_read_b128 v[170:173], v155 offset:3072
	ds_read_b128 v[174:177], v156
	ds_read_b128 v[178:181], v156 offset:1024
	ds_read_b128 v[182:185], v156 offset:2048
	ds_read_b128 v[186:189], v156 offset:3072
	s_add_u32 s98, s24, 0xb0000
	s_addc_u32 s99, s25, 0
	s_mov_b32 m0, s35
	ds_read_b128 v[190:193], v154 offset:32768
	ds_read_b128 v[194:197], v154 offset:33792
	ds_read_b128 v[198:201], v154 offset:34816
	ds_read_b128 v[202:205], v154 offset:35840
	ds_read_b128 v[206:209], v154 offset:36864
	ds_read_b128 v[210:213], v154 offset:37888
	ds_read_b128 v[214:217], v154 offset:38912
	ds_read_b128 v[218:221], v154 offset:39936
	global_load_lds_dwordx4 v130, s[98:99]
	s_mov_b32 m0, s42
	s_nop 0
	global_load_lds_dwordx4 v134, s[98:99]
	s_waitcnt vmcnt(8)
	s_waitcnt lgkmcnt(0)
	s_barrier
	v_mfma_f32_16x16x32_bf16 v[126:129], v[158:161], v[190:193], v[126:129]
	v_mfma_f32_16x16x32_bf16 v[122:125], v[166:169], v[190:193], v[122:125]
	v_mfma_f32_16x16x32_bf16 v[118:121], v[158:161], v[198:201], v[118:121]
	v_mfma_f32_16x16x32_bf16 v[114:117], v[166:169], v[198:201], v[114:117]
	v_mfma_f32_16x16x32_bf16 v[110:113], v[158:161], v[206:209], v[110:113]
	v_mfma_f32_16x16x32_bf16 v[106:109], v[166:169], v[206:209], v[106:109]
	v_mfma_f32_16x16x32_bf16 v[102:105], v[158:161], v[214:217], v[102:105]
	v_mfma_f32_16x16x32_bf16 v[98:101], v[166:169], v[214:217], v[98:101]
	v_mfma_f32_16x16x32_bf16 v[126:129], v[162:165], v[194:197], v[126:129]
	v_mfma_f32_16x16x32_bf16 v[122:125], v[170:173], v[194:197], v[122:125]
	v_mfma_f32_16x16x32_bf16 v[118:121], v[162:165], v[202:205], v[118:121]
	v_mfma_f32_16x16x32_bf16 v[114:117], v[170:173], v[202:205], v[114:117]
	v_mfma_f32_16x16x32_bf16 v[110:113], v[162:165], v[210:213], v[110:113]
	v_mfma_f32_16x16x32_bf16 v[106:109], v[170:173], v[210:213], v[106:109]
	v_mfma_f32_16x16x32_bf16 v[102:105], v[162:165], v[218:221], v[102:105]
	v_mfma_f32_16x16x32_bf16 v[98:101], v[170:173], v[218:221], v[98:101]
	v_mfma_f32_16x16x32_bf16 v[94:97], v[174:177], v[190:193], v[94:97]
	v_mfma_f32_16x16x32_bf16 v[90:93], v[182:185], v[190:193], v[90:93]
	v_mfma_f32_16x16x32_bf16 v[86:89], v[174:177], v[198:201], v[86:89]
	v_mfma_f32_16x16x32_bf16 v[82:85], v[182:185], v[198:201], v[82:85]
	v_mfma_f32_16x16x32_bf16 v[78:81], v[174:177], v[206:209], v[78:81]
	v_mfma_f32_16x16x32_bf16 v[74:77], v[182:185], v[206:209], v[74:77]
	v_mfma_f32_16x16x32_bf16 v[70:73], v[174:177], v[214:217], v[70:73]
	v_mfma_f32_16x16x32_bf16 v[66:69], v[182:185], v[214:217], v[66:69]
	v_mfma_f32_16x16x32_bf16 v[94:97], v[178:181], v[194:197], v[94:97]
	v_mfma_f32_16x16x32_bf16 v[90:93], v[186:189], v[194:197], v[90:93]
	v_mfma_f32_16x16x32_bf16 v[86:89], v[178:181], v[202:205], v[86:89]
	v_mfma_f32_16x16x32_bf16 v[82:85], v[186:189], v[202:205], v[82:85]
	v_mfma_f32_16x16x32_bf16 v[78:81], v[178:181], v[210:213], v[78:81]
	v_mfma_f32_16x16x32_bf16 v[74:77], v[186:189], v[210:213], v[74:77]
	v_mfma_f32_16x16x32_bf16 v[70:73], v[178:181], v[218:221], v[70:73]
	v_mfma_f32_16x16x32_bf16 v[66:69], v[186:189], v[218:221], v[66:69]
	s_barrier
	s_add_i32 m0, s56, 0xffffff80
	ds_read_b128 v[190:193], v154 offset:49152
	ds_read_b128 v[194:197], v154 offset:50176
	ds_read_b128 v[198:201], v154 offset:51200
	ds_read_b128 v[202:205], v154 offset:52224
	ds_read_b128 v[206:209], v154 offset:53248
	ds_read_b128 v[210:213], v154 offset:54272
	ds_read_b128 v[214:217], v154 offset:55296
	ds_read_b128 v[218:221], v154 offset:56320
	global_load_lds_dwordx4 v132, s[20:21] offset:128
	s_add_i32 m0, s57, 0xffffff80
	s_nop 0
	global_load_lds_dwordx4 v136, s[20:21] offset:128
	s_add_u32 s20, s20, 0xb0080
	s_addc_u32 s21, s21, 0
	s_mov_b32 m0, s58
	s_nop 0
	global_load_lds_dwordx4 v132, s[20:21]
	s_mov_b32 m0, s59
	s_nop 0
	global_load_lds_dwordx4 v136, s[20:21]
	s_add_i32 m0, s43, 0xffffff80
	s_nop 0
	global_load_lds_dwordx4 v130, s[24:25] offset:128
	s_add_i32 m0, s44, 0xffffff80
	s_nop 0
	global_load_lds_dwordx4 v134, s[24:25] offset:128
	s_waitcnt vmcnt(8)
	s_waitcnt lgkmcnt(0)
	s_barrier
	v_mfma_f32_16x16x32_bf16 v[62:65], v[158:161], v[190:193], v[62:65]
	v_mfma_f32_16x16x32_bf16 v[58:61], v[166:169], v[190:193], v[58:61]
	v_mfma_f32_16x16x32_bf16 v[54:57], v[158:161], v[198:201], v[54:57]
	v_mfma_f32_16x16x32_bf16 v[50:53], v[166:169], v[198:201], v[50:53]
	v_mfma_f32_16x16x32_bf16 v[46:49], v[158:161], v[206:209], v[46:49]
	v_mfma_f32_16x16x32_bf16 v[42:45], v[166:169], v[206:209], v[42:45]
	v_mfma_f32_16x16x32_bf16 v[38:41], v[158:161], v[214:217], v[38:41]
	v_mfma_f32_16x16x32_bf16 v[34:37], v[166:169], v[214:217], v[34:37]
	v_mfma_f32_16x16x32_bf16 v[62:65], v[162:165], v[194:197], v[62:65]
	v_mfma_f32_16x16x32_bf16 v[58:61], v[170:173], v[194:197], v[58:61]
	v_mfma_f32_16x16x32_bf16 v[54:57], v[162:165], v[202:205], v[54:57]
	v_mfma_f32_16x16x32_bf16 v[50:53], v[170:173], v[202:205], v[50:53]
	v_mfma_f32_16x16x32_bf16 v[46:49], v[162:165], v[210:213], v[46:49]
	v_mfma_f32_16x16x32_bf16 v[42:45], v[170:173], v[210:213], v[42:45]
	v_mfma_f32_16x16x32_bf16 v[38:41], v[162:165], v[218:221], v[38:41]
	v_mfma_f32_16x16x32_bf16 v[34:37], v[170:173], v[218:221], v[34:37]
	v_mfma_f32_16x16x32_bf16 v[30:33], v[174:177], v[190:193], v[30:33]
	v_mfma_f32_16x16x32_bf16 v[26:29], v[182:185], v[190:193], v[26:29]
	v_mfma_f32_16x16x32_bf16 v[22:25], v[174:177], v[198:201], v[22:25]
	v_mfma_f32_16x16x32_bf16 v[18:21], v[182:185], v[198:201], v[18:21]
	v_mfma_f32_16x16x32_bf16 v[14:17], v[174:177], v[206:209], v[14:17]
	v_mfma_f32_16x16x32_bf16 v[10:13], v[182:185], v[206:209], v[10:13]
	v_mfma_f32_16x16x32_bf16 v[6:9], v[174:177], v[214:217], v[6:9]
	v_mfma_f32_16x16x32_bf16 v[2:5], v[182:185], v[214:217], v[2:5]
	v_mfma_f32_16x16x32_bf16 v[30:33], v[178:181], v[194:197], v[30:33]
	v_mfma_f32_16x16x32_bf16 v[26:29], v[186:189], v[194:197], v[26:29]
	v_mfma_f32_16x16x32_bf16 v[22:25], v[178:181], v[202:205], v[22:25]
	v_mfma_f32_16x16x32_bf16 v[18:21], v[186:189], v[202:205], v[18:21]
	v_mfma_f32_16x16x32_bf16 v[14:17], v[178:181], v[210:213], v[14:17]
	v_mfma_f32_16x16x32_bf16 v[10:13], v[186:189], v[210:213], v[10:13]
	v_mfma_f32_16x16x32_bf16 v[6:9], v[178:181], v[218:221], v[6:9]
	v_mfma_f32_16x16x32_bf16 v[2:5], v[186:189], v[218:221], v[2:5]
	s_barrier
	s_add_i32 s49, s49, 2
	s_add_u32 s45, s45, 0x100
	s_addc_u32 s46, s46, 0
	s_add_u32 s47, s47, 0x100
	s_addc_u32 s48, s48, 0
	v_lshl_add_u64 v[146:147], v[146:147], 0, s[18:19]
	s_cmp_lt_u32 s49, 6
	v_lshl_add_u64 v[148:149], v[148:149], 0, s[18:19]
	s_cbranch_scc1 .LBB0_2205
	s_waitcnt vmcnt(0)
	s_cmpk_gt_u32 s30, 0xff
	s_cbranch_scc1 .LBB0_2208
	s_barrier

.LBB0_2214:
	ds_read_b128 v[152:155], v144
	ds_read_b128 v[156:159], v144 offset:1024
	ds_read_b128 v[160:163], v144 offset:2048
	ds_read_b128 v[164:167], v144 offset:3072
	ds_read_b128 v[168:171], v145
	ds_read_b128 v[172:175], v145 offset:1024
	ds_read_b128 v[176:179], v145 offset:2048
	ds_read_b128 v[180:183], v145 offset:3072
	s_add_u32 s20, s26, s40
	s_addc_u32 s21, s27, s42
	s_add_u32 s56, s26, s43
	s_addc_u32 s57, s27, s44
	s_cmp_eq_u32 s45, 36
	s_cselect_b32 s25, s5, s21
	s_cselect_b32 s24, s4, s20
	s_cselect_b32 s21, s1, s57
	s_cselect_b32 s20, s0, s56
	s_mov_b32 m0, s46
	v_lshl_add_u64 v[216:217], s[26:27], 0, v[140:141]
	ds_read_b128 v[184:187], v146
	ds_read_b128 v[188:191], v146 offset:1024
	ds_read_b128 v[192:195], v146 offset:2048
	ds_read_b128 v[196:199], v146 offset:3072
	ds_read_b128 v[200:203], v146 offset:4096
	ds_read_b128 v[204:207], v146 offset:5120
	ds_read_b128 v[208:211], v146 offset:6144
	ds_read_b128 v[212:215], v146 offset:7168
	global_load_lds_dwordx4 v[216:217], off
	v_lshl_add_u64 v[216:217], s[26:27], 0, v[142:143]
	s_mov_b32 m0, s47
	s_nop 0
	global_load_lds_dwordx4 v[216:217], off
	s_waitcnt vmcnt(8)
	s_waitcnt lgkmcnt(0)
	s_barrier
	v_mfma_f32_16x16x32_bf16 v[126:129], v[152:155], v[184:187], v[126:129]
	v_mfma_f32_16x16x32_bf16 v[122:125], v[160:163], v[184:187], v[122:125]
	v_mfma_f32_16x16x32_bf16 v[118:121], v[152:155], v[192:195], v[118:121]
	v_mfma_f32_16x16x32_bf16 v[114:117], v[160:163], v[192:195], v[114:117]
	v_mfma_f32_16x16x32_bf16 v[94:97], v[152:155], v[200:203], v[94:97]
	v_mfma_f32_16x16x32_bf16 v[90:93], v[160:163], v[200:203], v[90:93]
	v_mfma_f32_16x16x32_bf16 v[78:81], v[152:155], v[208:211], v[78:81]
	v_mfma_f32_16x16x32_bf16 v[74:77], v[160:163], v[208:211], v[74:77]
	v_mfma_f32_16x16x32_bf16 v[126:129], v[156:159], v[188:191], v[126:129]
	v_mfma_f32_16x16x32_bf16 v[122:125], v[164:167], v[188:191], v[122:125]
	v_mfma_f32_16x16x32_bf16 v[118:121], v[156:159], v[196:199], v[118:121]
	v_mfma_f32_16x16x32_bf16 v[114:117], v[164:167], v[196:199], v[114:117]
	v_mfma_f32_16x16x32_bf16 v[94:97], v[156:159], v[204:207], v[94:97]
	v_mfma_f32_16x16x32_bf16 v[90:93], v[164:167], v[204:207], v[90:93]
	v_mfma_f32_16x16x32_bf16 v[78:81], v[156:159], v[212:215], v[78:81]
	v_mfma_f32_16x16x32_bf16 v[74:77], v[164:167], v[212:215], v[74:77]
	v_mfma_f32_16x16x32_bf16 v[110:113], v[168:171], v[184:187], v[110:113]
	v_mfma_f32_16x16x32_bf16 v[106:109], v[176:179], v[184:187], v[106:109]
	v_mfma_f32_16x16x32_bf16 v[102:105], v[168:171], v[192:195], v[102:105]
	v_mfma_f32_16x16x32_bf16 v[98:101], v[176:179], v[192:195], v[98:101]
	v_mfma_f32_16x16x32_bf16 v[86:89], v[168:171], v[200:203], v[86:89]
	v_mfma_f32_16x16x32_bf16 v[82:85], v[176:179], v[200:203], v[82:85]
	v_mfma_f32_16x16x32_bf16 v[70:73], v[168:171], v[208:211], v[70:73]
	v_mfma_f32_16x16x32_bf16 v[66:69], v[176:179], v[208:211], v[66:69]
	v_mfma_f32_16x16x32_bf16 v[110:113], v[172:175], v[188:191], v[110:113]
	v_mfma_f32_16x16x32_bf16 v[106:109], v[180:183], v[188:191], v[106:109]
	v_mfma_f32_16x16x32_bf16 v[102:105], v[172:175], v[196:199], v[102:105]
	v_mfma_f32_16x16x32_bf16 v[98:101], v[180:183], v[196:199], v[98:101]
	v_mfma_f32_16x16x32_bf16 v[86:89], v[172:175], v[204:207], v[86:89]
	v_mfma_f32_16x16x32_bf16 v[82:85], v[180:183], v[204:207], v[82:85]
	v_mfma_f32_16x16x32_bf16 v[70:73], v[172:175], v[212:215], v[70:73]
	v_mfma_f32_16x16x32_bf16 v[66:69], v[180:183], v[212:215], v[66:69]
	s_barrier
	s_mov_b32 m0, s48
	s_add_u32 s56, s20, 0xb0000
	ds_read_b128 v[184:187], v146 offset:16384
	ds_read_b128 v[188:191], v146 offset:17408
	ds_read_b128 v[192:195], v146 offset:18432
	ds_read_b128 v[196:199], v146 offset:19456
	ds_read_b128 v[200:203], v146 offset:20480
	ds_read_b128 v[204:207], v146 offset:21504
	ds_read_b128 v[208:211], v146 offset:22528
	ds_read_b128 v[212:215], v146 offset:23552
	global_load_lds_dwordx4 v132, s[20:21]
	s_mov_b32 m0, s49
	s_addc_u32 s57, s21, 0
	global_load_lds_dwordx4 v136, s[20:21]
	s_mov_b32 m0, s50
	s_nop 0
	global_load_lds_dwordx4 v132, s[56:57]
	s_mov_b32 m0, s51
	s_nop 0
	global_load_lds_dwordx4 v136, s[56:57]
	s_mov_b32 m0, s31
	s_nop 0
	global_load_lds_dwordx4 v130, s[24:25]
	s_mov_b32 m0, s34
	s_nop 0
	global_load_lds_dwordx4 v134, s[24:25]
	s_waitcnt vmcnt(8)
	s_waitcnt lgkmcnt(0)
	s_barrier
	v_mfma_f32_16x16x32_bf16 v[62:65], v[152:155], v[184:187], v[62:65]
	v_mfma_f32_16x16x32_bf16 v[58:61], v[160:163], v[184:187], v[58:61]
	v_mfma_f32_16x16x32_bf16 v[46:49], v[152:155], v[192:195], v[46:49]
	v_mfma_f32_16x16x32_bf16 v[42:45], v[160:163], v[192:195], v[42:45]
	v_mfma_f32_16x16x32_bf16 v[30:33], v[152:155], v[200:203], v[30:33]
	v_mfma_f32_16x16x32_bf16 v[26:29], v[160:163], v[200:203], v[26:29]
	v_mfma_f32_16x16x32_bf16 v[14:17], v[152:155], v[208:211], v[14:17]
	v_mfma_f32_16x16x32_bf16 v[10:13], v[160:163], v[208:211], v[10:13]
	v_mfma_f32_16x16x32_bf16 v[62:65], v[156:159], v[188:191], v[62:65]
	v_mfma_f32_16x16x32_bf16 v[58:61], v[164:167], v[188:191], v[58:61]
	v_mfma_f32_16x16x32_bf16 v[46:49], v[156:159], v[196:199], v[46:49]
	v_mfma_f32_16x16x32_bf16 v[42:45], v[164:167], v[196:199], v[42:45]
	v_mfma_f32_16x16x32_bf16 v[30:33], v[156:159], v[204:207], v[30:33]
	v_mfma_f32_16x16x32_bf16 v[26:29], v[164:167], v[204:207], v[26:29]
	v_mfma_f32_16x16x32_bf16 v[14:17], v[156:159], v[212:215], v[14:17]
	v_mfma_f32_16x16x32_bf16 v[10:13], v[164:167], v[212:215], v[10:13]
	v_mfma_f32_16x16x32_bf16 v[54:57], v[168:171], v[184:187], v[54:57]
	v_mfma_f32_16x16x32_bf16 v[50:53], v[176:179], v[184:187], v[50:53]
	v_mfma_f32_16x16x32_bf16 v[38:41], v[168:171], v[192:195], v[38:41]
	v_mfma_f32_16x16x32_bf16 v[34:37], v[176:179], v[192:195], v[34:37]
	v_mfma_f32_16x16x32_bf16 v[22:25], v[168:171], v[200:203], v[22:25]
	v_mfma_f32_16x16x32_bf16 v[18:21], v[176:179], v[200:203], v[18:21]
	v_mfma_f32_16x16x32_bf16 v[6:9], v[168:171], v[208:211], v[6:9]
	v_mfma_f32_16x16x32_bf16 v[2:5], v[176:179], v[208:211], v[2:5]
	v_mfma_f32_16x16x32_bf16 v[54:57], v[172:175], v[188:191], v[54:57]
	v_mfma_f32_16x16x32_bf16 v[50:53], v[180:183], v[188:191], v[50:53]
	v_mfma_f32_16x16x32_bf16 v[38:41], v[172:175], v[196:199], v[38:41]
	v_mfma_f32_16x16x32_bf16 v[34:37], v[180:183], v[196:199], v[34:37]
	v_mfma_f32_16x16x32_bf16 v[22:25], v[172:175], v[204:207], v[22:25]
	v_mfma_f32_16x16x32_bf16 v[18:21], v[180:183], v[204:207], v[18:21]
	v_mfma_f32_16x16x32_bf16 v[6:9], v[172:175], v[212:215], v[6:9]
	v_mfma_f32_16x16x32_bf16 v[2:5], v[180:183], v[212:215], v[2:5]
	s_barrier
	ds_read_b128 v[152:155], v147
	ds_read_b128 v[156:159], v147 offset:1024
	ds_read_b128 v[160:163], v147 offset:2048
	ds_read_b128 v[164:167], v147 offset:3072
	ds_read_b128 v[168:171], v148
	ds_read_b128 v[172:175], v148 offset:1024
	ds_read_b128 v[176:179], v148 offset:2048
	ds_read_b128 v[180:183], v148 offset:3072
	s_add_u32 s98, s24, 0xb0000
	s_addc_u32 s99, s25, 0
	s_mov_b32 m0, s35
	ds_read_b128 v[184:187], v146 offset:32768
	ds_read_b128 v[188:191], v146 offset:33792
	ds_read_b128 v[192:195], v146 offset:34816
	ds_read_b128 v[196:199], v146 offset:35840
	ds_read_b128 v[200:203], v146 offset:36864
	ds_read_b128 v[204:207], v146 offset:37888
	ds_read_b128 v[208:211], v146 offset:38912
	ds_read_b128 v[212:215], v146 offset:39936
	global_load_lds_dwordx4 v130, s[98:99]
	s_mov_b32 m0, s37
	s_nop 0
	global_load_lds_dwordx4 v134, s[98:99]
	s_waitcnt vmcnt(8)
	s_waitcnt lgkmcnt(0)
	s_barrier
	v_mfma_f32_16x16x32_bf16 v[126:129], v[152:155], v[184:187], v[126:129]
	v_mfma_f32_16x16x32_bf16 v[122:125], v[160:163], v[184:187], v[122:125]
	v_mfma_f32_16x16x32_bf16 v[118:121], v[152:155], v[192:195], v[118:121]
	v_mfma_f32_16x16x32_bf16 v[114:117], v[160:163], v[192:195], v[114:117]
	v_mfma_f32_16x16x32_bf16 v[94:97], v[152:155], v[200:203], v[94:97]
	v_mfma_f32_16x16x32_bf16 v[90:93], v[160:163], v[200:203], v[90:93]
	v_mfma_f32_16x16x32_bf16 v[78:81], v[152:155], v[208:211], v[78:81]
	v_mfma_f32_16x16x32_bf16 v[74:77], v[160:163], v[208:211], v[74:77]
	v_mfma_f32_16x16x32_bf16 v[126:129], v[156:159], v[188:191], v[126:129]
	v_mfma_f32_16x16x32_bf16 v[122:125], v[164:167], v[188:191], v[122:125]
	v_mfma_f32_16x16x32_bf16 v[118:121], v[156:159], v[196:199], v[118:121]
	v_mfma_f32_16x16x32_bf16 v[114:117], v[164:167], v[196:199], v[114:117]
	v_mfma_f32_16x16x32_bf16 v[94:97], v[156:159], v[204:207], v[94:97]
	v_mfma_f32_16x16x32_bf16 v[90:93], v[164:167], v[204:207], v[90:93]
	v_mfma_f32_16x16x32_bf16 v[78:81], v[156:159], v[212:215], v[78:81]
	v_mfma_f32_16x16x32_bf16 v[74:77], v[164:167], v[212:215], v[74:77]
	v_mfma_f32_16x16x32_bf16 v[110:113], v[168:171], v[184:187], v[110:113]
	v_mfma_f32_16x16x32_bf16 v[106:109], v[176:179], v[184:187], v[106:109]
	v_mfma_f32_16x16x32_bf16 v[102:105], v[168:171], v[192:195], v[102:105]
	v_mfma_f32_16x16x32_bf16 v[98:101], v[176:179], v[192:195], v[98:101]
	v_mfma_f32_16x16x32_bf16 v[86:89], v[168:171], v[200:203], v[86:89]
	v_mfma_f32_16x16x32_bf16 v[82:85], v[176:179], v[200:203], v[82:85]
	v_mfma_f32_16x16x32_bf16 v[70:73], v[168:171], v[208:211], v[70:73]
	v_mfma_f32_16x16x32_bf16 v[66:69], v[176:179], v[208:211], v[66:69]
	v_mfma_f32_16x16x32_bf16 v[110:113], v[172:175], v[188:191], v[110:113]
	v_mfma_f32_16x16x32_bf16 v[106:109], v[180:183], v[188:191], v[106:109]
	v_mfma_f32_16x16x32_bf16 v[102:105], v[172:175], v[196:199], v[102:105]
	v_mfma_f32_16x16x32_bf16 v[98:101], v[180:183], v[196:199], v[98:101]
	v_mfma_f32_16x16x32_bf16 v[86:89], v[172:175], v[204:207], v[86:89]
	v_mfma_f32_16x16x32_bf16 v[82:85], v[180:183], v[204:207], v[82:85]
	v_mfma_f32_16x16x32_bf16 v[70:73], v[172:175], v[212:215], v[70:73]
	v_mfma_f32_16x16x32_bf16 v[66:69], v[180:183], v[212:215], v[66:69]
	s_barrier
	s_add_i32 m0, s52, 0xffffff80
	ds_read_b128 v[184:187], v146 offset:49152
	ds_read_b128 v[188:191], v146 offset:50176
	ds_read_b128 v[192:195], v146 offset:51200
	ds_read_b128 v[196:199], v146 offset:52224
	ds_read_b128 v[200:203], v146 offset:53248
	ds_read_b128 v[204:207], v146 offset:54272
	ds_read_b128 v[208:211], v146 offset:55296
	ds_read_b128 v[212:215], v146 offset:56320
	global_load_lds_dwordx4 v132, s[20:21] offset:128
	s_add_i32 m0, s53, 0xffffff80
	s_nop 0
	global_load_lds_dwordx4 v136, s[20:21] offset:128
	s_add_u32 s20, s20, 0xb0080
	s_addc_u32 s21, s21, 0
	s_mov_b32 m0, s54
	s_nop 0
	global_load_lds_dwordx4 v132, s[20:21]
	s_mov_b32 m0, s55
	s_nop 0
	global_load_lds_dwordx4 v136, s[20:21]
	s_add_i32 m0, s38, 0xffffff80
	s_nop 0
	global_load_lds_dwordx4 v130, s[24:25] offset:128
	s_add_i32 m0, s39, 0xffffff80
	s_nop 0
	global_load_lds_dwordx4 v134, s[24:25] offset:128
	s_waitcnt vmcnt(8)
	s_waitcnt lgkmcnt(0)
	s_barrier
	v_mfma_f32_16x16x32_bf16 v[62:65], v[152:155], v[184:187], v[62:65]
	v_mfma_f32_16x16x32_bf16 v[58:61], v[160:163], v[184:187], v[58:61]
	v_mfma_f32_16x16x32_bf16 v[46:49], v[152:155], v[192:195], v[46:49]
	v_mfma_f32_16x16x32_bf16 v[42:45], v[160:163], v[192:195], v[42:45]
	v_mfma_f32_16x16x32_bf16 v[30:33], v[152:155], v[200:203], v[30:33]
	v_mfma_f32_16x16x32_bf16 v[26:29], v[160:163], v[200:203], v[26:29]
	v_mfma_f32_16x16x32_bf16 v[14:17], v[152:155], v[208:211], v[14:17]
	v_mfma_f32_16x16x32_bf16 v[10:13], v[160:163], v[208:211], v[10:13]
	v_mfma_f32_16x16x32_bf16 v[62:65], v[156:159], v[188:191], v[62:65]
	v_mfma_f32_16x16x32_bf16 v[58:61], v[164:167], v[188:191], v[58:61]
	v_mfma_f32_16x16x32_bf16 v[46:49], v[156:159], v[196:199], v[46:49]
	v_mfma_f32_16x16x32_bf16 v[42:45], v[164:167], v[196:199], v[42:45]
	v_mfma_f32_16x16x32_bf16 v[30:33], v[156:159], v[204:207], v[30:33]
	v_mfma_f32_16x16x32_bf16 v[26:29], v[164:167], v[204:207], v[26:29]
	v_mfma_f32_16x16x32_bf16 v[14:17], v[156:159], v[212:215], v[14:17]
	v_mfma_f32_16x16x32_bf16 v[10:13], v[164:167], v[212:215], v[10:13]
	v_mfma_f32_16x16x32_bf16 v[54:57], v[168:171], v[184:187], v[54:57]
	v_mfma_f32_16x16x32_bf16 v[50:53], v[176:179], v[184:187], v[50:53]
	v_mfma_f32_16x16x32_bf16 v[38:41], v[168:171], v[192:195], v[38:41]
	v_mfma_f32_16x16x32_bf16 v[34:37], v[176:179], v[192:195], v[34:37]
	v_mfma_f32_16x16x32_bf16 v[22:25], v[168:171], v[200:203], v[22:25]
	v_mfma_f32_16x16x32_bf16 v[18:21], v[176:179], v[200:203], v[18:21]
	v_mfma_f32_16x16x32_bf16 v[6:9], v[168:171], v[208:211], v[6:9]
	v_mfma_f32_16x16x32_bf16 v[2:5], v[176:179], v[208:211], v[2:5]
	v_mfma_f32_16x16x32_bf16 v[54:57], v[172:175], v[188:191], v[54:57]
	v_mfma_f32_16x16x32_bf16 v[50:53], v[180:183], v[188:191], v[50:53]
	v_mfma_f32_16x16x32_bf16 v[38:41], v[172:175], v[196:199], v[38:41]
	v_mfma_f32_16x16x32_bf16 v[34:37], v[180:183], v[196:199], v[34:37]
	v_mfma_f32_16x16x32_bf16 v[22:25], v[172:175], v[204:207], v[22:25]
	v_mfma_f32_16x16x32_bf16 v[18:21], v[180:183], v[204:207], v[18:21]
	v_mfma_f32_16x16x32_bf16 v[6:9], v[172:175], v[212:215], v[6:9]
	v_mfma_f32_16x16x32_bf16 v[2:5], v[180:183], v[212:215], v[2:5]
	s_barrier
	s_add_i32 s45, s45, 2
	s_add_u32 s40, s40, 0x100
	s_addc_u32 s42, s42, 0
	s_add_u32 s43, s43, 0x100
	s_addc_u32 s44, s44, 0
	v_lshl_add_u64 v[140:141], v[140:141], 0, s[18:19]
	s_cmp_lt_u32 s45, 38
	v_lshl_add_u64 v[142:143], v[142:143], 0, s[18:19]
	s_cbranch_scc1 .LBB0_2214
	s_waitcnt vmcnt(0)
	s_cmpk_gt_u32 s30, 0xff
	s_cbranch_scc1 .LBB0_2217
	s_barrier
